# strategy 2 prologue de-serialisation: GEMM K-loops peel the first iteration with inline-0 SrcC so the 127 v_mov accumulator zero-init per tile disappears (on top of the barrier-handoff prio cleanup)
# speedup vs baseline: 1.0029x; 1.0029x over previous
; #define PG8_STAGE(bufoff, gbase, voff) do { _Pragma("unroll") for (int _i = 0; _i < 2; ++_i) \
;         __builtin_amdgcn_global_load_lds((const unsigned*)((const char*)(gbase) + (voff)[_i]), (LAS unsigned*)(lds + (bufoff) + ldsw + _i * 8192), 16, 0, 0); } while (0)
; #define PG8_WAIT_V(n) asm volatile("s_waitcnt vmcnt(" #n ")" ::: "memory")
; #define PG8_WAIT_L(n) asm volatile("s_waitcnt lgkmcnt(" #n ")" ::: "memory")
; template <class Epi, class Sched, bool ALIGN_EPI = false, bool SP2 = false>
; __device__ __forceinline__ void gemm_phase(LAS unsigned char* lds, const Gemm g, const Sched& S, const Epi& E) {
;     ...
;     f32x4 acc[2][2][4][2];
; #pragma unroll
;     for (int a = 0; a < 2; ++a)
; #pragma unroll
;         for (int b = 0; b < 2; ++b)
; #pragma unroll
;             for (int m = 0; m < 4; ++m)
; #pragma unroll
;                 for (int n = 0; n < 2; ++n) acc[a][b][m][n] = (f32x4){0.f, 0.f, 0.f, 0.f};
;     ...
;         for (int t = 0; t < nt; t += 2) {
;             const bool last = (t == nt - 2);
;             const char* a1 = cA + (size_t)(t + 1) * kstep;
;             const char* a2 = last ? nA : cA + (size_t)(t + 2) * kstep; const char* b2 = last ? nB : cB + (size_t)(t + 2) * kstep;
;             const char* a3 = a2 + kstep; const char* b3 = b2 + kstep;
;             if (last && has_next) S.a_ready(nxt);
;             if constexpr (SP2) {
;             PG8_LDB(B0, 0, 0); PG8_LDB(B1, 0, 1); PG8_SCHED; PG8_LDA(At, 0, 0); PG8_STAGE(PG8_SA(1, 1), a1 + hstepA, voffA);
;             PG8_WAIT_V(8); PG8_WAIT_L(0); PG8_BAR; PG8_MMA(0, 0, At, B0); PG8_MMA(0, 1, At, B1); PG8_BAR; PG8_SCHED;
;             PG8_LDA(At, 0, 1); PG8_STAGE(PG8_SB(0, 0), b2, voffB); PG8_STAGE(PG8_SB(0, 1), b2 + hstepB, voffB); PG8_STAGE(PG8_SA(0, 0), a2, voffA);
;             PG8_WAIT_V(8); PG8_WAIT_L(0); PG8_BAR; PG8_MMA(1, 0, At, B0); PG8_MMA(1, 1, At, B1); PG8_BAR; PG8_SCHED;
;             PG8_LDB(B0, 1, 0); PG8_LDB(B1, 1, 1); PG8_SCHED; PG8_LDA(At, 1, 0); PG8_STAGE(PG8_SA(0, 1), a2 + hstepA, voffA);
;             PG8_WAIT_V(8); PG8_WAIT_L(0); PG8_BAR; PG8_MMA(0, 0, At, B0); PG8_MMA(0, 1, At, B1); PG8_BAR; PG8_SCHED;
;             PG8_LDA(At, 1, 1); PG8_STAGE(PG8_SB(1, 0), b3, voffB); PG8_STAGE(PG8_SB(1, 1), b3 + hstepB, voffB); PG8_STAGE(PG8_SA(1, 0), a3, voffA);
;             PG8_WAIT_V(8); PG8_WAIT_L(0); PG8_BAR; PG8_MMA(1, 0, At, B0); PG8_MMA(1, 1, At, B1); PG8_BAR; PG8_SCHED;
.LBB0_414:
	s_ashr_i32 s13, s12, 31
	s_lshl_b64 s[14:15], s[12:13], 20
	s_add_u32 s14, s34, s14
	s_addc_u32 s15, s35, s15
	s_and_b64 s[44:45], s[8:9], exec
	s_cselect_b32 s13, s15, s17
	s_cselect_b32 s60, s14, s16
	s_ashr_i32 s11, s10, 31
	s_lshl_b64 s[44:45], s[10:11], 20
	s_add_u32 s44, s2, s44
	s_addc_u32 s45, s24, s45
	s_and_b64 s[48:49], s[8:9], exec
	s_cselect_b32 s11, s45, s23
	s_cselect_b32 s61, s44, s22
	s_add_u32 s48, s16, 0x80080
	s_addc_u32 s49, s17, 0
	s_add_u32 s62, s22, 0x100
	v_mov_b32_e32 v4, 0
	s_addc_u32 s63, s23, 0
	s_mov_b32 s64, -2
	s_add_u32 s16, s48, 0xfff80080
	s_addc_u32 s17, s49, -1
	s_add_i32 s65, 0, 0x10000
	s_cmp_eq_u32 s64, 28
	s_cselect_b32 s23, s13, s17
	s_cselect_b32 s22, s60, s16
	s_cselect_b32 s17, s11, s63
	s_cselect_b32 s16, s61, s62
	s_add_i32 s68, 0, 0x14000
	v_add_u32_e32 v158, s65, v144
	v_add_u32_e32 v174, s68, v144
	ds_read_b128 v[146:149], v158
	ds_read_b128 v[150:153], v158 offset:1024
	ds_read_b128 v[154:157], v158 offset:2048
	ds_read_b128 v[158:161], v158 offset:3072
	ds_read_b128 v[162:165], v174
	ds_read_b128 v[166:169], v174 offset:1024
	ds_read_b128 v[170:173], v174 offset:2048
	ds_read_b128 v[174:177], v174 offset:3072
	v_lshl_add_u64 v[208:209], s[48:49], 0, v[140:141]
	s_add_i32 m0, s37, 0xc000
	ds_read_b128 v[178:181], v145
	ds_read_b128 v[182:185], v145 offset:1024
	ds_read_b128 v[186:189], v145 offset:2048
	ds_read_b128 v[190:193], v145 offset:3072
	ds_read_b128 v[194:197], v145 offset:4096
	ds_read_b128 v[204:207], v145 offset:5120
	ds_read_b128 v[220:223], v145 offset:6144
	ds_read_b128 v[224:227], v145 offset:7168
	global_load_lds_dwordx4 v[208:209], off
	v_lshl_add_u64 v[208:209], s[48:49], 0, v[142:143]
	s_add_i32 m0, s37, 0xe000
	s_nop 0
	global_load_lds_dwordx4 v[208:209], off
	s_waitcnt vmcnt(8)
	s_waitcnt lgkmcnt(0)
	s_setprio 1
	s_barrier
	v_mfma_f32_16x16x32_f16 v[128:131], v[146:149], v[178:181], 0
	v_mfma_f32_16x16x32_f16 v[124:127], v[154:157], v[178:181], 0
	v_mfma_f32_16x16x32_f16 v[120:123], v[146:149], v[186:189], 0
	v_mfma_f32_16x16x32_f16 v[116:119], v[154:157], v[186:189], 0
	v_mfma_f32_16x16x32_f16 v[104:107], v[146:149], v[194:197], 0
	v_mfma_f32_16x16x32_f16 v[100:103], v[154:157], v[194:197], 0
	v_mfma_f32_16x16x32_f16 v[88:91], v[146:149], v[220:223], 0
	v_mfma_f32_16x16x32_f16 v[84:87], v[154:157], v[220:223], 0
	v_mfma_f32_16x16x32_f16 v[128:131], v[150:153], v[182:185], v[128:131]
	v_mfma_f32_16x16x32_f16 v[124:127], v[158:161], v[182:185], v[124:127]
	v_mfma_f32_16x16x32_f16 v[120:123], v[150:153], v[190:193], v[120:123]
	v_mfma_f32_16x16x32_f16 v[116:119], v[158:161], v[190:193], v[116:119]
	v_mfma_f32_16x16x32_f16 v[104:107], v[150:153], v[204:207], v[104:107]
	v_mfma_f32_16x16x32_f16 v[100:103], v[158:161], v[204:207], v[100:103]
	v_mfma_f32_16x16x32_f16 v[88:91], v[150:153], v[224:227], v[88:91]
	v_mfma_f32_16x16x32_f16 v[84:87], v[158:161], v[224:227], v[84:87]
	v_mfma_f32_16x16x32_f16 v[112:115], v[162:165], v[178:181], 0
	v_mfma_f32_16x16x32_f16 v[108:111], v[170:173], v[178:181], 0
	v_mfma_f32_16x16x32_f16 v[96:99], v[162:165], v[186:189], 0
	v_mfma_f32_16x16x32_f16 v[92:95], v[170:173], v[186:189], 0
	v_mfma_f32_16x16x32_f16 v[80:83], v[162:165], v[194:197], 0
	v_mfma_f32_16x16x32_f16 v[76:79], v[170:173], v[194:197], 0
	v_mfma_f32_16x16x32_f16 v[72:75], v[162:165], v[220:223], 0
	v_mfma_f32_16x16x32_f16 v[68:71], v[170:173], v[220:223], 0
	v_mfma_f32_16x16x32_f16 v[112:115], v[166:169], v[182:185], v[112:115]
	v_mfma_f32_16x16x32_f16 v[108:111], v[174:177], v[182:185], v[108:111]
	v_mfma_f32_16x16x32_f16 v[96:99], v[166:169], v[190:193], v[96:99]
	v_mfma_f32_16x16x32_f16 v[92:95], v[174:177], v[190:193], v[92:95]
	v_mfma_f32_16x16x32_f16 v[80:83], v[166:169], v[204:207], v[80:83]
	v_mfma_f32_16x16x32_f16 v[76:79], v[174:177], v[204:207], v[76:79]
	v_mfma_f32_16x16x32_f16 v[72:75], v[166:169], v[224:227], v[72:75]
	v_mfma_f32_16x16x32_f16 v[68:71], v[174:177], v[224:227], v[68:71]
	s_barrier
	s_setprio 0
	s_add_i32 s65, s65, s25
	v_lshl_add_u64 v[208:209], s[16:17], 0, v[2:3]
	s_mov_b32 m0, s65
	ds_read_b128 v[178:181], v145 offset:16384
	ds_read_b128 v[182:185], v145 offset:17408
	ds_read_b128 v[186:189], v145 offset:18432
	ds_read_b128 v[190:193], v145 offset:19456
	ds_read_b128 v[194:197], v145 offset:20480
	ds_read_b128 v[204:207], v145 offset:21504
	ds_read_b128 v[220:223], v145 offset:22528
	ds_read_b128 v[224:227], v145 offset:23552
	global_load_lds_dwordx4 v[208:209], off
	s_add_i32 m0, s65, 0x2000
	s_add_u32 s66, s16, 0x80000
	v_lshl_add_u64 v[228:229], s[16:17], 0, v[132:133]
	s_addc_u32 s67, s17, 0
	s_add_i32 s65, s68, s25
	global_load_lds_dwordx4 v[228:229], off
	v_lshl_add_u64 v[230:231], s[66:67], 0, v[2:3]
	s_mov_b32 m0, s65
	v_lshl_add_u64 v[232:233], s[22:23], 0, v[134:135]
	global_load_lds_dwordx4 v[230:231], off
	v_lshl_add_u64 v[230:231], s[66:67], 0, v[132:133]
	s_add_i32 m0, s65, 0x2000
	s_nop 0
	global_load_lds_dwordx4 v[230:231], off
	v_lshl_add_u64 v[230:231], s[22:23], 0, v[136:137]
	s_mov_b32 m0, s37
	s_nop 0
	global_load_lds_dwordx4 v[230:231], off
	s_mov_b32 m0, s52
	s_nop 0
	global_load_lds_dwordx4 v[232:233], off
	s_waitcnt vmcnt(8)
	s_waitcnt lgkmcnt(0)
	s_setprio 1
	s_barrier
; #define PG8_STAGE(bufoff, gbase, voff) do { _Pragma("unroll") for (int _i = 0; _i < 2; ++_i) \
;         __builtin_amdgcn_global_load_lds((const unsigned*)((const char*)(gbase) + (voff)[_i]), (LAS unsigned*)(lds + (bufoff) + ldsw + _i * 8192), 16, 0, 0); } while (0)
; #define PG8_LDA(dst, b, h) do { _Pragma("unroll") for (int m = 0; m < 4; ++m) _Pragma("unroll") for (int k = 0; k < 2; ++k) dst[m][k] = *(const LAS half8*)(lds + PG8_SA(b, h) + aoff + m * 2048 + k * 1024); } while (0)
; #define PG8_LDB(dst, b, h) do { _Pragma("unroll") for (int n = 0; n < 2; ++n) _Pragma("unroll") for (int k = 0; k < 2; ++k) dst[n][k] = *(const LAS half8*)(lds + PG8_SB(b, h) + boff + n * 2048 + k * 1024); } while (0)
; #define PG8_MMA(ai, bj, At, Bt) do { __builtin_amdgcn_s_setprio(1); _Pragma("unroll") for (int m = 0; m < 4; ++m) _Pragma("unroll") for (int n = 0; n < 2; ++n) _Pragma("unroll") for (int k = 0; k < 2; ++k) \
;         acc[ai][bj][m][n] = __builtin_amdgcn_mfma_f32_16x16x32_f16(Bt[n][k], At[m][k], acc[ai][bj][m][n], 0, 0, 0); __builtin_amdgcn_s_setprio(0); } while (0)
; #define PG8_BAR __builtin_amdgcn_s_barrier()
; template <class Epi, class Sched, bool ALIGN_EPI = false, bool SP2 = false>
; __device__ __forceinline__ void gemm_phase(LAS unsigned char* lds, const Gemm g, const Sched& S, const Epi& E) {
;     ...
;             if constexpr (SP2) {
;             PG8_LDB(B0, 0, 0); PG8_LDB(B1, 0, 1); PG8_SCHED; PG8_LDA(At, 0, 0); PG8_STAGE(PG8_SA(1, 1), a1 + hstepA, voffA);
;             PG8_WAIT_V(8); PG8_WAIT_L(0); PG8_BAR; PG8_MMA(0, 0, At, B0); PG8_MMA(0, 1, At, B1); PG8_BAR; PG8_SCHED;
;             PG8_LDA(At, 0, 1); PG8_STAGE(PG8_SB(0, 0), b2, voffB); PG8_STAGE(PG8_SB(0, 1), b2 + hstepB, voffB); PG8_STAGE(PG8_SA(0, 0), a2, voffA);
;             PG8_WAIT_V(8); PG8_WAIT_L(0); PG8_BAR; PG8_MMA(1, 0, At, B0); PG8_MMA(1, 1, At, B1); PG8_BAR; PG8_SCHED;
;             PG8_LDB(B0, 1, 0); PG8_LDB(B1, 1, 1); PG8_SCHED; PG8_LDA(At, 1, 0); PG8_STAGE(PG8_SA(0, 1), a2 + hstepA, voffA);
;             PG8_WAIT_V(8); PG8_WAIT_L(0); PG8_BAR; PG8_MMA(0, 0, At, B0); PG8_MMA(0, 1, At, B1); PG8_BAR; PG8_SCHED;
;             PG8_LDA(At, 1, 1); PG8_STAGE(PG8_SB(1, 0), b3, voffB); PG8_STAGE(PG8_SB(1, 1), b3 + hstepB, voffB); PG8_STAGE(PG8_SA(1, 0), a3, voffA);
;             PG8_WAIT_V(8); PG8_WAIT_L(0); PG8_BAR; PG8_MMA(1, 0, At, B0); PG8_MMA(1, 1, At, B1); PG8_BAR; PG8_SCHED;
	v_mfma_f32_16x16x32_f16 v[64:67], v[146:149], v[178:181], 0
	v_mfma_f32_16x16x32_f16 v[60:63], v[154:157], v[178:181], 0
	v_mfma_f32_16x16x32_f16 v[56:59], v[146:149], v[186:189], 0
	v_mfma_f32_16x16x32_f16 v[52:55], v[154:157], v[186:189], 0
	v_mfma_f32_16x16x32_f16 v[40:43], v[146:149], v[194:197], 0
	v_mfma_f32_16x16x32_f16 v[36:39], v[154:157], v[194:197], 0
	v_mfma_f32_16x16x32_f16 v[24:27], v[146:149], v[220:223], 0
	v_mfma_f32_16x16x32_f16 v[20:23], v[154:157], v[220:223], 0
	v_mfma_f32_16x16x32_f16 v[64:67], v[150:153], v[182:185], v[64:67]
	v_mfma_f32_16x16x32_f16 v[60:63], v[158:161], v[182:185], v[60:63]
	v_mfma_f32_16x16x32_f16 v[56:59], v[150:153], v[190:193], v[56:59]
	v_mfma_f32_16x16x32_f16 v[52:55], v[158:161], v[190:193], v[52:55]
	v_mfma_f32_16x16x32_f16 v[40:43], v[150:153], v[204:207], v[40:43]
	v_mfma_f32_16x16x32_f16 v[36:39], v[158:161], v[204:207], v[36:39]
	v_mfma_f32_16x16x32_f16 v[24:27], v[150:153], v[224:227], v[24:27]
	v_mfma_f32_16x16x32_f16 v[20:23], v[158:161], v[224:227], v[20:23]
	v_mfma_f32_16x16x32_f16 v[48:51], v[162:165], v[178:181], 0
	v_mfma_f32_16x16x32_f16 v[44:47], v[170:173], v[178:181], 0
	v_mfma_f32_16x16x32_f16 v[32:35], v[162:165], v[186:189], 0
	v_mfma_f32_16x16x32_f16 v[28:31], v[170:173], v[186:189], 0
	v_mfma_f32_16x16x32_f16 v[16:19], v[162:165], v[194:197], 0
	v_mfma_f32_16x16x32_f16 v[12:15], v[170:173], v[194:197], 0
	v_mfma_f32_16x16x32_f16 v[8:11], v[162:165], v[220:223], 0
	v_mfma_f32_16x16x32_f16 v[4:7], v[170:173], v[220:223], 0
	v_mfma_f32_16x16x32_f16 v[48:51], v[166:169], v[182:185], v[48:51]
	v_mfma_f32_16x16x32_f16 v[44:47], v[174:177], v[182:185], v[44:47]
	v_mfma_f32_16x16x32_f16 v[32:35], v[166:169], v[190:193], v[32:35]
	v_mfma_f32_16x16x32_f16 v[28:31], v[174:177], v[190:193], v[28:31]
	v_mfma_f32_16x16x32_f16 v[16:19], v[166:169], v[204:207], v[16:19]
	v_mfma_f32_16x16x32_f16 v[12:15], v[174:177], v[204:207], v[12:15]
	v_mfma_f32_16x16x32_f16 v[8:11], v[166:169], v[224:227], v[8:11]
	v_mfma_f32_16x16x32_f16 v[4:7], v[174:177], v[224:227], v[4:7]
	s_barrier
	s_setprio 0
	s_add_i32 s65, 0, 0x18000
	s_add_i32 s66, 0, 0x1c000
	v_add_u32_e32 v158, s65, v144
	v_add_u32_e32 v174, s66, v144
	ds_read_b128 v[146:149], v158
	ds_read_b128 v[150:153], v158 offset:1024
	ds_read_b128 v[154:157], v158 offset:2048
	ds_read_b128 v[158:161], v158 offset:3072
	ds_read_b128 v[162:165], v174
	ds_read_b128 v[166:169], v174 offset:1024
	ds_read_b128 v[170:173], v174 offset:2048
	ds_read_b128 v[174:177], v174 offset:3072
	s_add_u32 s22, s22, 0x80000
	s_addc_u32 s23, s23, 0
	s_mov_b32 m0, s53
	v_lshl_add_u64 v[234:235], s[22:23], 0, v[136:137]
	ds_read_b128 v[178:181], v145 offset:32768
	ds_read_b128 v[182:185], v145 offset:33792
	ds_read_b128 v[186:189], v145 offset:34816
	ds_read_b128 v[190:193], v145 offset:35840
	ds_read_b128 v[194:197], v145 offset:36864
	ds_read_b128 v[204:207], v145 offset:37888
	ds_read_b128 v[220:223], v145 offset:38912
	ds_read_b128 v[224:227], v145 offset:39936
	global_load_lds_dwordx4 v[234:235], off
	v_lshl_add_u64 v[234:235], s[22:23], 0, v[134:135]
	s_mov_b32 m0, s54
	s_nop 0
	global_load_lds_dwordx4 v[234:235], off
	s_waitcnt vmcnt(8)
	s_waitcnt lgkmcnt(0)
	s_setprio 1
	s_barrier
	v_mfma_f32_16x16x32_f16 v[128:131], v[146:149], v[178:181], v[128:131]
	v_mfma_f32_16x16x32_f16 v[124:127], v[154:157], v[178:181], v[124:127]
	v_mfma_f32_16x16x32_f16 v[120:123], v[146:149], v[186:189], v[120:123]
	v_mfma_f32_16x16x32_f16 v[116:119], v[154:157], v[186:189], v[116:119]
	v_mfma_f32_16x16x32_f16 v[104:107], v[146:149], v[194:197], v[104:107]
	v_mfma_f32_16x16x32_f16 v[100:103], v[154:157], v[194:197], v[100:103]
	v_mfma_f32_16x16x32_f16 v[88:91], v[146:149], v[220:223], v[88:91]
	v_mfma_f32_16x16x32_f16 v[84:87], v[154:157], v[220:223], v[84:87]
	v_mfma_f32_16x16x32_f16 v[128:131], v[150:153], v[182:185], v[128:131]
	v_mfma_f32_16x16x32_f16 v[124:127], v[158:161], v[182:185], v[124:127]
	v_mfma_f32_16x16x32_f16 v[120:123], v[150:153], v[190:193], v[120:123]
	v_mfma_f32_16x16x32_f16 v[116:119], v[158:161], v[190:193], v[116:119]
	v_mfma_f32_16x16x32_f16 v[104:107], v[150:153], v[204:207], v[104:107]
	v_mfma_f32_16x16x32_f16 v[100:103], v[158:161], v[204:207], v[100:103]
	v_mfma_f32_16x16x32_f16 v[88:91], v[150:153], v[224:227], v[88:91]
	v_mfma_f32_16x16x32_f16 v[84:87], v[158:161], v[224:227], v[84:87]
	v_mfma_f32_16x16x32_f16 v[112:115], v[162:165], v[178:181], v[112:115]
	v_mfma_f32_16x16x32_f16 v[108:111], v[170:173], v[178:181], v[108:111]
	v_mfma_f32_16x16x32_f16 v[96:99], v[162:165], v[186:189], v[96:99]
	v_mfma_f32_16x16x32_f16 v[92:95], v[170:173], v[186:189], v[92:95]
	v_mfma_f32_16x16x32_f16 v[80:83], v[162:165], v[194:197], v[80:83]
	v_mfma_f32_16x16x32_f16 v[76:79], v[170:173], v[194:197], v[76:79]
	v_mfma_f32_16x16x32_f16 v[72:75], v[162:165], v[220:223], v[72:75]
	v_mfma_f32_16x16x32_f16 v[68:71], v[170:173], v[220:223], v[68:71]
	v_mfma_f32_16x16x32_f16 v[112:115], v[166:169], v[182:185], v[112:115]
	v_mfma_f32_16x16x32_f16 v[108:111], v[174:177], v[182:185], v[108:111]
	v_mfma_f32_16x16x32_f16 v[96:99], v[166:169], v[190:193], v[96:99]
	v_mfma_f32_16x16x32_f16 v[92:95], v[174:177], v[190:193], v[92:95]
	v_mfma_f32_16x16x32_f16 v[80:83], v[166:169], v[204:207], v[80:83]
	v_mfma_f32_16x16x32_f16 v[76:79], v[174:177], v[204:207], v[76:79]
	v_mfma_f32_16x16x32_f16 v[72:75], v[166:169], v[224:227], v[72:75]
	v_mfma_f32_16x16x32_f16 v[68:71], v[174:177], v[224:227], v[68:71]
	s_barrier
; #define PG8_STAGE(bufoff, gbase, voff) do { _Pragma("unroll") for (int _i = 0; _i < 2; ++_i) \
;         __builtin_amdgcn_global_load_lds((const unsigned*)((const char*)(gbase) + (voff)[_i]), (LAS unsigned*)(lds + (bufoff) + ldsw + _i * 8192), 16, 0, 0); } while (0)
; #define PG8_LDA(dst, b, h) do { _Pragma("unroll") for (int m = 0; m < 4; ++m) _Pragma("unroll") for (int k = 0; k < 2; ++k) dst[m][k] = *(const LAS half8*)(lds + PG8_SA(b, h) + aoff + m * 2048 + k * 1024); } while (0)
; #define PG8_LDB(dst, b, h) do { _Pragma("unroll") for (int n = 0; n < 2; ++n) _Pragma("unroll") for (int k = 0; k < 2; ++k) dst[n][k] = *(const LAS half8*)(lds + PG8_SB(b, h) + boff + n * 2048 + k * 1024); } while (0)
; #define PG8_MMA(ai, bj, At, Bt) do { __builtin_amdgcn_s_setprio(1); _Pragma("unroll") for (int m = 0; m < 4; ++m) _Pragma("unroll") for (int n = 0; n < 2; ++n) _Pragma("unroll") for (int k = 0; k < 2; ++k) \
;         acc[ai][bj][m][n] = __builtin_amdgcn_mfma_f32_16x16x32_f16(Bt[n][k], At[m][k], acc[ai][bj][m][n], 0, 0, 0); __builtin_amdgcn_s_setprio(0); } while (0)
; #define PG8_BAR __builtin_amdgcn_s_barrier()
; template <class Epi, class Sched, bool ALIGN_EPI = false, bool SP2 = false>
; __device__ __forceinline__ void gemm_phase(LAS unsigned char* lds, const Gemm g, const Sched& S, const Epi& E) {
;     ...
;             if constexpr (SP2) {
;             PG8_LDB(B0, 0, 0); PG8_LDB(B1, 0, 1); PG8_SCHED; PG8_LDA(At, 0, 0); PG8_STAGE(PG8_SA(1, 1), a1 + hstepA, voffA);
;             PG8_WAIT_V(8); PG8_WAIT_L(0); PG8_BAR; PG8_MMA(0, 0, At, B0); PG8_MMA(0, 1, At, B1); PG8_BAR; PG8_SCHED;
;             PG8_LDA(At, 0, 1); PG8_STAGE(PG8_SB(0, 0), b2, voffB); PG8_STAGE(PG8_SB(0, 1), b2 + hstepB, voffB); PG8_STAGE(PG8_SA(0, 0), a2, voffA);
;             PG8_WAIT_V(8); PG8_WAIT_L(0); PG8_BAR; PG8_MMA(1, 0, At, B0); PG8_MMA(1, 1, At, B1); PG8_BAR; PG8_SCHED;
;             PG8_LDB(B0, 1, 0); PG8_LDB(B1, 1, 1); PG8_SCHED; PG8_LDA(At, 1, 0); PG8_STAGE(PG8_SA(0, 1), a2 + hstepA, voffA);
;             PG8_WAIT_V(8); PG8_WAIT_L(0); PG8_BAR; PG8_MMA(0, 0, At, B0); PG8_MMA(0, 1, At, B1); PG8_BAR; PG8_SCHED;
;             PG8_LDA(At, 1, 1); PG8_STAGE(PG8_SB(1, 0), b3, voffB); PG8_STAGE(PG8_SB(1, 1), b3 + hstepB, voffB); PG8_STAGE(PG8_SA(1, 0), a3, voffA);
;             PG8_WAIT_V(8); PG8_WAIT_L(0); PG8_BAR; PG8_MMA(1, 0, At, B0); PG8_MMA(1, 1, At, B1); PG8_BAR; PG8_SCHED;
	s_setprio 0
	s_add_i32 s22, s65, s25
	v_lshl_add_u64 v[208:209], v[208:209], 0, s[96:97]
	s_mov_b32 m0, s22
	ds_read_b128 v[178:181], v145 offset:49152
	ds_read_b128 v[182:185], v145 offset:50176
	ds_read_b128 v[186:189], v145 offset:51200
	ds_read_b128 v[190:193], v145 offset:52224
	ds_read_b128 v[194:197], v145 offset:53248
	ds_read_b128 v[204:207], v145 offset:54272
	ds_read_b128 v[220:223], v145 offset:55296
	ds_read_b128 v[224:227], v145 offset:56320
	global_load_lds_dwordx4 v[208:209], off
	s_add_i32 m0, s22, 0x2000
	s_add_u32 s16, s16, 0x80080
	v_lshl_add_u64 v[208:209], v[228:229], 0, s[96:97]
	s_addc_u32 s17, s17, 0
	s_add_i32 s22, s66, s25
	global_load_lds_dwordx4 v[208:209], off
	v_lshl_add_u64 v[208:209], s[16:17], 0, v[2:3]
	s_mov_b32 m0, s22
	s_nop 0
	global_load_lds_dwordx4 v[208:209], off
	v_lshl_add_u64 v[208:209], s[16:17], 0, v[132:133]
	s_add_i32 m0, s22, 0x2000
	s_nop 0
	global_load_lds_dwordx4 v[208:209], off
	v_lshl_add_u64 v[208:209], v[230:231], 0, s[96:97]
	s_mov_b32 m0, s55
	s_nop 0
	global_load_lds_dwordx4 v[208:209], off
	v_lshl_add_u64 v[208:209], v[232:233], 0, s[96:97]
	s_mov_b32 m0, s56
	s_nop 0
	global_load_lds_dwordx4 v[208:209], off
	s_waitcnt vmcnt(8)
	s_waitcnt lgkmcnt(0)
	s_setprio 1
	s_barrier
	v_mfma_f32_16x16x32_f16 v[64:67], v[146:149], v[178:181], v[64:67]
	v_mfma_f32_16x16x32_f16 v[60:63], v[154:157], v[178:181], v[60:63]
	v_mfma_f32_16x16x32_f16 v[56:59], v[146:149], v[186:189], v[56:59]
	v_mfma_f32_16x16x32_f16 v[52:55], v[154:157], v[186:189], v[52:55]
	v_mfma_f32_16x16x32_f16 v[40:43], v[146:149], v[194:197], v[40:43]
	v_mfma_f32_16x16x32_f16 v[36:39], v[154:157], v[194:197], v[36:39]
	v_mfma_f32_16x16x32_f16 v[24:27], v[146:149], v[220:223], v[24:27]
	v_mfma_f32_16x16x32_f16 v[20:23], v[154:157], v[220:223], v[20:23]
	v_mfma_f32_16x16x32_f16 v[64:67], v[150:153], v[182:185], v[64:67]
	v_mfma_f32_16x16x32_f16 v[60:63], v[158:161], v[182:185], v[60:63]
	v_mfma_f32_16x16x32_f16 v[56:59], v[150:153], v[190:193], v[56:59]
	v_mfma_f32_16x16x32_f16 v[52:55], v[158:161], v[190:193], v[52:55]
	v_mfma_f32_16x16x32_f16 v[40:43], v[150:153], v[204:207], v[40:43]
	v_mfma_f32_16x16x32_f16 v[36:39], v[158:161], v[204:207], v[36:39]
	v_mfma_f32_16x16x32_f16 v[24:27], v[150:153], v[224:227], v[24:27]
	v_mfma_f32_16x16x32_f16 v[20:23], v[158:161], v[224:227], v[20:23]
	v_mfma_f32_16x16x32_f16 v[48:51], v[162:165], v[178:181], v[48:51]
	v_mfma_f32_16x16x32_f16 v[44:47], v[170:173], v[178:181], v[44:47]
	v_mfma_f32_16x16x32_f16 v[32:35], v[162:165], v[186:189], v[32:35]
	v_mfma_f32_16x16x32_f16 v[28:31], v[170:173], v[186:189], v[28:31]
	v_mfma_f32_16x16x32_f16 v[16:19], v[162:165], v[194:197], v[16:19]
	v_mfma_f32_16x16x32_f16 v[12:15], v[170:173], v[194:197], v[12:15]
	v_mfma_f32_16x16x32_f16 v[8:11], v[162:165], v[220:223], v[8:11]
	v_mfma_f32_16x16x32_f16 v[4:7], v[170:173], v[220:223], v[4:7]
	v_mfma_f32_16x16x32_f16 v[48:51], v[166:169], v[182:185], v[48:51]
	v_mfma_f32_16x16x32_f16 v[44:47], v[174:177], v[182:185], v[44:47]
	v_mfma_f32_16x16x32_f16 v[32:35], v[166:169], v[190:193], v[32:35]
	v_mfma_f32_16x16x32_f16 v[28:31], v[174:177], v[190:193], v[28:31]
	v_mfma_f32_16x16x32_f16 v[16:19], v[166:169], v[204:207], v[16:19]
	v_mfma_f32_16x16x32_f16 v[12:15], v[174:177], v[204:207], v[12:15]
	v_mfma_f32_16x16x32_f16 v[8:11], v[166:169], v[224:227], v[8:11]
	v_mfma_f32_16x16x32_f16 v[4:7], v[174:177], v[224:227], v[4:7]
	s_barrier
	s_setprio 0
	s_add_i32 s64, s64, 2
	s_add_u32 s48, s48, 0x100
	s_addc_u32 s49, s49, 0
	s_add_u32 s62, s62, 0x100
	s_addc_u32 s63, s63, 0
	s_cmp_gt_u32 s64, 29
	s_cbranch_scc0 .LBB0_415

; #define PG8_WAIT_V(n) asm volatile("s_waitcnt vmcnt(" #n ")" ::: "memory")
; #define PG8_BAR __builtin_amdgcn_s_barrier()
; template <class Epi, class Sched, bool ALIGN_EPI = false, bool SP2 = false>
; __device__ __forceinline__ void gemm_phase(LAS unsigned char* lds, const Gemm g, const Sched& S, const Epi& E) {
;     ...
;         PG8_STAGE(PG8_SB(1, 0), cB + kstep, voffB); PG8_STAGE(PG8_SA(1, 0), cA + kstep, voffA); PG8_STAGE(PG8_SB(1, 1), cB + hstepB + kstep, voffB);
;         PG8_WAIT_V(6); PG8_BAR;
;     } else {
;         PG8_STAGE(PG8_SB(0, 0), cB, voffB); PG8_STAGE(PG8_SA(0, 0), cA, voffA); PG8_STAGE(PG8_SB(0, 1), cB + hstepB, voffB); PG8_STAGE(PG8_SA(0, 1), cA + hstepA, voffA);
;         if (wr == 1) PG8_BAR;
;         PG8_WAIT_V(4); PG8_BAR;
;         PG8_STAGE(PG8_SB(1, 0), cB + kstep, voffB); PG8_STAGE(PG8_SA(1, 0), cA + kstep, voffA); PG8_STAGE(PG8_SB(1, 1), cB + hstepB + kstep, voffB);
;         PG8_WAIT_V(6); PG8_BAR;
;     }
;     for (;;) {
;         const bool has_next = S.next(ui + 1, nxt);
;         const char* nA = has_next ? (const char*)g.A + (size_t)nxt.pm * tstepA : cA; const char* nB = has_next ? (const char*)g.Bt + (size_t)nxt.pn * tstepB : cB;
;         for (int t = 0; t < nt; t += 2) {
;             const bool last = (t == nt - 2);
;             const char* a1 = cA + (size_t)(t + 1) * kstep;
;             const char* a2 = last ? nA : cA + (size_t)(t + 2) * kstep; const char* b2 = last ? nB : cB + (size_t)(t + 2) * kstep;
;             const char* a3 = a2 + kstep; const char* b3 = b2 + kstep;
;             if (last && has_next) S.a_ready(nxt);
;             if constexpr (SP2) {
;             PG8_LDB(B0, 0, 0); PG8_LDB(B1, 0, 1); PG8_SCHED; PG8_LDA(At, 0, 0); PG8_STAGE(PG8_SA(1, 1), a1 + hstepA, voffA);
;             PG8_WAIT_V(8); PG8_WAIT_L(0); PG8_BAR; PG8_MMA(0, 0, At, B0); PG8_MMA(0, 1, At, B1); PG8_BAR; PG8_SCHED;
;             PG8_LDA(At, 0, 1); PG8_STAGE(PG8_SB(0, 0), b2, voffB); PG8_STAGE(PG8_SB(0, 1), b2 + hstepB, voffB); PG8_STAGE(PG8_SA(0, 0), a2, voffA);
;             PG8_WAIT_V(8); PG8_WAIT_L(0); PG8_BAR; PG8_MMA(1, 0, At, B0); PG8_MMA(1, 1, At, B1); PG8_BAR; PG8_SCHED;
;             PG8_LDB(B0, 1, 0); PG8_LDB(B1, 1, 1); PG8_SCHED; PG8_LDA(At, 1, 0); PG8_STAGE(PG8_SA(0, 1), a2 + hstepA, voffA);
;             PG8_WAIT_V(8); PG8_WAIT_L(0); PG8_BAR; PG8_MMA(0, 0, At, B0); PG8_MMA(0, 1, At, B1); PG8_BAR; PG8_SCHED;
.LBB0_425:
	v_lshrrev_b32_e32 v1, 1, v11
	v_and_b32_e32 v15, 15, v11
	v_and_b32_e32 v1, 24, v1
	v_lshl_or_b32 v132, s6, 6, v15
	v_lshlrev_b32_e32 v16, 1, v1
	v_lshlrev_b32_e32 v15, 6, v15
	v_lshlrev_b32_e32 v11, 2, v11
	v_or_b32_e32 v17, v15, v16
	s_lshl_b32 s6, s6, 13
	v_and_b32_e32 v11, 32, v11
	v_bitop3_b32 v15, v15, v11, v16 bitop3:0x36
	v_bitop3_b32 v11, v17, s6, v11 bitop3:0xde
	s_lshl_b32 s6, s2, 12
	s_and_b32 s6, s6, 0x3000
	v_or_b32_e32 v133, s6, v15
	v_readlane_b32 s6, v255, 32
	v_readlane_b32 s7, v255, 33
	s_lshl_b64 s[6:7], s[6:7], 22
	v_readlane_b32 s8, v254, 35
	s_add_u32 s22, s8, s6
	s_addc_u32 s23, 0, s7
	s_add_i32 m0, s14, 0x18000
	v_lshl_add_u64 v[4:5], v[4:5], 0, s[96:97]
	v_readlane_b32 s6, v251, 33
	v_mov_b32_e32 v139, v3
	s_waitcnt vmcnt(2)
	s_barrier
	global_load_lds_dwordx4 v[4:5], off
	v_lshl_add_u64 v[4:5], v[6:7], 0, s[96:97]
	s_add_i32 m0, s14, 0x1a000
	v_readlane_b32 s7, v251, 34
	s_add_i32 s24, s14, 0x8000
	v_mov_b32_e32 v137, v3
	global_load_lds_dwordx4 v[4:5], off
	v_lshl_add_u64 v[4:5], s[6:7], 0, v[138:139]
	s_mov_b32 m0, s24
	s_add_i32 s25, s14, 0xa000
	global_load_lds_dwordx4 v[4:5], off
	v_lshl_add_u64 v[4:5], s[6:7], 0, v[136:137]
	s_add_u32 s6, s0, 0x80080
	s_mov_b32 m0, s25
	s_addc_u32 s7, s1, 0
	global_load_lds_dwordx4 v[4:5], off
	s_add_i32 m0, s14, 0x1c000
	v_lshl_add_u64 v[4:5], s[6:7], 0, v[2:3]
	global_load_lds_dwordx4 v[4:5], off
	v_lshl_add_u64 v[4:5], s[6:7], 0, v[134:135]
	s_add_i32 m0, s14, 0x1e000
	s_mov_b64 s[6:7], 0x3c080080
	global_load_lds_dwordx4 v[4:5], off
	v_lshlrev_b32_e32 v4, 15, v13
	v_and_b32_e32 v4, 0xffff0000, v4
	v_lshl_add_u32 v4, v12, 12, v4
	v_and_b32_e32 v5, 1, v13
	v_lshl_or_b32 v4, v5, 6, v4
	v_lshl_add_u32 v4, v14, 1, v4
	v_mov_b32_e32 v5, v3
	v_lshl_add_u64 v[140:141], v[4:5], 0, s[6:7]
	v_lshlrev_b32_e32 v4, 15, v8
	v_and_b32_e32 v4, 0xffff0000, v4
	v_lshl_add_u32 v4, v9, 12, v4
	v_and_b32_e32 v5, 1, v8
	v_lshl_or_b32 v4, v5, 6, v4
	s_waitcnt vmcnt(6)
	v_lshl_add_u32 v4, v10, 1, v4
	v_mov_b32_e32 v5, v3
	v_lshl_add_u64 v[142:143], v[4:5], 0, s[6:7]
	v_mov_b32_e32 v4, 0
	s_mov_b32 s37, -2
	v_add_u32_e32 v144, 0, v11
	s_mov_b64 s[6:7], s[74:75]
	s_barrier
	s_add_u32 s8, s6, 0x3c000100
	s_addc_u32 s9, s7, 0
	s_add_u32 s44, s6, s22
	s_addc_u32 s45, s7, s23
	s_add_i32 s48, 0, 0x10000
	s_cmp_eq_u32 s37, 28
	s_cselect_b32 s11, s53, s9
	s_cselect_b32 s10, s52, s8
	v_add_u32_e32 v145, s48, v133
	s_cselect_b32 s9, s1, s45
	s_cselect_b32 s8, s0, s44
	s_add_i32 s49, 0, 0x14000
	ds_read_b128 v[146:149], v145
	ds_read_b128 v[150:153], v145 offset:1024
	ds_read_b128 v[154:157], v145 offset:2048
	ds_read_b128 v[158:161], v145 offset:3072
	v_add_u32_e32 v145, s49, v133
	ds_read_b128 v[162:165], v145
	ds_read_b128 v[166:169], v145 offset:1024
	ds_read_b128 v[170:173], v145 offset:2048
	ds_read_b128 v[174:177], v145 offset:3072
	v_lshl_add_u64 v[208:209], s[6:7], 0, v[140:141]
	s_add_i32 m0, s14, 0xc000
	ds_read_b128 v[178:181], v144
	ds_read_b128 v[182:185], v144 offset:1024
	ds_read_b128 v[186:189], v144 offset:2048
	ds_read_b128 v[190:193], v144 offset:3072
	ds_read_b128 v[194:197], v144 offset:4096
	ds_read_b128 v[204:207], v144 offset:5120
	ds_read_b128 v[220:223], v144 offset:6144
	ds_read_b128 v[224:227], v144 offset:7168
	global_load_lds_dwordx4 v[208:209], off
	v_lshl_add_u64 v[208:209], s[6:7], 0, v[142:143]
	s_add_i32 m0, s14, 0xe000
	s_nop 0
	global_load_lds_dwordx4 v[208:209], off
	s_waitcnt vmcnt(8)
	s_waitcnt lgkmcnt(0)
	s_setprio 1
	s_barrier
	v_mfma_f32_16x16x32_f16 v[128:131], v[146:149], v[178:181], 0
	v_mfma_f32_16x16x32_f16 v[124:127], v[154:157], v[178:181], 0
	v_mfma_f32_16x16x32_f16 v[120:123], v[146:149], v[186:189], 0
	v_mfma_f32_16x16x32_f16 v[116:119], v[154:157], v[186:189], 0
	v_mfma_f32_16x16x32_f16 v[104:107], v[146:149], v[194:197], 0
	v_mfma_f32_16x16x32_f16 v[100:103], v[154:157], v[194:197], 0
	v_mfma_f32_16x16x32_f16 v[88:91], v[146:149], v[220:223], 0
	v_mfma_f32_16x16x32_f16 v[84:87], v[154:157], v[220:223], 0
	v_mfma_f32_16x16x32_f16 v[128:131], v[150:153], v[182:185], v[128:131]
	v_mfma_f32_16x16x32_f16 v[124:127], v[158:161], v[182:185], v[124:127]
	v_mfma_f32_16x16x32_f16 v[120:123], v[150:153], v[190:193], v[120:123]
	v_mfma_f32_16x16x32_f16 v[116:119], v[158:161], v[190:193], v[116:119]
	v_mfma_f32_16x16x32_f16 v[104:107], v[150:153], v[204:207], v[104:107]
	v_mfma_f32_16x16x32_f16 v[100:103], v[158:161], v[204:207], v[100:103]
	v_mfma_f32_16x16x32_f16 v[88:91], v[150:153], v[224:227], v[88:91]
	v_mfma_f32_16x16x32_f16 v[84:87], v[158:161], v[224:227], v[84:87]
	v_mfma_f32_16x16x32_f16 v[112:115], v[162:165], v[178:181], 0
	v_mfma_f32_16x16x32_f16 v[108:111], v[170:173], v[178:181], 0
	v_mfma_f32_16x16x32_f16 v[96:99], v[162:165], v[186:189], 0
	v_mfma_f32_16x16x32_f16 v[92:95], v[170:173], v[186:189], 0
	v_mfma_f32_16x16x32_f16 v[80:83], v[162:165], v[194:197], 0
	v_mfma_f32_16x16x32_f16 v[76:79], v[170:173], v[194:197], 0
	v_mfma_f32_16x16x32_f16 v[72:75], v[162:165], v[220:223], 0
	v_mfma_f32_16x16x32_f16 v[68:71], v[170:173], v[220:223], 0
	v_mfma_f32_16x16x32_f16 v[112:115], v[166:169], v[182:185], v[112:115]
	v_mfma_f32_16x16x32_f16 v[108:111], v[174:177], v[182:185], v[108:111]
	v_mfma_f32_16x16x32_f16 v[96:99], v[166:169], v[190:193], v[96:99]
	v_mfma_f32_16x16x32_f16 v[92:95], v[174:177], v[190:193], v[92:95]
	v_mfma_f32_16x16x32_f16 v[80:83], v[166:169], v[204:207], v[80:83]
	v_mfma_f32_16x16x32_f16 v[76:79], v[174:177], v[204:207], v[76:79]
	v_mfma_f32_16x16x32_f16 v[72:75], v[166:169], v[224:227], v[72:75]
	v_mfma_f32_16x16x32_f16 v[68:71], v[174:177], v[224:227], v[68:71]
	s_barrier
; #define PG8_STAGE(bufoff, gbase, voff) do { _Pragma("unroll") for (int _i = 0; _i < 2; ++_i) \
;         __builtin_amdgcn_global_load_lds((const unsigned*)((const char*)(gbase) + (voff)[_i]), (LAS unsigned*)(lds + (bufoff) + ldsw + _i * 8192), 16, 0, 0); } while (0)
; #define PG8_LDA(dst, b, h) do { _Pragma("unroll") for (int m = 0; m < 4; ++m) _Pragma("unroll") for (int k = 0; k < 2; ++k) dst[m][k] = *(const LAS half8*)(lds + PG8_SA(b, h) + aoff + m * 2048 + k * 1024); } while (0)
; #define PG8_LDB(dst, b, h) do { _Pragma("unroll") for (int n = 0; n < 2; ++n) _Pragma("unroll") for (int k = 0; k < 2; ++k) dst[n][k] = *(const LAS half8*)(lds + PG8_SB(b, h) + boff + n * 2048 + k * 1024); } while (0)
; #define PG8_MMA(ai, bj, At, Bt) do { __builtin_amdgcn_s_setprio(1); _Pragma("unroll") for (int m = 0; m < 4; ++m) _Pragma("unroll") for (int n = 0; n < 2; ++n) _Pragma("unroll") for (int k = 0; k < 2; ++k) \
;         acc[ai][bj][m][n] = __builtin_amdgcn_mfma_f32_16x16x32_f16(Bt[n][k], At[m][k], acc[ai][bj][m][n], 0, 0, 0); __builtin_amdgcn_s_setprio(0); } while (0)
; #define PG8_BAR __builtin_amdgcn_s_barrier()
; template <class Epi, class Sched, bool ALIGN_EPI = false, bool SP2 = false>
; __device__ __forceinline__ void gemm_phase(LAS unsigned char* lds, const Gemm g, const Sched& S, const Epi& E) {
;     ...
;             if constexpr (SP2) {
;             PG8_LDB(B0, 0, 0); PG8_LDB(B1, 0, 1); PG8_SCHED; PG8_LDA(At, 0, 0); PG8_STAGE(PG8_SA(1, 1), a1 + hstepA, voffA);
;             PG8_WAIT_V(8); PG8_WAIT_L(0); PG8_BAR; PG8_MMA(0, 0, At, B0); PG8_MMA(0, 1, At, B1); PG8_BAR; PG8_SCHED;
;             PG8_LDA(At, 0, 1); PG8_STAGE(PG8_SB(0, 0), b2, voffB); PG8_STAGE(PG8_SB(0, 1), b2 + hstepB, voffB); PG8_STAGE(PG8_SA(0, 0), a2, voffA);
;             PG8_WAIT_V(8); PG8_WAIT_L(0); PG8_BAR; PG8_MMA(1, 0, At, B0); PG8_MMA(1, 1, At, B1); PG8_BAR; PG8_SCHED;
;             PG8_LDB(B0, 1, 0); PG8_LDB(B1, 1, 1); PG8_SCHED; PG8_LDA(At, 1, 0); PG8_STAGE(PG8_SA(0, 1), a2 + hstepA, voffA);
;             PG8_WAIT_V(8); PG8_WAIT_L(0); PG8_BAR; PG8_MMA(0, 0, At, B0); PG8_MMA(0, 1, At, B1); PG8_BAR; PG8_SCHED;
;             PG8_LDA(At, 1, 1); PG8_STAGE(PG8_SB(1, 0), b3, voffB); PG8_STAGE(PG8_SB(1, 1), b3 + hstepB, voffB); PG8_STAGE(PG8_SA(1, 0), a3, voffA);
;             PG8_WAIT_V(8); PG8_WAIT_L(0); PG8_BAR; PG8_MMA(1, 0, At, B0); PG8_MMA(1, 1, At, B1); PG8_BAR; PG8_SCHED;
	s_setprio 0
	s_add_i32 s44, s48, s13
	v_lshl_add_u64 v[208:209], s[8:9], 0, v[2:3]
	s_mov_b32 m0, s44
	ds_read_b128 v[178:181], v144 offset:16384
	ds_read_b128 v[182:185], v144 offset:17408
	ds_read_b128 v[186:189], v144 offset:18432
	ds_read_b128 v[190:193], v144 offset:19456
	ds_read_b128 v[194:197], v144 offset:20480
	ds_read_b128 v[204:207], v144 offset:21504
	ds_read_b128 v[220:223], v144 offset:22528
	ds_read_b128 v[224:227], v144 offset:23552
	global_load_lds_dwordx4 v[208:209], off
	s_add_i32 m0, s44, 0x2000
	s_add_u32 s44, s8, 0x80000
	v_lshl_add_u64 v[228:229], s[8:9], 0, v[134:135]
	s_addc_u32 s45, s9, 0
	s_add_i32 s48, s49, s13
	global_load_lds_dwordx4 v[228:229], off
	v_lshl_add_u64 v[230:231], s[44:45], 0, v[2:3]
	s_mov_b32 m0, s48
	v_lshl_add_u64 v[232:233], s[10:11], 0, v[136:137]
	global_load_lds_dwordx4 v[230:231], off
	v_lshl_add_u64 v[230:231], s[44:45], 0, v[134:135]
	s_add_i32 m0, s48, 0x2000
	s_nop 0
	global_load_lds_dwordx4 v[230:231], off
	v_lshl_add_u64 v[230:231], s[10:11], 0, v[138:139]
	s_mov_b32 m0, s14
	s_nop 0
	global_load_lds_dwordx4 v[230:231], off
	s_mov_b32 m0, s15
	s_nop 0
	global_load_lds_dwordx4 v[232:233], off
	s_waitcnt vmcnt(8)
	s_waitcnt lgkmcnt(0)
	s_setprio 1
	s_barrier
	v_mfma_f32_16x16x32_f16 v[64:67], v[146:149], v[178:181], 0
	v_mfma_f32_16x16x32_f16 v[60:63], v[154:157], v[178:181], 0
	v_mfma_f32_16x16x32_f16 v[56:59], v[146:149], v[186:189], 0
	v_mfma_f32_16x16x32_f16 v[52:55], v[154:157], v[186:189], 0
	v_mfma_f32_16x16x32_f16 v[40:43], v[146:149], v[194:197], 0
	v_mfma_f32_16x16x32_f16 v[36:39], v[154:157], v[194:197], 0
	v_mfma_f32_16x16x32_f16 v[24:27], v[146:149], v[220:223], 0
	v_mfma_f32_16x16x32_f16 v[20:23], v[154:157], v[220:223], 0
	v_mfma_f32_16x16x32_f16 v[64:67], v[150:153], v[182:185], v[64:67]
	v_mfma_f32_16x16x32_f16 v[60:63], v[158:161], v[182:185], v[60:63]
	v_mfma_f32_16x16x32_f16 v[56:59], v[150:153], v[190:193], v[56:59]
	v_mfma_f32_16x16x32_f16 v[52:55], v[158:161], v[190:193], v[52:55]
	v_mfma_f32_16x16x32_f16 v[40:43], v[150:153], v[204:207], v[40:43]
	v_mfma_f32_16x16x32_f16 v[36:39], v[158:161], v[204:207], v[36:39]
	v_mfma_f32_16x16x32_f16 v[24:27], v[150:153], v[224:227], v[24:27]
	v_mfma_f32_16x16x32_f16 v[20:23], v[158:161], v[224:227], v[20:23]
	v_mfma_f32_16x16x32_f16 v[48:51], v[162:165], v[178:181], 0
	v_mfma_f32_16x16x32_f16 v[44:47], v[170:173], v[178:181], 0
	v_mfma_f32_16x16x32_f16 v[32:35], v[162:165], v[186:189], 0
	v_mfma_f32_16x16x32_f16 v[28:31], v[170:173], v[186:189], 0
	v_mfma_f32_16x16x32_f16 v[16:19], v[162:165], v[194:197], 0
	v_mfma_f32_16x16x32_f16 v[12:15], v[170:173], v[194:197], 0
	v_mfma_f32_16x16x32_f16 v[8:11], v[162:165], v[220:223], 0
	v_mfma_f32_16x16x32_f16 v[4:7], v[170:173], v[220:223], 0
	v_mfma_f32_16x16x32_f16 v[48:51], v[166:169], v[182:185], v[48:51]
	v_mfma_f32_16x16x32_f16 v[44:47], v[174:177], v[182:185], v[44:47]
	v_mfma_f32_16x16x32_f16 v[32:35], v[166:169], v[190:193], v[32:35]
	v_mfma_f32_16x16x32_f16 v[28:31], v[174:177], v[190:193], v[28:31]
	v_mfma_f32_16x16x32_f16 v[16:19], v[166:169], v[204:207], v[16:19]
	v_mfma_f32_16x16x32_f16 v[12:15], v[174:177], v[204:207], v[12:15]
	v_mfma_f32_16x16x32_f16 v[8:11], v[166:169], v[224:227], v[8:11]
	v_mfma_f32_16x16x32_f16 v[4:7], v[174:177], v[224:227], v[4:7]
	s_barrier
	s_setprio 0
	s_add_i32 s44, 0, 0x18000
	v_add_u32_e32 v145, s44, v133
	s_add_i32 s45, 0, 0x1c000
	ds_read_b128 v[146:149], v145
	ds_read_b128 v[150:153], v145 offset:1024
	ds_read_b128 v[154:157], v145 offset:2048
	ds_read_b128 v[158:161], v145 offset:3072
	v_add_u32_e32 v145, s45, v133
	ds_read_b128 v[162:165], v145
	ds_read_b128 v[166:169], v145 offset:1024
	ds_read_b128 v[170:173], v145 offset:2048
	ds_read_b128 v[174:177], v145 offset:3072
	s_add_u32 s10, s10, 0x80000
	s_addc_u32 s11, s11, 0
	s_mov_b32 m0, s16
	v_lshl_add_u64 v[234:235], s[10:11], 0, v[138:139]
	ds_read_b128 v[178:181], v144 offset:32768
	ds_read_b128 v[182:185], v144 offset:33792
	ds_read_b128 v[186:189], v144 offset:34816
	ds_read_b128 v[190:193], v144 offset:35840
	ds_read_b128 v[194:197], v144 offset:36864
	ds_read_b128 v[204:207], v144 offset:37888
	ds_read_b128 v[220:223], v144 offset:38912
	ds_read_b128 v[224:227], v144 offset:39936
	global_load_lds_dwordx4 v[234:235], off
	v_lshl_add_u64 v[234:235], s[10:11], 0, v[136:137]
	s_mov_b32 m0, s17
	s_nop 0
	global_load_lds_dwordx4 v[234:235], off
	s_waitcnt vmcnt(8)
	s_waitcnt lgkmcnt(0)
	s_setprio 1
	s_barrier
;     __device__ __forceinline__ bool next(int i, Unit& u) const { if (i != 0 || !valid) return false; u.pm = pm; u.pn = pn; return true; }
; #define PG8_STAGE(bufoff, gbase, voff) do { _Pragma("unroll") for (int _i = 0; _i < 2; ++_i) \
;         __builtin_amdgcn_global_load_lds((const unsigned*)((const char*)(gbase) + (voff)[_i]), (LAS unsigned*)(lds + (bufoff) + ldsw + _i * 8192), 16, 0, 0); } while (0)
; #define PG8_WAIT_V(n) asm volatile("s_waitcnt vmcnt(" #n ")" ::: "memory")
; template <class Epi, class Sched, bool ALIGN_EPI = false, bool SP2 = false>
; __device__ __forceinline__ void gemm_phase(LAS unsigned char* lds, const Gemm g, const Sched& S, const Epi& E) {
;     ...
;         const bool has_next = S.next(ui + 1, nxt);
;         const char* nA = has_next ? (const char*)g.A + (size_t)nxt.pm * tstepA : cA; const char* nB = has_next ? (const char*)g.Bt + (size_t)nxt.pn * tstepB : cB;
;         for (int t = 0; t < nt; t += 2) {
;             const bool last = (t == nt - 2);
;             const char* a1 = cA + (size_t)(t + 1) * kstep;
;             const char* a2 = last ? nA : cA + (size_t)(t + 2) * kstep; const char* b2 = last ? nB : cB + (size_t)(t + 2) * kstep;
;             const char* a3 = a2 + kstep; const char* b3 = b2 + kstep;
;             if (last && has_next) S.a_ready(nxt);
;             if constexpr (SP2) {
;             PG8_LDB(B0, 0, 0); PG8_LDB(B1, 0, 1); PG8_SCHED; PG8_LDA(At, 0, 0); PG8_STAGE(PG8_SA(1, 1), a1 + hstepA, voffA);
;             PG8_WAIT_V(8); PG8_WAIT_L(0); PG8_BAR; PG8_MMA(0, 0, At, B0); PG8_MMA(0, 1, At, B1); PG8_BAR; PG8_SCHED;
;             PG8_LDA(At, 0, 1); PG8_STAGE(PG8_SB(0, 0), b2, voffB); PG8_STAGE(PG8_SB(0, 1), b2 + hstepB, voffB); PG8_STAGE(PG8_SA(0, 0), a2, voffA);
;             PG8_WAIT_V(8); PG8_WAIT_L(0); PG8_BAR; PG8_MMA(1, 0, At, B0); PG8_MMA(1, 1, At, B1); PG8_BAR; PG8_SCHED;
;             PG8_LDB(B0, 1, 0); PG8_LDB(B1, 1, 1); PG8_SCHED; PG8_LDA(At, 1, 0); PG8_STAGE(PG8_SA(0, 1), a2 + hstepA, voffA);
;             PG8_WAIT_V(8); PG8_WAIT_L(0); PG8_BAR; PG8_MMA(0, 0, At, B0); PG8_MMA(0, 1, At, B1); PG8_BAR; PG8_SCHED;
;             PG8_LDA(At, 1, 1); PG8_STAGE(PG8_SB(1, 0), b3, voffB); PG8_STAGE(PG8_SB(1, 1), b3 + hstepB, voffB); PG8_STAGE(PG8_SA(1, 0), a3, voffA);
;             PG8_WAIT_V(8); PG8_WAIT_L(0); PG8_BAR; PG8_MMA(1, 0, At, B0); PG8_MMA(1, 1, At, B1); PG8_BAR; PG8_SCHED;
	v_mfma_f32_16x16x32_f16 v[128:131], v[146:149], v[178:181], v[128:131]
	v_mfma_f32_16x16x32_f16 v[124:127], v[154:157], v[178:181], v[124:127]
	v_mfma_f32_16x16x32_f16 v[120:123], v[146:149], v[186:189], v[120:123]
	v_mfma_f32_16x16x32_f16 v[116:119], v[154:157], v[186:189], v[116:119]
	v_mfma_f32_16x16x32_f16 v[104:107], v[146:149], v[194:197], v[104:107]
	v_mfma_f32_16x16x32_f16 v[100:103], v[154:157], v[194:197], v[100:103]
	v_mfma_f32_16x16x32_f16 v[88:91], v[146:149], v[220:223], v[88:91]
	v_mfma_f32_16x16x32_f16 v[84:87], v[154:157], v[220:223], v[84:87]
	v_mfma_f32_16x16x32_f16 v[128:131], v[150:153], v[182:185], v[128:131]
	v_mfma_f32_16x16x32_f16 v[124:127], v[158:161], v[182:185], v[124:127]
	v_mfma_f32_16x16x32_f16 v[120:123], v[150:153], v[190:193], v[120:123]
	v_mfma_f32_16x16x32_f16 v[116:119], v[158:161], v[190:193], v[116:119]
	v_mfma_f32_16x16x32_f16 v[104:107], v[150:153], v[204:207], v[104:107]
	v_mfma_f32_16x16x32_f16 v[100:103], v[158:161], v[204:207], v[100:103]
	v_mfma_f32_16x16x32_f16 v[88:91], v[150:153], v[224:227], v[88:91]
	v_mfma_f32_16x16x32_f16 v[84:87], v[158:161], v[224:227], v[84:87]
	v_mfma_f32_16x16x32_f16 v[112:115], v[162:165], v[178:181], v[112:115]
	v_mfma_f32_16x16x32_f16 v[108:111], v[170:173], v[178:181], v[108:111]
	v_mfma_f32_16x16x32_f16 v[96:99], v[162:165], v[186:189], v[96:99]
	v_mfma_f32_16x16x32_f16 v[92:95], v[170:173], v[186:189], v[92:95]
	v_mfma_f32_16x16x32_f16 v[80:83], v[162:165], v[194:197], v[80:83]
	v_mfma_f32_16x16x32_f16 v[76:79], v[170:173], v[194:197], v[76:79]
	v_mfma_f32_16x16x32_f16 v[72:75], v[162:165], v[220:223], v[72:75]
	v_mfma_f32_16x16x32_f16 v[68:71], v[170:173], v[220:223], v[68:71]
	v_mfma_f32_16x16x32_f16 v[112:115], v[166:169], v[182:185], v[112:115]
	v_mfma_f32_16x16x32_f16 v[108:111], v[174:177], v[182:185], v[108:111]
	v_mfma_f32_16x16x32_f16 v[96:99], v[166:169], v[190:193], v[96:99]
	v_mfma_f32_16x16x32_f16 v[92:95], v[174:177], v[190:193], v[92:95]
	v_mfma_f32_16x16x32_f16 v[80:83], v[166:169], v[204:207], v[80:83]
	v_mfma_f32_16x16x32_f16 v[76:79], v[174:177], v[204:207], v[76:79]
	v_mfma_f32_16x16x32_f16 v[72:75], v[166:169], v[224:227], v[72:75]
	v_mfma_f32_16x16x32_f16 v[68:71], v[174:177], v[224:227], v[68:71]
	s_barrier
	s_setprio 0
	s_add_i32 s10, s44, s13
	v_lshl_add_u64 v[208:209], v[208:209], 0, s[96:97]
	s_mov_b32 m0, s10
	ds_read_b128 v[178:181], v144 offset:49152
	ds_read_b128 v[182:185], v144 offset:50176
	ds_read_b128 v[186:189], v144 offset:51200
	ds_read_b128 v[190:193], v144 offset:52224
	ds_read_b128 v[194:197], v144 offset:53248
	ds_read_b128 v[204:207], v144 offset:54272
	ds_read_b128 v[220:223], v144 offset:55296
	ds_read_b128 v[224:227], v144 offset:56320
	global_load_lds_dwordx4 v[208:209], off
	s_add_i32 m0, s10, 0x2000
	s_add_u32 s8, s8, 0x80080
	v_lshl_add_u64 v[208:209], v[228:229], 0, s[96:97]
	s_addc_u32 s9, s9, 0
	s_add_i32 s10, s45, s13
	global_load_lds_dwordx4 v[208:209], off
	v_lshl_add_u64 v[208:209], s[8:9], 0, v[2:3]
	s_mov_b32 m0, s10
	s_nop 0
	global_load_lds_dwordx4 v[208:209], off
	v_lshl_add_u64 v[208:209], s[8:9], 0, v[134:135]
	s_add_i32 m0, s10, 0x2000
	s_nop 0
	global_load_lds_dwordx4 v[208:209], off
	v_lshl_add_u64 v[208:209], v[230:231], 0, s[96:97]
	s_mov_b32 m0, s24
	s_nop 0
	global_load_lds_dwordx4 v[208:209], off
	v_lshl_add_u64 v[208:209], v[232:233], 0, s[96:97]
	s_mov_b32 m0, s25
	s_nop 0
	global_load_lds_dwordx4 v[208:209], off
	s_waitcnt vmcnt(8)
	s_waitcnt lgkmcnt(0)
	s_setprio 1
	s_barrier
	v_mfma_f32_16x16x32_f16 v[64:67], v[146:149], v[178:181], v[64:67]
	v_mfma_f32_16x16x32_f16 v[60:63], v[154:157], v[178:181], v[60:63]
	v_mfma_f32_16x16x32_f16 v[56:59], v[146:149], v[186:189], v[56:59]
	v_mfma_f32_16x16x32_f16 v[52:55], v[154:157], v[186:189], v[52:55]
	v_mfma_f32_16x16x32_f16 v[40:43], v[146:149], v[194:197], v[40:43]
	v_mfma_f32_16x16x32_f16 v[36:39], v[154:157], v[194:197], v[36:39]
	v_mfma_f32_16x16x32_f16 v[24:27], v[146:149], v[220:223], v[24:27]
	v_mfma_f32_16x16x32_f16 v[20:23], v[154:157], v[220:223], v[20:23]
	v_mfma_f32_16x16x32_f16 v[64:67], v[150:153], v[182:185], v[64:67]
	v_mfma_f32_16x16x32_f16 v[60:63], v[158:161], v[182:185], v[60:63]
	v_mfma_f32_16x16x32_f16 v[56:59], v[150:153], v[190:193], v[56:59]
	v_mfma_f32_16x16x32_f16 v[52:55], v[158:161], v[190:193], v[52:55]
	v_mfma_f32_16x16x32_f16 v[40:43], v[150:153], v[204:207], v[40:43]
	v_mfma_f32_16x16x32_f16 v[36:39], v[158:161], v[204:207], v[36:39]
	v_mfma_f32_16x16x32_f16 v[24:27], v[150:153], v[224:227], v[24:27]
	v_mfma_f32_16x16x32_f16 v[20:23], v[158:161], v[224:227], v[20:23]
	v_mfma_f32_16x16x32_f16 v[48:51], v[162:165], v[178:181], v[48:51]
	v_mfma_f32_16x16x32_f16 v[44:47], v[170:173], v[178:181], v[44:47]
	v_mfma_f32_16x16x32_f16 v[32:35], v[162:165], v[186:189], v[32:35]
	v_mfma_f32_16x16x32_f16 v[28:31], v[170:173], v[186:189], v[28:31]
	v_mfma_f32_16x16x32_f16 v[16:19], v[162:165], v[194:197], v[16:19]
	v_mfma_f32_16x16x32_f16 v[12:15], v[170:173], v[194:197], v[12:15]
	v_mfma_f32_16x16x32_f16 v[8:11], v[162:165], v[220:223], v[8:11]
	v_mfma_f32_16x16x32_f16 v[4:7], v[170:173], v[220:223], v[4:7]
	v_mfma_f32_16x16x32_f16 v[48:51], v[166:169], v[182:185], v[48:51]
	v_mfma_f32_16x16x32_f16 v[44:47], v[174:177], v[182:185], v[44:47]
	v_mfma_f32_16x16x32_f16 v[32:35], v[166:169], v[190:193], v[32:35]
	v_mfma_f32_16x16x32_f16 v[28:31], v[174:177], v[190:193], v[28:31]
	v_mfma_f32_16x16x32_f16 v[16:19], v[166:169], v[204:207], v[16:19]
	v_mfma_f32_16x16x32_f16 v[12:15], v[174:177], v[204:207], v[12:15]
	v_mfma_f32_16x16x32_f16 v[8:11], v[166:169], v[224:227], v[8:11]
	v_mfma_f32_16x16x32_f16 v[4:7], v[174:177], v[224:227], v[4:7]
	s_barrier
	s_setprio 0
	s_add_i32 s37, s37, 2
	s_add_u32 s6, s6, 0x100
	s_addc_u32 s7, s7, 0
	s_cmp_gt_u32 s37, 29
	s_cbranch_scc0 .LBB0_426

; #define PG8_STAGE(bufoff, gbase, voff) do { _Pragma("unroll") for (int _i = 0; _i < 2; ++_i) \
;         __builtin_amdgcn_global_load_lds((const unsigned*)((const char*)(gbase) + (voff)[_i]), (LAS unsigned*)(lds + (bufoff) + ldsw + _i * 8192), 16, 0, 0); } while (0)
; #define PG8_WAIT_V(n) asm volatile("s_waitcnt vmcnt(" #n ")" ::: "memory")
; #define PG8_WAIT_L(n) asm volatile("s_waitcnt lgkmcnt(" #n ")" ::: "memory")
; template <class Epi, class Sched, bool ALIGN_EPI = false, bool SP2 = false>
; __device__ __forceinline__ void gemm_phase(LAS unsigned char* lds, const Gemm g, const Sched& S, const Epi& E) {
;     ...
;     f32x4 acc[2][2][4][2];
; #pragma unroll
;     for (int a = 0; a < 2; ++a)
; #pragma unroll
;         for (int b = 0; b < 2; ++b)
; #pragma unroll
;             for (int m = 0; m < 4; ++m)
; #pragma unroll
;                 for (int n = 0; n < 2; ++n) acc[a][b][m][n] = (f32x4){0.f, 0.f, 0.f, 0.f};
;     ...
;         for (int t = 0; t < nt; t += 2) {
;             const bool last = (t == nt - 2);
;             const char* a1 = cA + (size_t)(t + 1) * kstep;
;             const char* a2 = last ? nA : cA + (size_t)(t + 2) * kstep; const char* b2 = last ? nB : cB + (size_t)(t + 2) * kstep;
;             const char* a3 = a2 + kstep; const char* b3 = b2 + kstep;
;             if (last && has_next) S.a_ready(nxt);
;             if constexpr (SP2) {
;             PG8_LDB(B0, 0, 0); PG8_LDB(B1, 0, 1); PG8_SCHED; PG8_LDA(At, 0, 0); PG8_STAGE(PG8_SA(1, 1), a1 + hstepA, voffA);
;             PG8_WAIT_V(8); PG8_WAIT_L(0); PG8_BAR; PG8_MMA(0, 0, At, B0); PG8_MMA(0, 1, At, B1); PG8_BAR; PG8_SCHED;
;             PG8_LDA(At, 0, 1); PG8_STAGE(PG8_SB(0, 0), b2, voffB); PG8_STAGE(PG8_SB(0, 1), b2 + hstepB, voffB); PG8_STAGE(PG8_SA(0, 0), a2, voffA);
;             PG8_WAIT_V(8); PG8_WAIT_L(0); PG8_BAR; PG8_MMA(1, 0, At, B0); PG8_MMA(1, 1, At, B1); PG8_BAR; PG8_SCHED;
;             PG8_LDB(B0, 1, 0); PG8_LDB(B1, 1, 1); PG8_SCHED; PG8_LDA(At, 1, 0); PG8_STAGE(PG8_SA(0, 1), a2 + hstepA, voffA);
;             PG8_WAIT_V(8); PG8_WAIT_L(0); PG8_BAR; PG8_MMA(0, 0, At, B0); PG8_MMA(0, 1, At, B1); PG8_BAR; PG8_SCHED;
;             PG8_LDA(At, 1, 1); PG8_STAGE(PG8_SB(1, 0), b3, voffB); PG8_STAGE(PG8_SB(1, 1), b3 + hstepB, voffB); PG8_STAGE(PG8_SA(1, 0), a3, voffA);
;             PG8_WAIT_V(8); PG8_WAIT_L(0); PG8_BAR; PG8_MMA(1, 0, At, B0); PG8_MMA(1, 1, At, B1); PG8_BAR; PG8_SCHED;
.LBB0_1100:
	s_ashr_i32 s15, s14, 31
	s_lshl_b64 s[38:39], s[14:15], 20
	s_add_u32 s38, s34, s38
	s_addc_u32 s39, s35, s39
	s_and_b64 s[40:41], s[0:1], exec
	s_cselect_b32 s15, s39, s23
	s_cselect_b32 s58, s38, s22
	s_ashr_i32 s13, s12, 31
	s_lshl_b64 s[40:41], s[12:13], 20
	s_add_u32 s40, s2, s40
	s_addc_u32 s41, s24, s41
	s_and_b64 s[46:47], s[0:1], exec
	s_cselect_b32 s13, s41, s17
	s_cselect_b32 s59, s40, s16
	s_add_u32 s46, s22, 0x80080
	s_addc_u32 s47, s23, 0
	s_add_u32 s60, s16, 0x100
	v_mov_b32_e32 v4, 0
	s_addc_u32 s61, s17, 0
	s_mov_b32 s62, -2
	s_add_u32 s16, s46, 0xfff80080
	s_addc_u32 s17, s47, -1
	s_add_i32 s63, 0, 0x10000
	s_cmp_eq_u32 s62, 28
	s_cselect_b32 s23, s15, s17
	s_cselect_b32 s22, s58, s16
	v_add_u32_e32 v145, s63, v142
	s_cselect_b32 s17, s13, s61
	s_cselect_b32 s16, s59, s60
	s_add_i32 s66, 0, 0x14000
	ds_read_b128 v[146:149], v145
	ds_read_b128 v[150:153], v145 offset:1024
	ds_read_b128 v[154:157], v145 offset:2048
	ds_read_b128 v[158:161], v145 offset:3072
	v_add_u32_e32 v145, s66, v142
	ds_read_b128 v[162:165], v145
	ds_read_b128 v[166:169], v145 offset:1024
	ds_read_b128 v[170:173], v145 offset:2048
	ds_read_b128 v[174:177], v145 offset:3072
	v_lshl_add_u64 v[194:195], s[46:47], 0, v[138:139]
	s_add_i32 m0, s37, 0xc000
	ds_read_b128 v[178:181], v144
	ds_read_b128 v[182:185], v144 offset:1024
	ds_read_b128 v[186:189], v144 offset:2048
	ds_read_b128 v[190:193], v144 offset:3072
	ds_read_b128 v[204:207], v144 offset:4096
	ds_read_b128 v[220:223], v144 offset:5120
	ds_read_b128 v[224:227], v144 offset:6144
	ds_read_b128 v[228:231], v144 offset:7168
	global_load_lds_dwordx4 v[194:195], off
	v_lshl_add_u64 v[194:195], s[46:47], 0, v[140:141]
	s_add_i32 m0, s37, 0xe000
	s_nop 0
	global_load_lds_dwordx4 v[194:195], off
	s_waitcnt vmcnt(8)
	s_waitcnt lgkmcnt(0)
	s_setprio 1
	s_barrier
	v_mfma_f32_16x16x32_f16 v[128:131], v[146:149], v[178:181], 0
	v_mfma_f32_16x16x32_f16 v[124:127], v[154:157], v[178:181], 0
	v_mfma_f32_16x16x32_f16 v[112:115], v[146:149], v[186:189], 0
	v_mfma_f32_16x16x32_f16 v[108:111], v[154:157], v[186:189], 0
	v_mfma_f32_16x16x32_f16 v[96:99], v[146:149], v[204:207], 0
	v_mfma_f32_16x16x32_f16 v[92:95], v[154:157], v[204:207], 0
	v_mfma_f32_16x16x32_f16 v[80:83], v[146:149], v[224:227], 0
	v_mfma_f32_16x16x32_f16 v[76:79], v[154:157], v[224:227], 0
	v_mfma_f32_16x16x32_f16 v[128:131], v[150:153], v[182:185], v[128:131]
	v_mfma_f32_16x16x32_f16 v[124:127], v[158:161], v[182:185], v[124:127]
	v_mfma_f32_16x16x32_f16 v[112:115], v[150:153], v[190:193], v[112:115]
	v_mfma_f32_16x16x32_f16 v[108:111], v[158:161], v[190:193], v[108:111]
	v_mfma_f32_16x16x32_f16 v[96:99], v[150:153], v[220:223], v[96:99]
	v_mfma_f32_16x16x32_f16 v[92:95], v[158:161], v[220:223], v[92:95]
	v_mfma_f32_16x16x32_f16 v[80:83], v[150:153], v[228:231], v[80:83]
	v_mfma_f32_16x16x32_f16 v[76:79], v[158:161], v[228:231], v[76:79]
	v_mfma_f32_16x16x32_f16 v[120:123], v[162:165], v[178:181], 0
	v_mfma_f32_16x16x32_f16 v[116:119], v[170:173], v[178:181], 0
	v_mfma_f32_16x16x32_f16 v[104:107], v[162:165], v[186:189], 0
	v_mfma_f32_16x16x32_f16 v[100:103], v[170:173], v[186:189], 0
	v_mfma_f32_16x16x32_f16 v[88:91], v[162:165], v[204:207], 0
	v_mfma_f32_16x16x32_f16 v[84:87], v[170:173], v[204:207], 0
	v_mfma_f32_16x16x32_f16 v[72:75], v[162:165], v[224:227], 0
	v_mfma_f32_16x16x32_f16 v[68:71], v[170:173], v[224:227], 0
	v_mfma_f32_16x16x32_f16 v[120:123], v[166:169], v[182:185], v[120:123]
	v_mfma_f32_16x16x32_f16 v[116:119], v[174:177], v[182:185], v[116:119]
	v_mfma_f32_16x16x32_f16 v[104:107], v[166:169], v[190:193], v[104:107]
	v_mfma_f32_16x16x32_f16 v[100:103], v[174:177], v[190:193], v[100:103]
	v_mfma_f32_16x16x32_f16 v[88:91], v[166:169], v[220:223], v[88:91]
	v_mfma_f32_16x16x32_f16 v[84:87], v[174:177], v[220:223], v[84:87]
	v_mfma_f32_16x16x32_f16 v[72:75], v[166:169], v[228:231], v[72:75]
	v_mfma_f32_16x16x32_f16 v[68:71], v[174:177], v[228:231], v[68:71]
	s_barrier
	s_setprio 0
	s_add_i32 s63, s63, s25
	v_lshl_add_u64 v[194:195], s[16:17], 0, v[2:3]
	s_mov_b32 m0, s63
	ds_read_b128 v[178:181], v144 offset:16384
	ds_read_b128 v[182:185], v144 offset:17408
	ds_read_b128 v[186:189], v144 offset:18432
	ds_read_b128 v[190:193], v144 offset:19456
	ds_read_b128 v[204:207], v144 offset:20480
	ds_read_b128 v[220:223], v144 offset:21504
	ds_read_b128 v[224:227], v144 offset:22528
	ds_read_b128 v[228:231], v144 offset:23552
	global_load_lds_dwordx4 v[194:195], off
	s_add_i32 m0, s63, 0x2000
	s_add_u32 s64, s16, 0x80000
	v_lshl_add_u64 v[196:197], s[16:17], 0, v[132:133]
	s_addc_u32 s65, s17, 0
	s_add_i32 s63, s66, s25
	global_load_lds_dwordx4 v[196:197], off
	v_lshl_add_u64 v[208:209], s[64:65], 0, v[2:3]
	s_mov_b32 m0, s63
	v_lshl_add_u64 v[232:233], s[22:23], 0, v[134:135]
	global_load_lds_dwordx4 v[208:209], off
	v_lshl_add_u64 v[208:209], s[64:65], 0, v[132:133]
	s_add_i32 m0, s63, 0x2000
	s_nop 0
	global_load_lds_dwordx4 v[208:209], off
	v_lshl_add_u64 v[208:209], s[22:23], 0, v[136:137]
	s_mov_b32 m0, s37
	s_nop 0
	global_load_lds_dwordx4 v[208:209], off
	s_mov_b32 m0, s48
	s_nop 0
	global_load_lds_dwordx4 v[232:233], off
	s_waitcnt vmcnt(8)
	s_waitcnt lgkmcnt(0)
	s_setprio 1
	s_barrier
; #define PG8_STAGE(bufoff, gbase, voff) do { _Pragma("unroll") for (int _i = 0; _i < 2; ++_i) \
;         __builtin_amdgcn_global_load_lds((const unsigned*)((const char*)(gbase) + (voff)[_i]), (LAS unsigned*)(lds + (bufoff) + ldsw + _i * 8192), 16, 0, 0); } while (0)
; #define PG8_LDA(dst, b, h) do { _Pragma("unroll") for (int m = 0; m < 4; ++m) _Pragma("unroll") for (int k = 0; k < 2; ++k) dst[m][k] = *(const LAS half8*)(lds + PG8_SA(b, h) + aoff + m * 2048 + k * 1024); } while (0)
; #define PG8_LDB(dst, b, h) do { _Pragma("unroll") for (int n = 0; n < 2; ++n) _Pragma("unroll") for (int k = 0; k < 2; ++k) dst[n][k] = *(const LAS half8*)(lds + PG8_SB(b, h) + boff + n * 2048 + k * 1024); } while (0)
; #define PG8_MMA(ai, bj, At, Bt) do { __builtin_amdgcn_s_setprio(1); _Pragma("unroll") for (int m = 0; m < 4; ++m) _Pragma("unroll") for (int n = 0; n < 2; ++n) _Pragma("unroll") for (int k = 0; k < 2; ++k) \
;         acc[ai][bj][m][n] = __builtin_amdgcn_mfma_f32_16x16x32_f16(Bt[n][k], At[m][k], acc[ai][bj][m][n], 0, 0, 0); __builtin_amdgcn_s_setprio(0); } while (0)
; #define PG8_BAR __builtin_amdgcn_s_barrier()
; template <class Epi, class Sched, bool ALIGN_EPI = false, bool SP2 = false>
; __device__ __forceinline__ void gemm_phase(LAS unsigned char* lds, const Gemm g, const Sched& S, const Epi& E) {
;     ...
;             if constexpr (SP2) {
;             PG8_LDB(B0, 0, 0); PG8_LDB(B1, 0, 1); PG8_SCHED; PG8_LDA(At, 0, 0); PG8_STAGE(PG8_SA(1, 1), a1 + hstepA, voffA);
;             PG8_WAIT_V(8); PG8_WAIT_L(0); PG8_BAR; PG8_MMA(0, 0, At, B0); PG8_MMA(0, 1, At, B1); PG8_BAR; PG8_SCHED;
;             PG8_LDA(At, 0, 1); PG8_STAGE(PG8_SB(0, 0), b2, voffB); PG8_STAGE(PG8_SB(0, 1), b2 + hstepB, voffB); PG8_STAGE(PG8_SA(0, 0), a2, voffA);
;             PG8_WAIT_V(8); PG8_WAIT_L(0); PG8_BAR; PG8_MMA(1, 0, At, B0); PG8_MMA(1, 1, At, B1); PG8_BAR; PG8_SCHED;
;             PG8_LDB(B0, 1, 0); PG8_LDB(B1, 1, 1); PG8_SCHED; PG8_LDA(At, 1, 0); PG8_STAGE(PG8_SA(0, 1), a2 + hstepA, voffA);
;             PG8_WAIT_V(8); PG8_WAIT_L(0); PG8_BAR; PG8_MMA(0, 0, At, B0); PG8_MMA(0, 1, At, B1); PG8_BAR; PG8_SCHED;
;             PG8_LDA(At, 1, 1); PG8_STAGE(PG8_SB(1, 0), b3, voffB); PG8_STAGE(PG8_SB(1, 1), b3 + hstepB, voffB); PG8_STAGE(PG8_SA(1, 0), a3, voffA);
;             PG8_WAIT_V(8); PG8_WAIT_L(0); PG8_BAR; PG8_MMA(1, 0, At, B0); PG8_MMA(1, 1, At, B1); PG8_BAR; PG8_SCHED;
	v_mfma_f32_16x16x32_f16 v[64:67], v[146:149], v[178:181], 0
	v_mfma_f32_16x16x32_f16 v[60:63], v[154:157], v[178:181], 0
	v_mfma_f32_16x16x32_f16 v[48:51], v[146:149], v[186:189], 0
	v_mfma_f32_16x16x32_f16 v[44:47], v[154:157], v[186:189], 0
	v_mfma_f32_16x16x32_f16 v[32:35], v[146:149], v[204:207], 0
	v_mfma_f32_16x16x32_f16 v[28:31], v[154:157], v[204:207], 0
	v_mfma_f32_16x16x32_f16 v[16:19], v[146:149], v[224:227], 0
	v_mfma_f32_16x16x32_f16 v[12:15], v[154:157], v[224:227], 0
	v_mfma_f32_16x16x32_f16 v[64:67], v[150:153], v[182:185], v[64:67]
	v_mfma_f32_16x16x32_f16 v[60:63], v[158:161], v[182:185], v[60:63]
	v_mfma_f32_16x16x32_f16 v[48:51], v[150:153], v[190:193], v[48:51]
	v_mfma_f32_16x16x32_f16 v[44:47], v[158:161], v[190:193], v[44:47]
	v_mfma_f32_16x16x32_f16 v[32:35], v[150:153], v[220:223], v[32:35]
	v_mfma_f32_16x16x32_f16 v[28:31], v[158:161], v[220:223], v[28:31]
	v_mfma_f32_16x16x32_f16 v[16:19], v[150:153], v[228:231], v[16:19]
	v_mfma_f32_16x16x32_f16 v[12:15], v[158:161], v[228:231], v[12:15]
	v_mfma_f32_16x16x32_f16 v[56:59], v[162:165], v[178:181], 0
	v_mfma_f32_16x16x32_f16 v[52:55], v[170:173], v[178:181], 0
	v_mfma_f32_16x16x32_f16 v[40:43], v[162:165], v[186:189], 0
	v_mfma_f32_16x16x32_f16 v[36:39], v[170:173], v[186:189], 0
	v_mfma_f32_16x16x32_f16 v[24:27], v[162:165], v[204:207], 0
	v_mfma_f32_16x16x32_f16 v[20:23], v[170:173], v[204:207], 0
	v_mfma_f32_16x16x32_f16 v[8:11], v[162:165], v[224:227], 0
	v_mfma_f32_16x16x32_f16 v[4:7], v[170:173], v[224:227], 0
	v_mfma_f32_16x16x32_f16 v[56:59], v[166:169], v[182:185], v[56:59]
	v_mfma_f32_16x16x32_f16 v[52:55], v[174:177], v[182:185], v[52:55]
	v_mfma_f32_16x16x32_f16 v[40:43], v[166:169], v[190:193], v[40:43]
	v_mfma_f32_16x16x32_f16 v[36:39], v[174:177], v[190:193], v[36:39]
	v_mfma_f32_16x16x32_f16 v[24:27], v[166:169], v[220:223], v[24:27]
	v_mfma_f32_16x16x32_f16 v[20:23], v[174:177], v[220:223], v[20:23]
	v_mfma_f32_16x16x32_f16 v[8:11], v[166:169], v[228:231], v[8:11]
	v_mfma_f32_16x16x32_f16 v[4:7], v[174:177], v[228:231], v[4:7]
	s_barrier
	s_setprio 0
	s_add_i32 s63, 0, 0x18000
	v_add_u32_e32 v145, s63, v142
	s_add_i32 s64, 0, 0x1c000
	ds_read_b128 v[146:149], v145
	ds_read_b128 v[150:153], v145 offset:1024
	ds_read_b128 v[154:157], v145 offset:2048
	ds_read_b128 v[158:161], v145 offset:3072
	v_add_u32_e32 v145, s64, v142
	ds_read_b128 v[162:165], v145
	ds_read_b128 v[166:169], v145 offset:1024
	ds_read_b128 v[170:173], v145 offset:2048
	ds_read_b128 v[174:177], v145 offset:3072
	s_add_u32 s22, s22, 0x80000
	s_addc_u32 s23, s23, 0
	s_mov_b32 m0, s49
	v_lshl_add_u64 v[234:235], s[22:23], 0, v[136:137]
	ds_read_b128 v[178:181], v144 offset:32768
	ds_read_b128 v[182:185], v144 offset:33792
	ds_read_b128 v[186:189], v144 offset:34816
	ds_read_b128 v[190:193], v144 offset:35840
	ds_read_b128 v[204:207], v144 offset:36864
	ds_read_b128 v[220:223], v144 offset:37888
	ds_read_b128 v[224:227], v144 offset:38912
	ds_read_b128 v[228:231], v144 offset:39936
	global_load_lds_dwordx4 v[234:235], off
	v_lshl_add_u64 v[234:235], s[22:23], 0, v[134:135]
	s_mov_b32 m0, s52
	s_nop 0
	global_load_lds_dwordx4 v[234:235], off
	s_waitcnt vmcnt(8)
	s_waitcnt lgkmcnt(0)
	s_setprio 1
	s_barrier
	v_mfma_f32_16x16x32_f16 v[128:131], v[146:149], v[178:181], v[128:131]
	v_mfma_f32_16x16x32_f16 v[124:127], v[154:157], v[178:181], v[124:127]
	v_mfma_f32_16x16x32_f16 v[112:115], v[146:149], v[186:189], v[112:115]
	v_mfma_f32_16x16x32_f16 v[108:111], v[154:157], v[186:189], v[108:111]
	v_mfma_f32_16x16x32_f16 v[96:99], v[146:149], v[204:207], v[96:99]
	v_mfma_f32_16x16x32_f16 v[92:95], v[154:157], v[204:207], v[92:95]
	v_mfma_f32_16x16x32_f16 v[80:83], v[146:149], v[224:227], v[80:83]
	v_mfma_f32_16x16x32_f16 v[76:79], v[154:157], v[224:227], v[76:79]
	v_mfma_f32_16x16x32_f16 v[128:131], v[150:153], v[182:185], v[128:131]
	v_mfma_f32_16x16x32_f16 v[124:127], v[158:161], v[182:185], v[124:127]
	v_mfma_f32_16x16x32_f16 v[112:115], v[150:153], v[190:193], v[112:115]
	v_mfma_f32_16x16x32_f16 v[108:111], v[158:161], v[190:193], v[108:111]
	v_mfma_f32_16x16x32_f16 v[96:99], v[150:153], v[220:223], v[96:99]
	v_mfma_f32_16x16x32_f16 v[92:95], v[158:161], v[220:223], v[92:95]
	v_mfma_f32_16x16x32_f16 v[80:83], v[150:153], v[228:231], v[80:83]
	v_mfma_f32_16x16x32_f16 v[76:79], v[158:161], v[228:231], v[76:79]
	v_mfma_f32_16x16x32_f16 v[120:123], v[162:165], v[178:181], v[120:123]
	v_mfma_f32_16x16x32_f16 v[116:119], v[170:173], v[178:181], v[116:119]
	v_mfma_f32_16x16x32_f16 v[104:107], v[162:165], v[186:189], v[104:107]
	v_mfma_f32_16x16x32_f16 v[100:103], v[170:173], v[186:189], v[100:103]
	v_mfma_f32_16x16x32_f16 v[88:91], v[162:165], v[204:207], v[88:91]
	v_mfma_f32_16x16x32_f16 v[84:87], v[170:173], v[204:207], v[84:87]
	v_mfma_f32_16x16x32_f16 v[72:75], v[162:165], v[224:227], v[72:75]
	v_mfma_f32_16x16x32_f16 v[68:71], v[170:173], v[224:227], v[68:71]
	v_mfma_f32_16x16x32_f16 v[120:123], v[166:169], v[182:185], v[120:123]
	v_mfma_f32_16x16x32_f16 v[116:119], v[174:177], v[182:185], v[116:119]
	v_mfma_f32_16x16x32_f16 v[104:107], v[166:169], v[190:193], v[104:107]
	v_mfma_f32_16x16x32_f16 v[100:103], v[174:177], v[190:193], v[100:103]
	v_mfma_f32_16x16x32_f16 v[88:91], v[166:169], v[220:223], v[88:91]
	v_mfma_f32_16x16x32_f16 v[84:87], v[174:177], v[220:223], v[84:87]
	v_mfma_f32_16x16x32_f16 v[72:75], v[166:169], v[228:231], v[72:75]
	v_mfma_f32_16x16x32_f16 v[68:71], v[174:177], v[228:231], v[68:71]
	s_barrier
; #define PG8_STAGE(bufoff, gbase, voff) do { _Pragma("unroll") for (int _i = 0; _i < 2; ++_i) \
;         __builtin_amdgcn_global_load_lds((const unsigned*)((const char*)(gbase) + (voff)[_i]), (LAS unsigned*)(lds + (bufoff) + ldsw + _i * 8192), 16, 0, 0); } while (0)
; #define PG8_LDA(dst, b, h) do { _Pragma("unroll") for (int m = 0; m < 4; ++m) _Pragma("unroll") for (int k = 0; k < 2; ++k) dst[m][k] = *(const LAS half8*)(lds + PG8_SA(b, h) + aoff + m * 2048 + k * 1024); } while (0)
; #define PG8_LDB(dst, b, h) do { _Pragma("unroll") for (int n = 0; n < 2; ++n) _Pragma("unroll") for (int k = 0; k < 2; ++k) dst[n][k] = *(const LAS half8*)(lds + PG8_SB(b, h) + boff + n * 2048 + k * 1024); } while (0)
; #define PG8_MMA(ai, bj, At, Bt) do { __builtin_amdgcn_s_setprio(1); _Pragma("unroll") for (int m = 0; m < 4; ++m) _Pragma("unroll") for (int n = 0; n < 2; ++n) _Pragma("unroll") for (int k = 0; k < 2; ++k) \
;         acc[ai][bj][m][n] = __builtin_amdgcn_mfma_f32_16x16x32_f16(Bt[n][k], At[m][k], acc[ai][bj][m][n], 0, 0, 0); __builtin_amdgcn_s_setprio(0); } while (0)
; #define PG8_BAR __builtin_amdgcn_s_barrier()
; template <class Epi, class Sched, bool ALIGN_EPI = false, bool SP2 = false>
; __device__ __forceinline__ void gemm_phase(LAS unsigned char* lds, const Gemm g, const Sched& S, const Epi& E) {
;     ...
;             if constexpr (SP2) {
;             PG8_LDB(B0, 0, 0); PG8_LDB(B1, 0, 1); PG8_SCHED; PG8_LDA(At, 0, 0); PG8_STAGE(PG8_SA(1, 1), a1 + hstepA, voffA);
;             PG8_WAIT_V(8); PG8_WAIT_L(0); PG8_BAR; PG8_MMA(0, 0, At, B0); PG8_MMA(0, 1, At, B1); PG8_BAR; PG8_SCHED;
;             PG8_LDA(At, 0, 1); PG8_STAGE(PG8_SB(0, 0), b2, voffB); PG8_STAGE(PG8_SB(0, 1), b2 + hstepB, voffB); PG8_STAGE(PG8_SA(0, 0), a2, voffA);
;             PG8_WAIT_V(8); PG8_WAIT_L(0); PG8_BAR; PG8_MMA(1, 0, At, B0); PG8_MMA(1, 1, At, B1); PG8_BAR; PG8_SCHED;
;             PG8_LDB(B0, 1, 0); PG8_LDB(B1, 1, 1); PG8_SCHED; PG8_LDA(At, 1, 0); PG8_STAGE(PG8_SA(0, 1), a2 + hstepA, voffA);
;             PG8_WAIT_V(8); PG8_WAIT_L(0); PG8_BAR; PG8_MMA(0, 0, At, B0); PG8_MMA(0, 1, At, B1); PG8_BAR; PG8_SCHED;
;             PG8_LDA(At, 1, 1); PG8_STAGE(PG8_SB(1, 0), b3, voffB); PG8_STAGE(PG8_SB(1, 1), b3 + hstepB, voffB); PG8_STAGE(PG8_SA(1, 0), a3, voffA);
;             PG8_WAIT_V(8); PG8_WAIT_L(0); PG8_BAR; PG8_MMA(1, 0, At, B0); PG8_MMA(1, 1, At, B1); PG8_BAR; PG8_SCHED;
	s_setprio 0
	s_add_i32 s22, s63, s25
	v_lshl_add_u64 v[194:195], v[194:195], 0, s[96:97]
	s_mov_b32 m0, s22
	ds_read_b128 v[178:181], v144 offset:49152
	ds_read_b128 v[182:185], v144 offset:50176
	ds_read_b128 v[186:189], v144 offset:51200
	ds_read_b128 v[190:193], v144 offset:52224
	ds_read_b128 v[204:207], v144 offset:53248
	ds_read_b128 v[220:223], v144 offset:54272
	ds_read_b128 v[224:227], v144 offset:55296
	ds_read_b128 v[228:231], v144 offset:56320
	global_load_lds_dwordx4 v[194:195], off
	s_add_i32 m0, s22, 0x2000
	s_add_u32 s16, s16, 0x80080
	v_lshl_add_u64 v[194:195], v[196:197], 0, s[96:97]
	s_addc_u32 s17, s17, 0
	s_add_i32 s22, s64, s25
	global_load_lds_dwordx4 v[194:195], off
	v_lshl_add_u64 v[194:195], s[16:17], 0, v[2:3]
	s_mov_b32 m0, s22
	s_nop 0
	global_load_lds_dwordx4 v[194:195], off
	v_lshl_add_u64 v[194:195], s[16:17], 0, v[132:133]
	s_add_i32 m0, s22, 0x2000
	s_nop 0
	global_load_lds_dwordx4 v[194:195], off
	v_lshl_add_u64 v[194:195], v[208:209], 0, s[96:97]
	s_mov_b32 m0, s53
	s_nop 0
	global_load_lds_dwordx4 v[194:195], off
	v_lshl_add_u64 v[194:195], v[232:233], 0, s[96:97]
	s_mov_b32 m0, s54
	s_nop 0
	global_load_lds_dwordx4 v[194:195], off
	s_waitcnt vmcnt(8)
	s_waitcnt lgkmcnt(0)
	s_setprio 1
	s_barrier
	v_mfma_f32_16x16x32_f16 v[64:67], v[146:149], v[178:181], v[64:67]
	v_mfma_f32_16x16x32_f16 v[60:63], v[154:157], v[178:181], v[60:63]
	v_mfma_f32_16x16x32_f16 v[48:51], v[146:149], v[186:189], v[48:51]
	v_mfma_f32_16x16x32_f16 v[44:47], v[154:157], v[186:189], v[44:47]
	v_mfma_f32_16x16x32_f16 v[32:35], v[146:149], v[204:207], v[32:35]
	v_mfma_f32_16x16x32_f16 v[28:31], v[154:157], v[204:207], v[28:31]
	v_mfma_f32_16x16x32_f16 v[16:19], v[146:149], v[224:227], v[16:19]
	v_mfma_f32_16x16x32_f16 v[12:15], v[154:157], v[224:227], v[12:15]
	v_mfma_f32_16x16x32_f16 v[64:67], v[150:153], v[182:185], v[64:67]
	v_mfma_f32_16x16x32_f16 v[60:63], v[158:161], v[182:185], v[60:63]
	v_mfma_f32_16x16x32_f16 v[48:51], v[150:153], v[190:193], v[48:51]
	v_mfma_f32_16x16x32_f16 v[44:47], v[158:161], v[190:193], v[44:47]
	v_mfma_f32_16x16x32_f16 v[32:35], v[150:153], v[220:223], v[32:35]
	v_mfma_f32_16x16x32_f16 v[28:31], v[158:161], v[220:223], v[28:31]
	v_mfma_f32_16x16x32_f16 v[16:19], v[150:153], v[228:231], v[16:19]
	v_mfma_f32_16x16x32_f16 v[12:15], v[158:161], v[228:231], v[12:15]
	v_mfma_f32_16x16x32_f16 v[56:59], v[162:165], v[178:181], v[56:59]
	v_mfma_f32_16x16x32_f16 v[52:55], v[170:173], v[178:181], v[52:55]
	v_mfma_f32_16x16x32_f16 v[40:43], v[162:165], v[186:189], v[40:43]
	v_mfma_f32_16x16x32_f16 v[36:39], v[170:173], v[186:189], v[36:39]
	v_mfma_f32_16x16x32_f16 v[24:27], v[162:165], v[204:207], v[24:27]
	v_mfma_f32_16x16x32_f16 v[20:23], v[170:173], v[204:207], v[20:23]
	v_mfma_f32_16x16x32_f16 v[8:11], v[162:165], v[224:227], v[8:11]
	v_mfma_f32_16x16x32_f16 v[4:7], v[170:173], v[224:227], v[4:7]
	v_mfma_f32_16x16x32_f16 v[56:59], v[166:169], v[182:185], v[56:59]
	v_mfma_f32_16x16x32_f16 v[52:55], v[174:177], v[182:185], v[52:55]
	v_mfma_f32_16x16x32_f16 v[40:43], v[166:169], v[190:193], v[40:43]
	v_mfma_f32_16x16x32_f16 v[36:39], v[174:177], v[190:193], v[36:39]
	v_mfma_f32_16x16x32_f16 v[24:27], v[166:169], v[220:223], v[24:27]
	v_mfma_f32_16x16x32_f16 v[20:23], v[174:177], v[220:223], v[20:23]
	v_mfma_f32_16x16x32_f16 v[8:11], v[166:169], v[228:231], v[8:11]
	v_mfma_f32_16x16x32_f16 v[4:7], v[174:177], v[228:231], v[4:7]
	s_barrier
	s_setprio 0
	s_add_i32 s62, s62, 2
	s_add_u32 s46, s46, 0x100
	s_addc_u32 s47, s47, 0
	s_add_u32 s60, s60, 0x100
	s_addc_u32 s61, s61, 0
	s_cmp_gt_u32 s62, 29
	s_cbranch_scc0 .LBB0_1101

; #define PG8_STAGE(bufoff, gbase, voff) do { _Pragma("unroll") for (int _i = 0; _i < 2; ++_i) \
;         __builtin_amdgcn_global_load_lds((const unsigned*)((const char*)(gbase) + (voff)[_i]), (LAS unsigned*)(lds + (bufoff) + ldsw + _i * 8192), 16, 0, 0); } while (0)
; #define PG8_WAIT_V(n) asm volatile("s_waitcnt vmcnt(" #n ")" ::: "memory")
; #define PG8_WAIT_L(n) asm volatile("s_waitcnt lgkmcnt(" #n ")" ::: "memory")
; template <class Epi, class Sched, bool ALIGN_EPI = false, bool SP2 = false>
; __device__ __forceinline__ void gemm_phase(LAS unsigned char* lds, const Gemm g, const Sched& S, const Epi& E) {
;     ...
;     f32x4 acc[2][2][4][2];
; #pragma unroll
;     for (int a = 0; a < 2; ++a)
; #pragma unroll
;         for (int b = 0; b < 2; ++b)
; #pragma unroll
;             for (int m = 0; m < 4; ++m)
; #pragma unroll
;                 for (int n = 0; n < 2; ++n) acc[a][b][m][n] = (f32x4){0.f, 0.f, 0.f, 0.f};
;     ...
;         for (int t = 0; t < nt; t += 2) {
;             const bool last = (t == nt - 2);
;             const char* a1 = cA + (size_t)(t + 1) * kstep;
;             const char* a2 = last ? nA : cA + (size_t)(t + 2) * kstep; const char* b2 = last ? nB : cB + (size_t)(t + 2) * kstep;
;             const char* a3 = a2 + kstep; const char* b3 = b2 + kstep;
;             if (last && has_next) S.a_ready(nxt);
;             if constexpr (SP2) {
;             PG8_LDB(B0, 0, 0); PG8_LDB(B1, 0, 1); PG8_SCHED; PG8_LDA(At, 0, 0); PG8_STAGE(PG8_SA(1, 1), a1 + hstepA, voffA);
;             PG8_WAIT_V(8); PG8_WAIT_L(0); PG8_BAR; PG8_MMA(0, 0, At, B0); PG8_MMA(0, 1, At, B1); PG8_BAR; PG8_SCHED;
;             PG8_LDA(At, 0, 1); PG8_STAGE(PG8_SB(0, 0), b2, voffB); PG8_STAGE(PG8_SB(0, 1), b2 + hstepB, voffB); PG8_STAGE(PG8_SA(0, 0), a2, voffA);
;             PG8_WAIT_V(8); PG8_WAIT_L(0); PG8_BAR; PG8_MMA(1, 0, At, B0); PG8_MMA(1, 1, At, B1); PG8_BAR; PG8_SCHED;
;             PG8_LDB(B0, 1, 0); PG8_LDB(B1, 1, 1); PG8_SCHED; PG8_LDA(At, 1, 0); PG8_STAGE(PG8_SA(0, 1), a2 + hstepA, voffA);
;             PG8_WAIT_V(8); PG8_WAIT_L(0); PG8_BAR; PG8_MMA(0, 0, At, B0); PG8_MMA(0, 1, At, B1); PG8_BAR; PG8_SCHED;
;             PG8_LDA(At, 1, 1); PG8_STAGE(PG8_SB(1, 0), b3, voffB); PG8_STAGE(PG8_SB(1, 1), b3 + hstepB, voffB); PG8_STAGE(PG8_SA(1, 0), a3, voffA);
;             PG8_WAIT_V(8); PG8_WAIT_L(0); PG8_BAR; PG8_MMA(1, 0, At, B0); PG8_MMA(1, 1, At, B1); PG8_BAR; PG8_SCHED;
.LBB0_1707:
	s_ashr_i32 s69, s68, 31
	s_lshl_b64 s[6:7], s[68:69], 20
	s_add_u32 s50, s34, s6
	s_addc_u32 s51, s35, s7
	s_and_b64 s[6:7], s[40:41], exec
	s_cselect_b32 s2, s51, s1
	s_cselect_b32 s12, s50, s0
	s_ashr_i32 s67, s66, 31
	s_lshl_b64 s[6:7], s[66:67], 20
	s_add_u32 s6, s37, s6
	s_addc_u32 s7, s25, s7
	s_and_b64 s[10:11], s[40:41], exec
	s_cselect_b32 s13, s7, s9
	s_cselect_b32 s14, s6, s8
	s_add_u32 s0, s0, 0x80080
	s_addc_u32 s1, s1, 0
	s_add_u32 s15, s8, 0x100
	v_mov_b32_e32 v4, 0
	s_addc_u32 s16, s9, 0
	s_mov_b32 s17, -2
	s_waitcnt lgkmcnt(0)
	s_waitcnt vmcnt(0)
	s_add_u32 s8, s0, 0xfff80080
	s_addc_u32 s9, s1, -1
	s_add_i32 s22, 0, 0x10000
	s_cmp_eq_u32 s17, 28
	s_cselect_b32 s11, s2, s9
	s_cselect_b32 s10, s12, s8
	v_add_u32_e32 v2, s22, v189
	s_cselect_b32 s9, s13, s16
	s_cselect_b32 s8, s14, s15
	s_add_i32 s44, 0, 0x14000
	ds_read_b128 v[132:135], v2
	ds_read_b128 v[136:139], v2 offset:1024
	ds_read_b128 v[140:143], v2 offset:2048
	ds_read_b128 v[144:147], v2 offset:3072
	v_add_u32_e32 v2, s44, v189
	ds_read_b128 v[148:151], v2
	ds_read_b128 v[152:155], v2 offset:1024
	ds_read_b128 v[156:159], v2 offset:2048
	ds_read_b128 v[160:163], v2 offset:3072
	v_lshl_add_u64 v[194:195], s[0:1], 0, v[172:173]
	s_add_i32 m0, s57, 0xc000
	ds_read_b128 v[176:179], v193
	ds_read_b128 v[180:183], v193 offset:1024
	ds_read_b128 v[184:187], v193 offset:2048
	ds_read_b128 v[204:207], v193 offset:3072
	ds_read_b128 v[220:223], v193 offset:4096
	ds_read_b128 v[224:227], v193 offset:5120
	ds_read_b128 v[228:231], v193 offset:6144
	ds_read_b128 v[232:235], v193 offset:7168
	global_load_lds_dwordx4 v[194:195], off
	v_lshl_add_u64 v[194:195], s[0:1], 0, v[174:175]
	s_add_i32 m0, s57, 0xe000
	s_nop 0
	global_load_lds_dwordx4 v[194:195], off
	s_waitcnt vmcnt(8)
	s_waitcnt lgkmcnt(0)
	s_setprio 1
	s_barrier
	v_mfma_f32_16x16x32_f16 v[128:131], v[132:135], v[176:179], 0
	v_mfma_f32_16x16x32_f16 v[124:127], v[140:143], v[176:179], 0
	v_mfma_f32_16x16x32_f16 v[112:115], v[132:135], v[184:187], 0
	v_mfma_f32_16x16x32_f16 v[108:111], v[140:143], v[184:187], 0
	v_mfma_f32_16x16x32_f16 v[96:99], v[132:135], v[220:223], 0
	v_mfma_f32_16x16x32_f16 v[92:95], v[140:143], v[220:223], 0
	v_mfma_f32_16x16x32_f16 v[80:83], v[132:135], v[228:231], 0
	v_mfma_f32_16x16x32_f16 v[76:79], v[140:143], v[228:231], 0
	v_mfma_f32_16x16x32_f16 v[128:131], v[136:139], v[180:183], v[128:131]
	v_mfma_f32_16x16x32_f16 v[124:127], v[144:147], v[180:183], v[124:127]
	v_mfma_f32_16x16x32_f16 v[112:115], v[136:139], v[204:207], v[112:115]
	v_mfma_f32_16x16x32_f16 v[108:111], v[144:147], v[204:207], v[108:111]
	v_mfma_f32_16x16x32_f16 v[96:99], v[136:139], v[224:227], v[96:99]
	v_mfma_f32_16x16x32_f16 v[92:95], v[144:147], v[224:227], v[92:95]
	v_mfma_f32_16x16x32_f16 v[80:83], v[136:139], v[232:235], v[80:83]
	v_mfma_f32_16x16x32_f16 v[76:79], v[144:147], v[232:235], v[76:79]
	v_mfma_f32_16x16x32_f16 v[120:123], v[148:151], v[176:179], 0
	v_mfma_f32_16x16x32_f16 v[116:119], v[156:159], v[176:179], 0
	v_mfma_f32_16x16x32_f16 v[104:107], v[148:151], v[184:187], 0
	v_mfma_f32_16x16x32_f16 v[100:103], v[156:159], v[184:187], 0
	v_mfma_f32_16x16x32_f16 v[88:91], v[148:151], v[220:223], 0
	v_mfma_f32_16x16x32_f16 v[84:87], v[156:159], v[220:223], 0
	v_mfma_f32_16x16x32_f16 v[72:75], v[148:151], v[228:231], 0
	v_mfma_f32_16x16x32_f16 v[68:71], v[156:159], v[228:231], 0
	v_mfma_f32_16x16x32_f16 v[120:123], v[152:155], v[180:183], v[120:123]
	v_mfma_f32_16x16x32_f16 v[116:119], v[160:163], v[180:183], v[116:119]
	v_mfma_f32_16x16x32_f16 v[104:107], v[152:155], v[204:207], v[104:107]
	v_mfma_f32_16x16x32_f16 v[100:103], v[160:163], v[204:207], v[100:103]
	v_mfma_f32_16x16x32_f16 v[88:91], v[152:155], v[224:227], v[88:91]
	v_mfma_f32_16x16x32_f16 v[84:87], v[160:163], v[224:227], v[84:87]
	v_mfma_f32_16x16x32_f16 v[72:75], v[152:155], v[232:235], v[72:75]
	v_mfma_f32_16x16x32_f16 v[68:71], v[160:163], v[232:235], v[68:71]
	s_barrier
	s_setprio 0
	s_add_i32 s22, s22, s56
	v_lshl_add_u64 v[194:195], s[8:9], 0, v[168:169]
	s_mov_b32 m0, s22
	ds_read_b128 v[176:179], v193 offset:16384
	ds_read_b128 v[180:183], v193 offset:17408
	ds_read_b128 v[184:187], v193 offset:18432
	ds_read_b128 v[204:207], v193 offset:19456
	ds_read_b128 v[220:223], v193 offset:20480
	ds_read_b128 v[224:227], v193 offset:21504
	ds_read_b128 v[228:231], v193 offset:22528
	ds_read_b128 v[232:235], v193 offset:23552
	global_load_lds_dwordx4 v[194:195], off
	s_add_i32 m0, s22, 0x2000
	s_add_u32 s22, s8, 0x80000
	v_lshl_add_u64 v[196:197], s[8:9], 0, v[164:165]
	s_addc_u32 s23, s9, 0
	s_add_i32 s44, s44, s56
	global_load_lds_dwordx4 v[196:197], off
	v_lshl_add_u64 v[208:209], s[22:23], 0, v[168:169]
	s_mov_b32 m0, s44
	v_lshl_add_u64 v[236:237], s[10:11], 0, v[166:167]
	global_load_lds_dwordx4 v[208:209], off
	v_lshl_add_u64 v[208:209], s[22:23], 0, v[164:165]
	s_add_i32 m0, s44, 0x2000
	s_nop 0
	global_load_lds_dwordx4 v[208:209], off
	v_lshl_add_u64 v[208:209], s[10:11], 0, v[170:171]
	s_mov_b32 m0, s57
	s_nop 0
	global_load_lds_dwordx4 v[208:209], off
	s_mov_b32 m0, s58
	s_nop 0
	global_load_lds_dwordx4 v[236:237], off
	s_waitcnt vmcnt(8)
	s_waitcnt lgkmcnt(0)
	s_setprio 1
	s_barrier
; #define PG8_STAGE(bufoff, gbase, voff) do { _Pragma("unroll") for (int _i = 0; _i < 2; ++_i) \
;         __builtin_amdgcn_global_load_lds((const unsigned*)((const char*)(gbase) + (voff)[_i]), (LAS unsigned*)(lds + (bufoff) + ldsw + _i * 8192), 16, 0, 0); } while (0)
; #define PG8_LDA(dst, b, h) do { _Pragma("unroll") for (int m = 0; m < 4; ++m) _Pragma("unroll") for (int k = 0; k < 2; ++k) dst[m][k] = *(const LAS half8*)(lds + PG8_SA(b, h) + aoff + m * 2048 + k * 1024); } while (0)
; #define PG8_LDB(dst, b, h) do { _Pragma("unroll") for (int n = 0; n < 2; ++n) _Pragma("unroll") for (int k = 0; k < 2; ++k) dst[n][k] = *(const LAS half8*)(lds + PG8_SB(b, h) + boff + n * 2048 + k * 1024); } while (0)
; #define PG8_MMA(ai, bj, At, Bt) do { __builtin_amdgcn_s_setprio(1); _Pragma("unroll") for (int m = 0; m < 4; ++m) _Pragma("unroll") for (int n = 0; n < 2; ++n) _Pragma("unroll") for (int k = 0; k < 2; ++k) \
;         acc[ai][bj][m][n] = __builtin_amdgcn_mfma_f32_16x16x32_f16(Bt[n][k], At[m][k], acc[ai][bj][m][n], 0, 0, 0); __builtin_amdgcn_s_setprio(0); } while (0)
; #define PG8_BAR __builtin_amdgcn_s_barrier()
; template <class Epi, class Sched, bool ALIGN_EPI = false, bool SP2 = false>
; __device__ __forceinline__ void gemm_phase(LAS unsigned char* lds, const Gemm g, const Sched& S, const Epi& E) {
;     ...
;             if constexpr (SP2) {
;             PG8_LDB(B0, 0, 0); PG8_LDB(B1, 0, 1); PG8_SCHED; PG8_LDA(At, 0, 0); PG8_STAGE(PG8_SA(1, 1), a1 + hstepA, voffA);
;             PG8_WAIT_V(8); PG8_WAIT_L(0); PG8_BAR; PG8_MMA(0, 0, At, B0); PG8_MMA(0, 1, At, B1); PG8_BAR; PG8_SCHED;
;             PG8_LDA(At, 0, 1); PG8_STAGE(PG8_SB(0, 0), b2, voffB); PG8_STAGE(PG8_SB(0, 1), b2 + hstepB, voffB); PG8_STAGE(PG8_SA(0, 0), a2, voffA);
;             PG8_WAIT_V(8); PG8_WAIT_L(0); PG8_BAR; PG8_MMA(1, 0, At, B0); PG8_MMA(1, 1, At, B1); PG8_BAR; PG8_SCHED;
;             PG8_LDB(B0, 1, 0); PG8_LDB(B1, 1, 1); PG8_SCHED; PG8_LDA(At, 1, 0); PG8_STAGE(PG8_SA(0, 1), a2 + hstepA, voffA);
;             PG8_WAIT_V(8); PG8_WAIT_L(0); PG8_BAR; PG8_MMA(0, 0, At, B0); PG8_MMA(0, 1, At, B1); PG8_BAR; PG8_SCHED;
;             PG8_LDA(At, 1, 1); PG8_STAGE(PG8_SB(1, 0), b3, voffB); PG8_STAGE(PG8_SB(1, 1), b3 + hstepB, voffB); PG8_STAGE(PG8_SA(1, 0), a3, voffA);
;             PG8_WAIT_V(8); PG8_WAIT_L(0); PG8_BAR; PG8_MMA(1, 0, At, B0); PG8_MMA(1, 1, At, B1); PG8_BAR; PG8_SCHED;
	v_mfma_f32_16x16x32_f16 v[64:67], v[132:135], v[176:179], 0
	v_mfma_f32_16x16x32_f16 v[60:63], v[140:143], v[176:179], 0
	v_mfma_f32_16x16x32_f16 v[48:51], v[132:135], v[184:187], 0
	v_mfma_f32_16x16x32_f16 v[44:47], v[140:143], v[184:187], 0
	v_mfma_f32_16x16x32_f16 v[32:35], v[132:135], v[220:223], 0
	v_mfma_f32_16x16x32_f16 v[28:31], v[140:143], v[220:223], 0
	v_mfma_f32_16x16x32_f16 v[16:19], v[132:135], v[228:231], 0
	v_mfma_f32_16x16x32_f16 v[12:15], v[140:143], v[228:231], 0
	v_mfma_f32_16x16x32_f16 v[64:67], v[136:139], v[180:183], v[64:67]
	v_mfma_f32_16x16x32_f16 v[60:63], v[144:147], v[180:183], v[60:63]
	v_mfma_f32_16x16x32_f16 v[48:51], v[136:139], v[204:207], v[48:51]
	v_mfma_f32_16x16x32_f16 v[44:47], v[144:147], v[204:207], v[44:47]
	v_mfma_f32_16x16x32_f16 v[32:35], v[136:139], v[224:227], v[32:35]
	v_mfma_f32_16x16x32_f16 v[28:31], v[144:147], v[224:227], v[28:31]
	v_mfma_f32_16x16x32_f16 v[16:19], v[136:139], v[232:235], v[16:19]
	v_mfma_f32_16x16x32_f16 v[12:15], v[144:147], v[232:235], v[12:15]
	v_mfma_f32_16x16x32_f16 v[56:59], v[148:151], v[176:179], 0
	v_mfma_f32_16x16x32_f16 v[52:55], v[156:159], v[176:179], 0
	v_mfma_f32_16x16x32_f16 v[40:43], v[148:151], v[184:187], 0
	v_mfma_f32_16x16x32_f16 v[36:39], v[156:159], v[184:187], 0
	v_mfma_f32_16x16x32_f16 v[24:27], v[148:151], v[220:223], 0
	v_mfma_f32_16x16x32_f16 v[20:23], v[156:159], v[220:223], 0
	v_mfma_f32_16x16x32_f16 v[8:11], v[148:151], v[228:231], 0
	v_mfma_f32_16x16x32_f16 v[4:7], v[156:159], v[228:231], 0
	v_mfma_f32_16x16x32_f16 v[56:59], v[152:155], v[180:183], v[56:59]
	v_mfma_f32_16x16x32_f16 v[52:55], v[160:163], v[180:183], v[52:55]
	v_mfma_f32_16x16x32_f16 v[40:43], v[152:155], v[204:207], v[40:43]
	v_mfma_f32_16x16x32_f16 v[36:39], v[160:163], v[204:207], v[36:39]
	v_mfma_f32_16x16x32_f16 v[24:27], v[152:155], v[224:227], v[24:27]
	v_mfma_f32_16x16x32_f16 v[20:23], v[160:163], v[224:227], v[20:23]
	v_mfma_f32_16x16x32_f16 v[8:11], v[152:155], v[232:235], v[8:11]
	v_mfma_f32_16x16x32_f16 v[4:7], v[160:163], v[232:235], v[4:7]
	s_barrier
	s_setprio 0
	s_add_i32 s22, 0, 0x18000
	v_add_u32_e32 v2, s22, v189
	s_add_i32 s23, 0, 0x1c000
	ds_read_b128 v[132:135], v2
	ds_read_b128 v[136:139], v2 offset:1024
	ds_read_b128 v[140:143], v2 offset:2048
	ds_read_b128 v[144:147], v2 offset:3072
	v_add_u32_e32 v2, s23, v189
	ds_read_b128 v[148:151], v2
	ds_read_b128 v[152:155], v2 offset:1024
	ds_read_b128 v[156:159], v2 offset:2048
	ds_read_b128 v[160:163], v2 offset:3072
	s_add_u32 s10, s10, 0x80000
	s_addc_u32 s11, s11, 0
	s_mov_b32 m0, s59
	v_lshl_add_u64 v[240:241], s[10:11], 0, v[170:171]
	ds_read_b128 v[176:179], v193 offset:32768
	ds_read_b128 v[180:183], v193 offset:33792
	ds_read_b128 v[184:187], v193 offset:34816
	ds_read_b128 v[204:207], v193 offset:35840
	ds_read_b128 v[220:223], v193 offset:36864
	ds_read_b128 v[224:227], v193 offset:37888
	ds_read_b128 v[228:231], v193 offset:38912
	ds_read_b128 v[232:235], v193 offset:39936
	global_load_lds_dwordx4 v[240:241], off
	v_lshl_add_u64 v[240:241], s[10:11], 0, v[166:167]
	s_mov_b32 m0, s60
	s_nop 0
	global_load_lds_dwordx4 v[240:241], off
	s_waitcnt vmcnt(8)
	s_waitcnt lgkmcnt(0)
	s_setprio 1
	s_barrier
	v_mfma_f32_16x16x32_f16 v[128:131], v[132:135], v[176:179], v[128:131]
	v_mfma_f32_16x16x32_f16 v[124:127], v[140:143], v[176:179], v[124:127]
	v_mfma_f32_16x16x32_f16 v[112:115], v[132:135], v[184:187], v[112:115]
	v_mfma_f32_16x16x32_f16 v[108:111], v[140:143], v[184:187], v[108:111]
	v_mfma_f32_16x16x32_f16 v[96:99], v[132:135], v[220:223], v[96:99]
	v_mfma_f32_16x16x32_f16 v[92:95], v[140:143], v[220:223], v[92:95]
	v_mfma_f32_16x16x32_f16 v[80:83], v[132:135], v[228:231], v[80:83]
	v_mfma_f32_16x16x32_f16 v[76:79], v[140:143], v[228:231], v[76:79]
	v_mfma_f32_16x16x32_f16 v[128:131], v[136:139], v[180:183], v[128:131]
	v_mfma_f32_16x16x32_f16 v[124:127], v[144:147], v[180:183], v[124:127]
	v_mfma_f32_16x16x32_f16 v[112:115], v[136:139], v[204:207], v[112:115]
	v_mfma_f32_16x16x32_f16 v[108:111], v[144:147], v[204:207], v[108:111]
	v_mfma_f32_16x16x32_f16 v[96:99], v[136:139], v[224:227], v[96:99]
	v_mfma_f32_16x16x32_f16 v[92:95], v[144:147], v[224:227], v[92:95]
	v_mfma_f32_16x16x32_f16 v[80:83], v[136:139], v[232:235], v[80:83]
	v_mfma_f32_16x16x32_f16 v[76:79], v[144:147], v[232:235], v[76:79]
	v_mfma_f32_16x16x32_f16 v[120:123], v[148:151], v[176:179], v[120:123]
	v_mfma_f32_16x16x32_f16 v[116:119], v[156:159], v[176:179], v[116:119]
	v_mfma_f32_16x16x32_f16 v[104:107], v[148:151], v[184:187], v[104:107]
	v_mfma_f32_16x16x32_f16 v[100:103], v[156:159], v[184:187], v[100:103]
	v_mfma_f32_16x16x32_f16 v[88:91], v[148:151], v[220:223], v[88:91]
	v_mfma_f32_16x16x32_f16 v[84:87], v[156:159], v[220:223], v[84:87]
	v_mfma_f32_16x16x32_f16 v[72:75], v[148:151], v[228:231], v[72:75]
	v_mfma_f32_16x16x32_f16 v[68:71], v[156:159], v[228:231], v[68:71]
	v_mfma_f32_16x16x32_f16 v[120:123], v[152:155], v[180:183], v[120:123]
	v_mfma_f32_16x16x32_f16 v[116:119], v[160:163], v[180:183], v[116:119]
	v_mfma_f32_16x16x32_f16 v[104:107], v[152:155], v[204:207], v[104:107]
	v_mfma_f32_16x16x32_f16 v[100:103], v[160:163], v[204:207], v[100:103]
	v_mfma_f32_16x16x32_f16 v[88:91], v[152:155], v[224:227], v[88:91]
	v_mfma_f32_16x16x32_f16 v[84:87], v[160:163], v[224:227], v[84:87]
	v_mfma_f32_16x16x32_f16 v[72:75], v[152:155], v[232:235], v[72:75]
	v_mfma_f32_16x16x32_f16 v[68:71], v[160:163], v[232:235], v[68:71]
	s_barrier
; #define PG8_STAGE(bufoff, gbase, voff) do { _Pragma("unroll") for (int _i = 0; _i < 2; ++_i) \
;         __builtin_amdgcn_global_load_lds((const unsigned*)((const char*)(gbase) + (voff)[_i]), (LAS unsigned*)(lds + (bufoff) + ldsw + _i * 8192), 16, 0, 0); } while (0)
; #define PG8_LDA(dst, b, h) do { _Pragma("unroll") for (int m = 0; m < 4; ++m) _Pragma("unroll") for (int k = 0; k < 2; ++k) dst[m][k] = *(const LAS half8*)(lds + PG8_SA(b, h) + aoff + m * 2048 + k * 1024); } while (0)
; #define PG8_LDB(dst, b, h) do { _Pragma("unroll") for (int n = 0; n < 2; ++n) _Pragma("unroll") for (int k = 0; k < 2; ++k) dst[n][k] = *(const LAS half8*)(lds + PG8_SB(b, h) + boff + n * 2048 + k * 1024); } while (0)
; #define PG8_MMA(ai, bj, At, Bt) do { __builtin_amdgcn_s_setprio(1); _Pragma("unroll") for (int m = 0; m < 4; ++m) _Pragma("unroll") for (int n = 0; n < 2; ++n) _Pragma("unroll") for (int k = 0; k < 2; ++k) \
;         acc[ai][bj][m][n] = __builtin_amdgcn_mfma_f32_16x16x32_f16(Bt[n][k], At[m][k], acc[ai][bj][m][n], 0, 0, 0); __builtin_amdgcn_s_setprio(0); } while (0)
; #define PG8_BAR __builtin_amdgcn_s_barrier()
; template <class Epi, class Sched, bool ALIGN_EPI = false, bool SP2 = false>
; __device__ __forceinline__ void gemm_phase(LAS unsigned char* lds, const Gemm g, const Sched& S, const Epi& E) {
;     ...
;             if constexpr (SP2) {
;             PG8_LDB(B0, 0, 0); PG8_LDB(B1, 0, 1); PG8_SCHED; PG8_LDA(At, 0, 0); PG8_STAGE(PG8_SA(1, 1), a1 + hstepA, voffA);
;             PG8_WAIT_V(8); PG8_WAIT_L(0); PG8_BAR; PG8_MMA(0, 0, At, B0); PG8_MMA(0, 1, At, B1); PG8_BAR; PG8_SCHED;
;             PG8_LDA(At, 0, 1); PG8_STAGE(PG8_SB(0, 0), b2, voffB); PG8_STAGE(PG8_SB(0, 1), b2 + hstepB, voffB); PG8_STAGE(PG8_SA(0, 0), a2, voffA);
;             PG8_WAIT_V(8); PG8_WAIT_L(0); PG8_BAR; PG8_MMA(1, 0, At, B0); PG8_MMA(1, 1, At, B1); PG8_BAR; PG8_SCHED;
;             PG8_LDB(B0, 1, 0); PG8_LDB(B1, 1, 1); PG8_SCHED; PG8_LDA(At, 1, 0); PG8_STAGE(PG8_SA(0, 1), a2 + hstepA, voffA);
;             PG8_WAIT_V(8); PG8_WAIT_L(0); PG8_BAR; PG8_MMA(0, 0, At, B0); PG8_MMA(0, 1, At, B1); PG8_BAR; PG8_SCHED;
;             PG8_LDA(At, 1, 1); PG8_STAGE(PG8_SB(1, 0), b3, voffB); PG8_STAGE(PG8_SB(1, 1), b3 + hstepB, voffB); PG8_STAGE(PG8_SA(1, 0), a3, voffA);
;             PG8_WAIT_V(8); PG8_WAIT_L(0); PG8_BAR; PG8_MMA(1, 0, At, B0); PG8_MMA(1, 1, At, B1); PG8_BAR; PG8_SCHED;
	s_setprio 0
	s_add_i32 s10, s22, s56
	v_lshl_add_u64 v[194:195], v[194:195], 0, s[96:97]
	s_mov_b32 m0, s10
	ds_read_b128 v[176:179], v193 offset:49152
	ds_read_b128 v[180:183], v193 offset:50176
	ds_read_b128 v[184:187], v193 offset:51200
	ds_read_b128 v[204:207], v193 offset:52224
	ds_read_b128 v[220:223], v193 offset:53248
	ds_read_b128 v[224:227], v193 offset:54272
	ds_read_b128 v[228:231], v193 offset:55296
	ds_read_b128 v[232:235], v193 offset:56320
	global_load_lds_dwordx4 v[194:195], off
	s_add_i32 m0, s10, 0x2000
	s_add_u32 s8, s8, 0x80080
	v_lshl_add_u64 v[194:195], v[196:197], 0, s[96:97]
	s_addc_u32 s9, s9, 0
	s_add_i32 s10, s23, s56
	global_load_lds_dwordx4 v[194:195], off
	v_lshl_add_u64 v[194:195], s[8:9], 0, v[168:169]
	s_mov_b32 m0, s10
	s_nop 0
	global_load_lds_dwordx4 v[194:195], off
	v_lshl_add_u64 v[194:195], s[8:9], 0, v[164:165]
	s_add_i32 m0, s10, 0x2000
	s_nop 0
	global_load_lds_dwordx4 v[194:195], off
	v_lshl_add_u64 v[194:195], v[208:209], 0, s[96:97]
	s_mov_b32 m0, s62
	s_nop 0
	global_load_lds_dwordx4 v[194:195], off
	v_lshl_add_u64 v[194:195], v[236:237], 0, s[96:97]
	s_mov_b32 m0, s63
	s_nop 0
	global_load_lds_dwordx4 v[194:195], off
	s_waitcnt vmcnt(8)
	s_waitcnt lgkmcnt(0)
	s_setprio 1
	s_barrier
	v_mfma_f32_16x16x32_f16 v[64:67], v[132:135], v[176:179], v[64:67]
	v_mfma_f32_16x16x32_f16 v[60:63], v[140:143], v[176:179], v[60:63]
	v_mfma_f32_16x16x32_f16 v[48:51], v[132:135], v[184:187], v[48:51]
	v_mfma_f32_16x16x32_f16 v[44:47], v[140:143], v[184:187], v[44:47]
	v_mfma_f32_16x16x32_f16 v[32:35], v[132:135], v[220:223], v[32:35]
	v_mfma_f32_16x16x32_f16 v[28:31], v[140:143], v[220:223], v[28:31]
	v_mfma_f32_16x16x32_f16 v[16:19], v[132:135], v[228:231], v[16:19]
	v_mfma_f32_16x16x32_f16 v[12:15], v[140:143], v[228:231], v[12:15]
	v_mfma_f32_16x16x32_f16 v[64:67], v[136:139], v[180:183], v[64:67]
	v_mfma_f32_16x16x32_f16 v[60:63], v[144:147], v[180:183], v[60:63]
	v_mfma_f32_16x16x32_f16 v[48:51], v[136:139], v[204:207], v[48:51]
	v_mfma_f32_16x16x32_f16 v[44:47], v[144:147], v[204:207], v[44:47]
	v_mfma_f32_16x16x32_f16 v[32:35], v[136:139], v[224:227], v[32:35]
	v_mfma_f32_16x16x32_f16 v[28:31], v[144:147], v[224:227], v[28:31]
	v_mfma_f32_16x16x32_f16 v[16:19], v[136:139], v[232:235], v[16:19]
	v_mfma_f32_16x16x32_f16 v[12:15], v[144:147], v[232:235], v[12:15]
	v_mfma_f32_16x16x32_f16 v[56:59], v[148:151], v[176:179], v[56:59]
	v_mfma_f32_16x16x32_f16 v[52:55], v[156:159], v[176:179], v[52:55]
	v_mfma_f32_16x16x32_f16 v[40:43], v[148:151], v[184:187], v[40:43]
	v_mfma_f32_16x16x32_f16 v[36:39], v[156:159], v[184:187], v[36:39]
	v_mfma_f32_16x16x32_f16 v[24:27], v[148:151], v[220:223], v[24:27]
	v_mfma_f32_16x16x32_f16 v[20:23], v[156:159], v[220:223], v[20:23]
	v_mfma_f32_16x16x32_f16 v[8:11], v[148:151], v[228:231], v[8:11]
	v_mfma_f32_16x16x32_f16 v[4:7], v[156:159], v[228:231], v[4:7]
	v_mfma_f32_16x16x32_f16 v[56:59], v[152:155], v[180:183], v[56:59]
	v_mfma_f32_16x16x32_f16 v[52:55], v[160:163], v[180:183], v[52:55]
	v_mfma_f32_16x16x32_f16 v[40:43], v[152:155], v[204:207], v[40:43]
	v_mfma_f32_16x16x32_f16 v[36:39], v[160:163], v[204:207], v[36:39]
	v_mfma_f32_16x16x32_f16 v[24:27], v[152:155], v[224:227], v[24:27]
	v_mfma_f32_16x16x32_f16 v[20:23], v[160:163], v[224:227], v[20:23]
	v_mfma_f32_16x16x32_f16 v[8:11], v[152:155], v[232:235], v[8:11]
	v_mfma_f32_16x16x32_f16 v[4:7], v[160:163], v[232:235], v[4:7]
	s_barrier
	s_setprio 0
	s_add_i32 s17, s17, 2
	s_add_u32 s0, s0, 0x100
	s_addc_u32 s1, s1, 0
	s_add_u32 s15, s15, 0x100
	s_addc_u32 s16, s16, 0
	s_cmp_gt_u32 s17, 29
	s_cbranch_scc0 .LBB0_1708

; #define PG8_WAIT_V(n) asm volatile("s_waitcnt vmcnt(" #n ")" ::: "memory")
; #define PG8_BAR __builtin_amdgcn_s_barrier()
; template <class Epi, class Sched, bool ALIGN_EPI = false, bool SP2 = false>
; __device__ __forceinline__ void gemm_phase(LAS unsigned char* lds, const Gemm g, const Sched& S, const Epi& E) {
;     ...
;         PG8_STAGE(PG8_SB(1, 0), cB + kstep, voffB); PG8_STAGE(PG8_SA(1, 0), cA + kstep, voffA); PG8_STAGE(PG8_SB(1, 1), cB + hstepB + kstep, voffB);
;         PG8_WAIT_V(6); PG8_BAR;
;     } else {
;         PG8_STAGE(PG8_SB(0, 0), cB, voffB); PG8_STAGE(PG8_SA(0, 0), cA, voffA); PG8_STAGE(PG8_SB(0, 1), cB + hstepB, voffB); PG8_STAGE(PG8_SA(0, 1), cA + hstepA, voffA);
;         if (wr == 1) PG8_BAR;
;         PG8_WAIT_V(4); PG8_BAR;
;         PG8_STAGE(PG8_SB(1, 0), cB + kstep, voffB); PG8_STAGE(PG8_SA(1, 0), cA + kstep, voffA); PG8_STAGE(PG8_SB(1, 1), cB + hstepB + kstep, voffB);
;         PG8_WAIT_V(6); PG8_BAR;
;     }
;     for (;;) {
;         const bool has_next = S.next(ui + 1, nxt);
;         const char* nA = has_next ? (const char*)g.A + (size_t)nxt.pm * tstepA : cA; const char* nB = has_next ? (const char*)g.Bt + (size_t)nxt.pn * tstepB : cB;
;         for (int t = 0; t < nt; t += 2) {
;             const bool last = (t == nt - 2);
;             const char* a1 = cA + (size_t)(t + 1) * kstep;
;             const char* a2 = last ? nA : cA + (size_t)(t + 2) * kstep; const char* b2 = last ? nB : cB + (size_t)(t + 2) * kstep;
;             const char* a3 = a2 + kstep; const char* b3 = b2 + kstep;
;             if (last && has_next) S.a_ready(nxt);
;             if constexpr (SP2) {
;             PG8_LDB(B0, 0, 0); PG8_LDB(B1, 0, 1); PG8_SCHED; PG8_LDA(At, 0, 0); PG8_STAGE(PG8_SA(1, 1), a1 + hstepA, voffA);
;             PG8_WAIT_V(8); PG8_WAIT_L(0); PG8_BAR; PG8_MMA(0, 0, At, B0); PG8_MMA(0, 1, At, B1); PG8_BAR; PG8_SCHED;
;             PG8_LDA(At, 0, 1); PG8_STAGE(PG8_SB(0, 0), b2, voffB); PG8_STAGE(PG8_SB(0, 1), b2 + hstepB, voffB); PG8_STAGE(PG8_SA(0, 0), a2, voffA);
;             PG8_WAIT_V(8); PG8_WAIT_L(0); PG8_BAR; PG8_MMA(1, 0, At, B0); PG8_MMA(1, 1, At, B1); PG8_BAR; PG8_SCHED;
;             PG8_LDB(B0, 1, 0); PG8_LDB(B1, 1, 1); PG8_SCHED; PG8_LDA(At, 1, 0); PG8_STAGE(PG8_SA(0, 1), a2 + hstepA, voffA);
;             PG8_WAIT_V(8); PG8_WAIT_L(0); PG8_BAR; PG8_MMA(0, 0, At, B0); PG8_MMA(0, 1, At, B1); PG8_BAR; PG8_SCHED;
.LBB0_2221:
	v_lshrrev_b32_e32 v20, 1, v17
	v_and_b32_e32 v142, 24, v20
	s_lshl_b32 s2, s2, 5
	v_and_b32_e32 v19, 15, v17
	v_lshlrev_b32_e32 v20, 1, v142
	v_lshlrev_b32_e32 v17, 2, v17
	s_and_b32 s58, s2, 0x60
	v_lshl_or_b32 v1, s13, 6, v19
	v_lshl_or_b32 v19, v19, 6, v20
	v_and_b32_e32 v17, 32, v17
	s_lshl_b32 s2, s58, 7
	s_lshl_b32 s13, s13, 13
	v_bitop3_b32 v143, v19, s2, v17 bitop3:0xde
	s_lshl_b32 s2, s56, 19
	v_bitop3_b32 v20, v19, s13, v17 bitop3:0xde
	s_and_b32 s13, s2, 0x100000
	s_lshl_b32 s2, s53, 7
	s_and_b32 s2, s2, 0xfffffe00
	v_cndmask_b32_e64 v17, 0, 1, s[44:45]
	s_lshl_b64 s[14:15], s[2:3], 1
	v_readfirstlane_b32 s2, v17
	s_lshl_b32 s2, s2, 19
	s_add_i32 s2, s22, s2
	s_lshl_b64 s[16:17], s[2:3], 1
	s_add_u32 s2, s14, s16
	s_addc_u32 s16, s15, s17
	v_readlane_b32 s17, v254, 42
	s_add_u32 s2, s17, s2
	v_readlane_b32 s17, v254, 43
	s_addc_u32 s59, s17, s16
	s_add_i32 m0, s37, 0x18000
	v_lshl_add_u64 v[10:11], v[10:11], 0, s[96:97]
	s_waitcnt vmcnt(2)
	s_barrier
	global_load_lds_dwordx4 v[10:11], off
	v_lshl_add_u64 v[8:9], v[8:9], 0, s[96:97]
	s_add_i32 m0, s37, 0x1a000
	s_add_i32 s60, s37, 0x8000
	s_add_i32 s61, s37, 0xa000
	global_load_lds_dwordx4 v[8:9], off
	v_lshl_add_u64 v[6:7], v[6:7], 0, s[96:97]
	s_mov_b32 m0, s60
	s_add_u32 s16, s8, 0x80080
	global_load_lds_dwordx4 v[6:7], off
	v_lshl_add_u64 v[4:5], v[4:5], 0, s[96:97]
	s_mov_b32 m0, s61
	s_addc_u32 s17, s9, 0
	global_load_lds_dwordx4 v[4:5], off
	s_add_i32 m0, s37, 0x1c000
	v_lshl_add_u64 v[4:5], s[16:17], 0, v[2:3]
	global_load_lds_dwordx4 v[4:5], off
	v_lshl_add_u64 v[4:5], s[16:17], 0, v[132:133]
	s_add_i32 m0, s37, 0x1e000
	s_add_u32 s12, s12, s13
	global_load_lds_dwordx4 v[4:5], off
	s_addc_u32 s13, 0, 0
	s_add_u32 s12, s12, s14
	s_addc_u32 s13, s13, s15
	v_lshlrev_b32_e32 v4, 15, v16
	s_add_u32 s62, s74, s12
	v_and_b32_e32 v4, 0xffff0000, v4
	s_addc_u32 s63, s75, s13
	v_lshl_add_u32 v4, v15, 12, v4
	v_and_b32_e32 v5, 1, v16
	v_readlane_b32 s14, v254, 40
	v_lshl_or_b32 v4, v5, 6, v4
	s_add_u32 s12, s14, s12
	v_readlane_b32 s14, v254, 41
	v_lshl_add_u32 v4, v18, 1, v4
	v_mov_b32_e32 v5, v3
	s_addc_u32 s13, s14, s13
	v_lshl_add_u64 v[138:139], s[12:13], 0, v[4:5]
	v_lshlrev_b32_e32 v4, 15, v12
	v_and_b32_e32 v4, 0xffff0000, v4
	v_lshl_add_u32 v4, v13, 12, v4
	v_and_b32_e32 v5, 1, v12
	v_lshl_or_b32 v4, v5, 6, v4
	s_waitcnt vmcnt(6)
	v_lshl_add_u32 v4, v14, 1, v4
	v_mov_b32_e32 v5, v3
	v_lshl_add_u64 v[140:141], s[12:13], 0, v[4:5]
	v_mov_b32_e32 v4, 0
	s_mov_b32 s64, -2
	s_mov_b64 s[12:13], 0
	v_add_u32_e32 v144, 0, v20
	s_waitcnt vmcnt(0)
	s_barrier
	s_add_u32 s14, s62, s12
	s_addc_u32 s15, s63, s13
	s_add_u32 s14, s14, 0x100
	s_addc_u32 s15, s15, 0
	s_add_u32 s65, s2, s12
	s_addc_u32 s66, s59, s13
	s_add_i32 s67, 0, 0x10000
	s_cmpk_eq_i32 s12, 0x300
	s_cselect_b32 s17, s11, s15
	s_cselect_b32 s16, s10, s14
	v_add_u32_e32 v145, s67, v143
	s_cselect_b32 s15, s9, s66
	s_cselect_b32 s14, s8, s65
	s_add_i32 s65, 0, 0x14000
	ds_read_b128 v[146:149], v145
	ds_read_b128 v[150:153], v145 offset:1024
	ds_read_b128 v[154:157], v145 offset:2048
	ds_read_b128 v[158:161], v145 offset:3072
	v_add_u32_e32 v145, s65, v143
	ds_read_b128 v[162:165], v145
	ds_read_b128 v[166:169], v145 offset:1024
	ds_read_b128 v[170:173], v145 offset:2048
	ds_read_b128 v[174:177], v145 offset:3072
	v_lshl_add_u64 v[194:195], v[138:139], 0, s[12:13]
	s_add_i32 m0, s37, 0xc000
	ds_read_b128 v[178:181], v144
	ds_read_b128 v[182:185], v144 offset:1024
	ds_read_b128 v[186:189], v144 offset:2048
	ds_read_b128 v[190:193], v144 offset:3072
	ds_read_b128 v[204:207], v144 offset:4096
	ds_read_b128 v[220:223], v144 offset:5120
	ds_read_b128 v[224:227], v144 offset:6144
	ds_read_b128 v[228:231], v144 offset:7168
	global_load_lds_dwordx4 v[194:195], off
	v_lshl_add_u64 v[194:195], v[140:141], 0, s[12:13]
	s_add_i32 m0, s37, 0xe000
	s_nop 0
	global_load_lds_dwordx4 v[194:195], off
	s_waitcnt vmcnt(8)
	s_waitcnt lgkmcnt(0)
	s_setprio 1
	s_barrier
	v_mfma_f32_16x16x32_f16 v[128:131], v[146:149], v[178:181], 0
	v_mfma_f32_16x16x32_f16 v[124:127], v[154:157], v[178:181], 0
	v_mfma_f32_16x16x32_f16 v[120:123], v[146:149], v[186:189], 0
	v_mfma_f32_16x16x32_f16 v[116:119], v[154:157], v[186:189], 0
	v_mfma_f32_16x16x32_f16 v[108:111], v[146:149], v[204:207], 0
	v_mfma_f32_16x16x32_f16 v[100:103], v[154:157], v[204:207], 0
	v_mfma_f32_16x16x32_f16 v[92:95], v[146:149], v[224:227], 0
	v_mfma_f32_16x16x32_f16 v[84:87], v[154:157], v[224:227], 0
	v_mfma_f32_16x16x32_f16 v[128:131], v[150:153], v[182:185], v[128:131]
	v_mfma_f32_16x16x32_f16 v[124:127], v[158:161], v[182:185], v[124:127]
	v_mfma_f32_16x16x32_f16 v[120:123], v[150:153], v[190:193], v[120:123]
	v_mfma_f32_16x16x32_f16 v[116:119], v[158:161], v[190:193], v[116:119]
	v_mfma_f32_16x16x32_f16 v[108:111], v[150:153], v[220:223], v[108:111]
	v_mfma_f32_16x16x32_f16 v[100:103], v[158:161], v[220:223], v[100:103]
	v_mfma_f32_16x16x32_f16 v[92:95], v[150:153], v[228:231], v[92:95]
	v_mfma_f32_16x16x32_f16 v[84:87], v[158:161], v[228:231], v[84:87]
	v_mfma_f32_16x16x32_f16 v[112:115], v[162:165], v[178:181], 0
	v_mfma_f32_16x16x32_f16 v[104:107], v[170:173], v[178:181], 0
	v_mfma_f32_16x16x32_f16 v[96:99], v[162:165], v[186:189], 0
	v_mfma_f32_16x16x32_f16 v[88:91], v[170:173], v[186:189], 0
	v_mfma_f32_16x16x32_f16 v[80:83], v[162:165], v[204:207], 0
	v_mfma_f32_16x16x32_f16 v[76:79], v[170:173], v[204:207], 0
	v_mfma_f32_16x16x32_f16 v[72:75], v[162:165], v[224:227], 0
	v_mfma_f32_16x16x32_f16 v[68:71], v[170:173], v[224:227], 0
	v_mfma_f32_16x16x32_f16 v[112:115], v[166:169], v[182:185], v[112:115]
	v_mfma_f32_16x16x32_f16 v[104:107], v[174:177], v[182:185], v[104:107]
	v_mfma_f32_16x16x32_f16 v[96:99], v[166:169], v[190:193], v[96:99]
	v_mfma_f32_16x16x32_f16 v[88:91], v[174:177], v[190:193], v[88:91]
	v_mfma_f32_16x16x32_f16 v[80:83], v[166:169], v[220:223], v[80:83]
	v_mfma_f32_16x16x32_f16 v[76:79], v[174:177], v[220:223], v[76:79]
	v_mfma_f32_16x16x32_f16 v[72:75], v[166:169], v[228:231], v[72:75]
	v_mfma_f32_16x16x32_f16 v[68:71], v[174:177], v[228:231], v[68:71]
	s_barrier
; #define PG8_STAGE(bufoff, gbase, voff) do { _Pragma("unroll") for (int _i = 0; _i < 2; ++_i) \
;         __builtin_amdgcn_global_load_lds((const unsigned*)((const char*)(gbase) + (voff)[_i]), (LAS unsigned*)(lds + (bufoff) + ldsw + _i * 8192), 16, 0, 0); } while (0)
; #define PG8_LDA(dst, b, h) do { _Pragma("unroll") for (int m = 0; m < 4; ++m) _Pragma("unroll") for (int k = 0; k < 2; ++k) dst[m][k] = *(const LAS half8*)(lds + PG8_SA(b, h) + aoff + m * 2048 + k * 1024); } while (0)
; #define PG8_LDB(dst, b, h) do { _Pragma("unroll") for (int n = 0; n < 2; ++n) _Pragma("unroll") for (int k = 0; k < 2; ++k) dst[n][k] = *(const LAS half8*)(lds + PG8_SB(b, h) + boff + n * 2048 + k * 1024); } while (0)
; #define PG8_MMA(ai, bj, At, Bt) do { __builtin_amdgcn_s_setprio(1); _Pragma("unroll") for (int m = 0; m < 4; ++m) _Pragma("unroll") for (int n = 0; n < 2; ++n) _Pragma("unroll") for (int k = 0; k < 2; ++k) \
;         acc[ai][bj][m][n] = __builtin_amdgcn_mfma_f32_16x16x32_f16(Bt[n][k], At[m][k], acc[ai][bj][m][n], 0, 0, 0); __builtin_amdgcn_s_setprio(0); } while (0)
; #define PG8_BAR __builtin_amdgcn_s_barrier()
; template <class Epi, class Sched, bool ALIGN_EPI = false, bool SP2 = false>
; __device__ __forceinline__ void gemm_phase(LAS unsigned char* lds, const Gemm g, const Sched& S, const Epi& E) {
;     ...
;             if constexpr (SP2) {
;             PG8_LDB(B0, 0, 0); PG8_LDB(B1, 0, 1); PG8_SCHED; PG8_LDA(At, 0, 0); PG8_STAGE(PG8_SA(1, 1), a1 + hstepA, voffA);
;             PG8_WAIT_V(8); PG8_WAIT_L(0); PG8_BAR; PG8_MMA(0, 0, At, B0); PG8_MMA(0, 1, At, B1); PG8_BAR; PG8_SCHED;
;             PG8_LDA(At, 0, 1); PG8_STAGE(PG8_SB(0, 0), b2, voffB); PG8_STAGE(PG8_SB(0, 1), b2 + hstepB, voffB); PG8_STAGE(PG8_SA(0, 0), a2, voffA);
;             PG8_WAIT_V(8); PG8_WAIT_L(0); PG8_BAR; PG8_MMA(1, 0, At, B0); PG8_MMA(1, 1, At, B1); PG8_BAR; PG8_SCHED;
;             PG8_LDB(B0, 1, 0); PG8_LDB(B1, 1, 1); PG8_SCHED; PG8_LDA(At, 1, 0); PG8_STAGE(PG8_SA(0, 1), a2 + hstepA, voffA);
;             PG8_WAIT_V(8); PG8_WAIT_L(0); PG8_BAR; PG8_MMA(0, 0, At, B0); PG8_MMA(0, 1, At, B1); PG8_BAR; PG8_SCHED;
;             PG8_LDA(At, 1, 1); PG8_STAGE(PG8_SB(1, 0), b3, voffB); PG8_STAGE(PG8_SB(1, 1), b3 + hstepB, voffB); PG8_STAGE(PG8_SA(1, 0), a3, voffA);
;             PG8_WAIT_V(8); PG8_WAIT_L(0); PG8_BAR; PG8_MMA(1, 0, At, B0); PG8_MMA(1, 1, At, B1); PG8_BAR; PG8_SCHED;
	s_setprio 0
	s_add_i32 s66, s67, s25
	v_lshl_add_u64 v[194:195], s[14:15], 0, v[2:3]
	s_mov_b32 m0, s66
	ds_read_b128 v[178:181], v144 offset:16384
	ds_read_b128 v[182:185], v144 offset:17408
	ds_read_b128 v[186:189], v144 offset:18432
	ds_read_b128 v[190:193], v144 offset:19456
	ds_read_b128 v[204:207], v144 offset:20480
	ds_read_b128 v[220:223], v144 offset:21504
	ds_read_b128 v[224:227], v144 offset:22528
	ds_read_b128 v[228:231], v144 offset:23552
	global_load_lds_dwordx4 v[194:195], off
	s_add_i32 m0, s66, 0x2000
	s_add_u32 s66, s14, 0x80000
	v_lshl_add_u64 v[196:197], s[14:15], 0, v[132:133]
	s_addc_u32 s67, s15, 0
	s_add_i32 s65, s65, s25
	global_load_lds_dwordx4 v[196:197], off
	v_lshl_add_u64 v[208:209], s[66:67], 0, v[2:3]
	s_mov_b32 m0, s65
	v_lshl_add_u64 v[232:233], s[16:17], 0, v[134:135]
	global_load_lds_dwordx4 v[208:209], off
	v_lshl_add_u64 v[208:209], s[66:67], 0, v[132:133]
	s_add_i32 m0, s65, 0x2000
	s_nop 0
	global_load_lds_dwordx4 v[208:209], off
	v_lshl_add_u64 v[208:209], s[16:17], 0, v[136:137]
	s_mov_b32 m0, s37
	s_nop 0
	global_load_lds_dwordx4 v[208:209], off
	s_mov_b32 m0, s38
	s_nop 0
	global_load_lds_dwordx4 v[232:233], off
	s_waitcnt vmcnt(8)
	s_waitcnt lgkmcnt(0)
	s_setprio 1
	s_barrier
	v_mfma_f32_16x16x32_f16 v[64:67], v[146:149], v[178:181], 0
	v_mfma_f32_16x16x32_f16 v[60:63], v[154:157], v[178:181], 0
	v_mfma_f32_16x16x32_f16 v[56:59], v[146:149], v[186:189], 0
	v_mfma_f32_16x16x32_f16 v[52:55], v[154:157], v[186:189], 0
	v_mfma_f32_16x16x32_f16 v[44:47], v[146:149], v[204:207], 0
	v_mfma_f32_16x16x32_f16 v[36:39], v[154:157], v[204:207], 0
	v_mfma_f32_16x16x32_f16 v[28:31], v[146:149], v[224:227], 0
	v_mfma_f32_16x16x32_f16 v[20:23], v[154:157], v[224:227], 0
	v_mfma_f32_16x16x32_f16 v[64:67], v[150:153], v[182:185], v[64:67]
	v_mfma_f32_16x16x32_f16 v[60:63], v[158:161], v[182:185], v[60:63]
	v_mfma_f32_16x16x32_f16 v[56:59], v[150:153], v[190:193], v[56:59]
	v_mfma_f32_16x16x32_f16 v[52:55], v[158:161], v[190:193], v[52:55]
	v_mfma_f32_16x16x32_f16 v[44:47], v[150:153], v[220:223], v[44:47]
	v_mfma_f32_16x16x32_f16 v[36:39], v[158:161], v[220:223], v[36:39]
	v_mfma_f32_16x16x32_f16 v[28:31], v[150:153], v[228:231], v[28:31]
	v_mfma_f32_16x16x32_f16 v[20:23], v[158:161], v[228:231], v[20:23]
	v_mfma_f32_16x16x32_f16 v[48:51], v[162:165], v[178:181], 0
	v_mfma_f32_16x16x32_f16 v[40:43], v[170:173], v[178:181], 0
	v_mfma_f32_16x16x32_f16 v[32:35], v[162:165], v[186:189], 0
	v_mfma_f32_16x16x32_f16 v[24:27], v[170:173], v[186:189], 0
	v_mfma_f32_16x16x32_f16 v[16:19], v[162:165], v[204:207], 0
	v_mfma_f32_16x16x32_f16 v[12:15], v[170:173], v[204:207], 0
	v_mfma_f32_16x16x32_f16 v[8:11], v[162:165], v[224:227], 0
	v_mfma_f32_16x16x32_f16 v[4:7], v[170:173], v[224:227], 0
	v_mfma_f32_16x16x32_f16 v[48:51], v[166:169], v[182:185], v[48:51]
	v_mfma_f32_16x16x32_f16 v[40:43], v[174:177], v[182:185], v[40:43]
	v_mfma_f32_16x16x32_f16 v[32:35], v[166:169], v[190:193], v[32:35]
	v_mfma_f32_16x16x32_f16 v[24:27], v[174:177], v[190:193], v[24:27]
	v_mfma_f32_16x16x32_f16 v[16:19], v[166:169], v[220:223], v[16:19]
	v_mfma_f32_16x16x32_f16 v[12:15], v[174:177], v[220:223], v[12:15]
	v_mfma_f32_16x16x32_f16 v[8:11], v[166:169], v[228:231], v[8:11]
	v_mfma_f32_16x16x32_f16 v[4:7], v[174:177], v[228:231], v[4:7]
	s_barrier
	s_setprio 0
	s_add_i32 s65, 0, 0x18000
	v_add_u32_e32 v145, s65, v143
	s_add_i32 s66, 0, 0x1c000
	ds_read_b128 v[146:149], v145
	ds_read_b128 v[150:153], v145 offset:1024
	ds_read_b128 v[154:157], v145 offset:2048
	ds_read_b128 v[158:161], v145 offset:3072
	v_add_u32_e32 v145, s66, v143
	ds_read_b128 v[162:165], v145
	ds_read_b128 v[166:169], v145 offset:1024
	ds_read_b128 v[170:173], v145 offset:2048
	ds_read_b128 v[174:177], v145 offset:3072
	s_add_u32 s16, s16, 0x80000
	s_addc_u32 s17, s17, 0
	s_mov_b32 m0, s39
	v_lshl_add_u64 v[234:235], s[16:17], 0, v[136:137]
	ds_read_b128 v[178:181], v144 offset:32768
	ds_read_b128 v[182:185], v144 offset:33792
	ds_read_b128 v[186:189], v144 offset:34816
	ds_read_b128 v[190:193], v144 offset:35840
	ds_read_b128 v[204:207], v144 offset:36864
	ds_read_b128 v[220:223], v144 offset:37888
	ds_read_b128 v[224:227], v144 offset:38912
	ds_read_b128 v[228:231], v144 offset:39936
	global_load_lds_dwordx4 v[234:235], off
	v_lshl_add_u64 v[234:235], s[16:17], 0, v[134:135]
	s_mov_b32 m0, s57
	s_nop 0
	global_load_lds_dwordx4 v[234:235], off
	s_waitcnt vmcnt(8)
	s_waitcnt lgkmcnt(0)
	s_setprio 1
	s_barrier
;     __device__ __forceinline__ bool next(int i, Unit& u) const { if (i != 0 || !valid) return false; u.pm = pm; u.pn = pn; return true; }
; #define PG8_STAGE(bufoff, gbase, voff) do { _Pragma("unroll") for (int _i = 0; _i < 2; ++_i) \
;         __builtin_amdgcn_global_load_lds((const unsigned*)((const char*)(gbase) + (voff)[_i]), (LAS unsigned*)(lds + (bufoff) + ldsw + _i * 8192), 16, 0, 0); } while (0)
; #define PG8_WAIT_V(n) asm volatile("s_waitcnt vmcnt(" #n ")" ::: "memory")
; template <class Epi, class Sched, bool ALIGN_EPI = false, bool SP2 = false>
; __device__ __forceinline__ void gemm_phase(LAS unsigned char* lds, const Gemm g, const Sched& S, const Epi& E) {
;     ...
;         const bool has_next = S.next(ui + 1, nxt);
;         const char* nA = has_next ? (const char*)g.A + (size_t)nxt.pm * tstepA : cA; const char* nB = has_next ? (const char*)g.Bt + (size_t)nxt.pn * tstepB : cB;
;         for (int t = 0; t < nt; t += 2) {
;             const bool last = (t == nt - 2);
;             const char* a1 = cA + (size_t)(t + 1) * kstep;
;             const char* a2 = last ? nA : cA + (size_t)(t + 2) * kstep; const char* b2 = last ? nB : cB + (size_t)(t + 2) * kstep;
;             const char* a3 = a2 + kstep; const char* b3 = b2 + kstep;
;             if (last && has_next) S.a_ready(nxt);
;             if constexpr (SP2) {
;             PG8_LDB(B0, 0, 0); PG8_LDB(B1, 0, 1); PG8_SCHED; PG8_LDA(At, 0, 0); PG8_STAGE(PG8_SA(1, 1), a1 + hstepA, voffA);
;             PG8_WAIT_V(8); PG8_WAIT_L(0); PG8_BAR; PG8_MMA(0, 0, At, B0); PG8_MMA(0, 1, At, B1); PG8_BAR; PG8_SCHED;
;             PG8_LDA(At, 0, 1); PG8_STAGE(PG8_SB(0, 0), b2, voffB); PG8_STAGE(PG8_SB(0, 1), b2 + hstepB, voffB); PG8_STAGE(PG8_SA(0, 0), a2, voffA);
;             PG8_WAIT_V(8); PG8_WAIT_L(0); PG8_BAR; PG8_MMA(1, 0, At, B0); PG8_MMA(1, 1, At, B1); PG8_BAR; PG8_SCHED;
;             PG8_LDB(B0, 1, 0); PG8_LDB(B1, 1, 1); PG8_SCHED; PG8_LDA(At, 1, 0); PG8_STAGE(PG8_SA(0, 1), a2 + hstepA, voffA);
;             PG8_WAIT_V(8); PG8_WAIT_L(0); PG8_BAR; PG8_MMA(0, 0, At, B0); PG8_MMA(0, 1, At, B1); PG8_BAR; PG8_SCHED;
;             PG8_LDA(At, 1, 1); PG8_STAGE(PG8_SB(1, 0), b3, voffB); PG8_STAGE(PG8_SB(1, 1), b3 + hstepB, voffB); PG8_STAGE(PG8_SA(1, 0), a3, voffA);
;             PG8_WAIT_V(8); PG8_WAIT_L(0); PG8_BAR; PG8_MMA(1, 0, At, B0); PG8_MMA(1, 1, At, B1); PG8_BAR; PG8_SCHED;
	v_mfma_f32_16x16x32_f16 v[128:131], v[146:149], v[178:181], v[128:131]
	v_mfma_f32_16x16x32_f16 v[124:127], v[154:157], v[178:181], v[124:127]
	v_mfma_f32_16x16x32_f16 v[120:123], v[146:149], v[186:189], v[120:123]
	v_mfma_f32_16x16x32_f16 v[116:119], v[154:157], v[186:189], v[116:119]
	v_mfma_f32_16x16x32_f16 v[108:111], v[146:149], v[204:207], v[108:111]
	v_mfma_f32_16x16x32_f16 v[100:103], v[154:157], v[204:207], v[100:103]
	v_mfma_f32_16x16x32_f16 v[92:95], v[146:149], v[224:227], v[92:95]
	v_mfma_f32_16x16x32_f16 v[84:87], v[154:157], v[224:227], v[84:87]
	v_mfma_f32_16x16x32_f16 v[128:131], v[150:153], v[182:185], v[128:131]
	v_mfma_f32_16x16x32_f16 v[124:127], v[158:161], v[182:185], v[124:127]
	v_mfma_f32_16x16x32_f16 v[120:123], v[150:153], v[190:193], v[120:123]
	v_mfma_f32_16x16x32_f16 v[116:119], v[158:161], v[190:193], v[116:119]
	v_mfma_f32_16x16x32_f16 v[108:111], v[150:153], v[220:223], v[108:111]
	v_mfma_f32_16x16x32_f16 v[100:103], v[158:161], v[220:223], v[100:103]
	v_mfma_f32_16x16x32_f16 v[92:95], v[150:153], v[228:231], v[92:95]
	v_mfma_f32_16x16x32_f16 v[84:87], v[158:161], v[228:231], v[84:87]
	v_mfma_f32_16x16x32_f16 v[112:115], v[162:165], v[178:181], v[112:115]
	v_mfma_f32_16x16x32_f16 v[104:107], v[170:173], v[178:181], v[104:107]
	v_mfma_f32_16x16x32_f16 v[96:99], v[162:165], v[186:189], v[96:99]
	v_mfma_f32_16x16x32_f16 v[88:91], v[170:173], v[186:189], v[88:91]
	v_mfma_f32_16x16x32_f16 v[80:83], v[162:165], v[204:207], v[80:83]
	v_mfma_f32_16x16x32_f16 v[76:79], v[170:173], v[204:207], v[76:79]
	v_mfma_f32_16x16x32_f16 v[72:75], v[162:165], v[224:227], v[72:75]
	v_mfma_f32_16x16x32_f16 v[68:71], v[170:173], v[224:227], v[68:71]
	v_mfma_f32_16x16x32_f16 v[112:115], v[166:169], v[182:185], v[112:115]
	v_mfma_f32_16x16x32_f16 v[104:107], v[174:177], v[182:185], v[104:107]
	v_mfma_f32_16x16x32_f16 v[96:99], v[166:169], v[190:193], v[96:99]
	v_mfma_f32_16x16x32_f16 v[88:91], v[174:177], v[190:193], v[88:91]
	v_mfma_f32_16x16x32_f16 v[80:83], v[166:169], v[220:223], v[80:83]
	v_mfma_f32_16x16x32_f16 v[76:79], v[174:177], v[220:223], v[76:79]
	v_mfma_f32_16x16x32_f16 v[72:75], v[166:169], v[228:231], v[72:75]
	v_mfma_f32_16x16x32_f16 v[68:71], v[174:177], v[228:231], v[68:71]
	s_barrier
	s_setprio 0
	s_add_i32 s16, s65, s25
	v_lshl_add_u64 v[194:195], v[194:195], 0, s[96:97]
	s_mov_b32 m0, s16
	ds_read_b128 v[178:181], v144 offset:49152
	ds_read_b128 v[182:185], v144 offset:50176
	ds_read_b128 v[186:189], v144 offset:51200
	ds_read_b128 v[190:193], v144 offset:52224
	ds_read_b128 v[204:207], v144 offset:53248
	ds_read_b128 v[220:223], v144 offset:54272
	ds_read_b128 v[224:227], v144 offset:55296
	ds_read_b128 v[228:231], v144 offset:56320
	global_load_lds_dwordx4 v[194:195], off
	s_add_i32 m0, s16, 0x2000
	s_add_u32 s14, s14, 0x80080
	v_lshl_add_u64 v[194:195], v[196:197], 0, s[96:97]
	s_addc_u32 s15, s15, 0
	s_add_i32 s16, s66, s25
	global_load_lds_dwordx4 v[194:195], off
	v_lshl_add_u64 v[194:195], s[14:15], 0, v[2:3]
	s_mov_b32 m0, s16
	s_nop 0
	global_load_lds_dwordx4 v[194:195], off
	v_lshl_add_u64 v[194:195], s[14:15], 0, v[132:133]
	s_add_i32 m0, s16, 0x2000
	s_nop 0
	global_load_lds_dwordx4 v[194:195], off
	v_lshl_add_u64 v[194:195], v[208:209], 0, s[96:97]
	s_mov_b32 m0, s60
	s_nop 0
	global_load_lds_dwordx4 v[194:195], off
	v_lshl_add_u64 v[194:195], v[232:233], 0, s[96:97]
	s_mov_b32 m0, s61
	s_nop 0
	global_load_lds_dwordx4 v[194:195], off
	s_waitcnt vmcnt(8)
	s_waitcnt lgkmcnt(0)
	s_setprio 1
	s_barrier
	v_mfma_f32_16x16x32_f16 v[64:67], v[146:149], v[178:181], v[64:67]
	v_mfma_f32_16x16x32_f16 v[60:63], v[154:157], v[178:181], v[60:63]
	v_mfma_f32_16x16x32_f16 v[56:59], v[146:149], v[186:189], v[56:59]
	v_mfma_f32_16x16x32_f16 v[52:55], v[154:157], v[186:189], v[52:55]
	v_mfma_f32_16x16x32_f16 v[44:47], v[146:149], v[204:207], v[44:47]
	v_mfma_f32_16x16x32_f16 v[36:39], v[154:157], v[204:207], v[36:39]
	v_mfma_f32_16x16x32_f16 v[28:31], v[146:149], v[224:227], v[28:31]
	v_mfma_f32_16x16x32_f16 v[20:23], v[154:157], v[224:227], v[20:23]
	v_mfma_f32_16x16x32_f16 v[64:67], v[150:153], v[182:185], v[64:67]
	v_mfma_f32_16x16x32_f16 v[60:63], v[158:161], v[182:185], v[60:63]
	v_mfma_f32_16x16x32_f16 v[56:59], v[150:153], v[190:193], v[56:59]
	v_mfma_f32_16x16x32_f16 v[52:55], v[158:161], v[190:193], v[52:55]
	v_mfma_f32_16x16x32_f16 v[44:47], v[150:153], v[220:223], v[44:47]
	v_mfma_f32_16x16x32_f16 v[36:39], v[158:161], v[220:223], v[36:39]
	v_mfma_f32_16x16x32_f16 v[28:31], v[150:153], v[228:231], v[28:31]
	v_mfma_f32_16x16x32_f16 v[20:23], v[158:161], v[228:231], v[20:23]
	v_mfma_f32_16x16x32_f16 v[48:51], v[162:165], v[178:181], v[48:51]
	v_mfma_f32_16x16x32_f16 v[40:43], v[170:173], v[178:181], v[40:43]
	v_mfma_f32_16x16x32_f16 v[32:35], v[162:165], v[186:189], v[32:35]
	v_mfma_f32_16x16x32_f16 v[24:27], v[170:173], v[186:189], v[24:27]
	v_mfma_f32_16x16x32_f16 v[16:19], v[162:165], v[204:207], v[16:19]
	v_mfma_f32_16x16x32_f16 v[12:15], v[170:173], v[204:207], v[12:15]
	v_mfma_f32_16x16x32_f16 v[8:11], v[162:165], v[224:227], v[8:11]
	v_mfma_f32_16x16x32_f16 v[4:7], v[170:173], v[224:227], v[4:7]
	v_mfma_f32_16x16x32_f16 v[48:51], v[166:169], v[182:185], v[48:51]
	v_mfma_f32_16x16x32_f16 v[40:43], v[174:177], v[182:185], v[40:43]
	v_mfma_f32_16x16x32_f16 v[32:35], v[166:169], v[190:193], v[32:35]
	v_mfma_f32_16x16x32_f16 v[24:27], v[174:177], v[190:193], v[24:27]
	v_mfma_f32_16x16x32_f16 v[16:19], v[166:169], v[220:223], v[16:19]
	v_mfma_f32_16x16x32_f16 v[12:15], v[174:177], v[220:223], v[12:15]
	v_mfma_f32_16x16x32_f16 v[8:11], v[166:169], v[228:231], v[8:11]
	v_mfma_f32_16x16x32_f16 v[4:7], v[174:177], v[228:231], v[4:7]
	s_barrier
	s_setprio 0
	s_add_i32 s64, s64, 2
	s_add_u32 s12, s12, 0x100
	s_addc_u32 s13, s13, 0
	s_cmp_gt_u32 s64, 5
	s_cbranch_scc0 .LBB0_2222

;     __device__ __forceinline__ bool next(int i, Unit& u) const { if (i != 0 || !valid) return false; u.pm = pm; u.pn = pn; return true; }
; #define PG8_LDA(dst, b, h) do { _Pragma("unroll") for (int m = 0; m < 4; ++m) _Pragma("unroll") for (int k = 0; k < 2; ++k) dst[m][k] = *(const LAS half8*)(lds + PG8_SA(b, h) + aoff + m * 2048 + k * 1024); } while (0)
; template <class Epi, class Sched, bool ALIGN_EPI = false, bool SP2 = false>
; __device__ __forceinline__ void gemm_phase(LAS unsigned char* lds, const Gemm g, const Sched& S, const Epi& E) {
;     ...
;     if constexpr (SP2) {
;         PG8_STAGE(PG8_SB(0, 0), cB, voffB); PG8_STAGE(PG8_SB(0, 1), cB + hstepB, voffB); PG8_STAGE(PG8_SA(0, 0), cA, voffA); PG8_STAGE(PG8_SA(0, 1), cA + hstepA, voffA);
;         if (wr == 1) PG8_BAR;
;         PG8_WAIT_V(2); PG8_BAR;
;         PG8_STAGE(PG8_SB(1, 0), cB + kstep, voffB); PG8_STAGE(PG8_SA(1, 0), cA + kstep, voffA); PG8_STAGE(PG8_SB(1, 1), cB + hstepB + kstep, voffB);
;         PG8_WAIT_V(6); PG8_BAR;
;     } else {
;         PG8_STAGE(PG8_SB(0, 0), cB, voffB); PG8_STAGE(PG8_SA(0, 0), cA, voffA); PG8_STAGE(PG8_SB(0, 1), cB + hstepB, voffB); PG8_STAGE(PG8_SA(0, 1), cA + hstepA, voffA);
;         if (wr == 1) PG8_BAR;
;         PG8_WAIT_V(4); PG8_BAR;
;         PG8_STAGE(PG8_SB(1, 0), cB + kstep, voffB); PG8_STAGE(PG8_SA(1, 0), cA + kstep, voffA); PG8_STAGE(PG8_SB(1, 1), cB + hstepB + kstep, voffB);
;         PG8_WAIT_V(6); PG8_BAR;
;     }
;     for (;;) {
;         const bool has_next = S.next(ui + 1, nxt);
;         const char* nA = has_next ? (const char*)g.A + (size_t)nxt.pm * tstepA : cA; const char* nB = has_next ? (const char*)g.Bt + (size_t)nxt.pn * tstepB : cB;
;         for (int t = 0; t < nt; t += 2) {
;             const bool last = (t == nt - 2);
;             const char* a1 = cA + (size_t)(t + 1) * kstep;
;             const char* a2 = last ? nA : cA + (size_t)(t + 2) * kstep; const char* b2 = last ? nB : cB + (size_t)(t + 2) * kstep;
;             const char* a3 = a2 + kstep; const char* b3 = b2 + kstep;
;             if (last && has_next) S.a_ready(nxt);
;             if constexpr (SP2) {
;             PG8_LDB(B0, 0, 0); PG8_LDB(B1, 0, 1); PG8_SCHED; PG8_LDA(At, 0, 0); PG8_STAGE(PG8_SA(1, 1), a1 + hstepA, voffA);
;             PG8_WAIT_V(8); PG8_WAIT_L(0); PG8_BAR; PG8_MMA(0, 0, At, B0); PG8_MMA(0, 1, At, B1); PG8_BAR; PG8_SCHED;
.LBB0_2229:
	v_lshrrev_b32_e32 v20, 1, v16
	v_and_b32_e32 v19, 15, v16
	v_and_b32_e32 v142, 24, v20
	v_lshl_or_b32 v1, s8, 6, v19
	v_lshlrev_b32_e32 v20, 1, v142
	v_lshlrev_b32_e32 v19, 6, v19
	v_lshlrev_b32_e32 v16, 2, v16
	v_or_b32_e32 v21, v19, v20
	s_lshl_b32 s8, s8, 13
	v_and_b32_e32 v16, 32, v16
	v_bitop3_b32 v19, v19, v16, v20 bitop3:0x36
	v_bitop3_b32 v16, v21, s8, v16 bitop3:0xde
	s_lshl_b32 s8, s15, 12
	s_and_b32 s8, s8, 0x3000
	v_or_b32_e32 v143, s8, v19
	s_lshl_b64 s[8:9], s[40:41], 16
	s_and_b32 s10, s9, 0xffff
	s_and_b32 s11, s8, 0xfffc0000
	s_add_u32 s39, s74, s11
	s_addc_u32 s57, s75, s10
	s_and_b32 s8, s52, 3
	s_lshl_b32 s8, s8, 18
	s_add_u32 s58, s48, s8
	s_addc_u32 s59, s49, 0
	s_add_i32 m0, s24, 0x18000
	v_lshl_add_u64 v[10:11], v[10:11], 0, s[96:97]
	s_waitcnt vmcnt(2)
	s_barrier
	global_load_lds_dwordx4 v[10:11], off
	v_lshl_add_u64 v[8:9], v[8:9], 0, s[96:97]
	s_add_i32 m0, s24, 0x1a000
	s_add_i32 s60, s24, 0x8000
	s_add_i32 s61, s24, 0xa000
	global_load_lds_dwordx4 v[8:9], off
	v_lshl_add_u64 v[6:7], v[6:7], 0, s[96:97]
	s_mov_b32 m0, s60
	s_add_u32 s8, s0, 0x20080
	global_load_lds_dwordx4 v[6:7], off
	v_lshl_add_u64 v[4:5], v[4:5], 0, s[96:97]
	s_mov_b32 m0, s61
	s_addc_u32 s9, s1, 0
	global_load_lds_dwordx4 v[4:5], off
	s_add_i32 m0, s24, 0x1c000
	v_lshl_add_u64 v[4:5], s[8:9], 0, v[2:3]
	global_load_lds_dwordx4 v[4:5], off
	v_lshl_add_u64 v[4:5], s[8:9], 0, v[132:133]
	s_add_i32 m0, s24, 0x1e000
	v_readlane_b32 s8, v254, 49
	global_load_lds_dwordx4 v[4:5], off
	v_lshlrev_b32_e32 v4, 13, v17
	v_and_b32_e32 v4, 0xffffc000, v4
	v_lshl_add_u32 v4, v15, 10, v4
	v_and_b32_e32 v5, 1, v17
	v_lshl_or_b32 v4, v5, 6, v4
	s_add_u32 s8, s8, s11
	v_readlane_b32 s9, v254, 50
	v_lshl_add_u32 v4, v18, 1, v4
	v_mov_b32_e32 v5, v3
	s_addc_u32 s9, s9, s10
	v_lshl_add_u64 v[138:139], s[8:9], 0, v[4:5]
	v_lshlrev_b32_e32 v4, 13, v12
	v_and_b32_e32 v4, 0xffffc000, v4
	v_lshl_add_u32 v4, v13, 10, v4
	v_and_b32_e32 v5, 1, v12
	v_lshl_or_b32 v4, v5, 6, v4
	s_waitcnt vmcnt(6)
	v_lshl_add_u32 v4, v14, 1, v4
	v_mov_b32_e32 v5, v3
	v_lshl_add_u64 v[140:141], s[8:9], 0, v[4:5]
	v_mov_b32_e32 v4, 0
	s_mov_b32 s62, -2
	s_mov_b64 s[8:9], 0
	v_add_u32_e32 v144, 0, v16
	s_waitcnt vmcnt(0)
	s_barrier
	s_add_u32 s10, s39, s8
	s_addc_u32 s11, s57, s9
	s_add_u32 s10, s10, 0x3e900100
	s_addc_u32 s11, s11, 0
	s_add_u32 s63, s58, s8
	s_addc_u32 s64, s59, s9
	s_add_i32 s65, 0, 0x10000
	s_cmpk_eq_i32 s8, 0x300
	s_cselect_b32 s13, s7, s11
	s_cselect_b32 s12, s6, s10
	v_add_u32_e32 v145, s65, v143
	s_cselect_b32 s11, s1, s64
	s_cselect_b32 s10, s0, s63
	s_add_i32 s63, 0, 0x14000
	ds_read_b128 v[146:149], v145
	ds_read_b128 v[150:153], v145 offset:1024
	ds_read_b128 v[154:157], v145 offset:2048
	ds_read_b128 v[158:161], v145 offset:3072
	v_add_u32_e32 v145, s63, v143
	ds_read_b128 v[162:165], v145
	ds_read_b128 v[166:169], v145 offset:1024
	ds_read_b128 v[170:173], v145 offset:2048
	ds_read_b128 v[174:177], v145 offset:3072
	v_lshl_add_u64 v[194:195], v[138:139], 0, s[8:9]
	s_add_i32 m0, s24, 0xc000
	ds_read_b128 v[178:181], v144
	ds_read_b128 v[182:185], v144 offset:1024
	ds_read_b128 v[186:189], v144 offset:2048
	ds_read_b128 v[190:193], v144 offset:3072
	ds_read_b128 v[204:207], v144 offset:4096
	ds_read_b128 v[220:223], v144 offset:5120
	ds_read_b128 v[224:227], v144 offset:6144
	ds_read_b128 v[228:231], v144 offset:7168
	global_load_lds_dwordx4 v[194:195], off
	v_lshl_add_u64 v[194:195], v[140:141], 0, s[8:9]
	s_add_i32 m0, s24, 0xe000
	s_nop 0
	global_load_lds_dwordx4 v[194:195], off
	s_waitcnt vmcnt(8)
	s_waitcnt lgkmcnt(0)
	s_setprio 1
	s_barrier
	v_mfma_f32_16x16x32_f16 v[128:131], v[146:149], v[178:181], 0
	v_mfma_f32_16x16x32_f16 v[124:127], v[154:157], v[178:181], 0
	v_mfma_f32_16x16x32_f16 v[112:115], v[146:149], v[186:189], 0
	v_mfma_f32_16x16x32_f16 v[108:111], v[154:157], v[186:189], 0
	v_mfma_f32_16x16x32_f16 v[96:99], v[146:149], v[204:207], 0
	v_mfma_f32_16x16x32_f16 v[92:95], v[154:157], v[204:207], 0
	v_mfma_f32_16x16x32_f16 v[80:83], v[146:149], v[224:227], 0
	v_mfma_f32_16x16x32_f16 v[76:79], v[154:157], v[224:227], 0
	v_mfma_f32_16x16x32_f16 v[128:131], v[150:153], v[182:185], v[128:131]
	v_mfma_f32_16x16x32_f16 v[124:127], v[158:161], v[182:185], v[124:127]
	v_mfma_f32_16x16x32_f16 v[112:115], v[150:153], v[190:193], v[112:115]
	v_mfma_f32_16x16x32_f16 v[108:111], v[158:161], v[190:193], v[108:111]
	v_mfma_f32_16x16x32_f16 v[96:99], v[150:153], v[220:223], v[96:99]
	v_mfma_f32_16x16x32_f16 v[92:95], v[158:161], v[220:223], v[92:95]
	v_mfma_f32_16x16x32_f16 v[80:83], v[150:153], v[228:231], v[80:83]
	v_mfma_f32_16x16x32_f16 v[76:79], v[158:161], v[228:231], v[76:79]
	v_mfma_f32_16x16x32_f16 v[120:123], v[162:165], v[178:181], 0
	v_mfma_f32_16x16x32_f16 v[116:119], v[170:173], v[178:181], 0
	v_mfma_f32_16x16x32_f16 v[104:107], v[162:165], v[186:189], 0
	v_mfma_f32_16x16x32_f16 v[100:103], v[170:173], v[186:189], 0
	v_mfma_f32_16x16x32_f16 v[88:91], v[162:165], v[204:207], 0
	v_mfma_f32_16x16x32_f16 v[84:87], v[170:173], v[204:207], 0
	v_mfma_f32_16x16x32_f16 v[72:75], v[162:165], v[224:227], 0
	v_mfma_f32_16x16x32_f16 v[68:71], v[170:173], v[224:227], 0
	v_mfma_f32_16x16x32_f16 v[120:123], v[166:169], v[182:185], v[120:123]
	v_mfma_f32_16x16x32_f16 v[116:119], v[174:177], v[182:185], v[116:119]
	v_mfma_f32_16x16x32_f16 v[104:107], v[166:169], v[190:193], v[104:107]
	v_mfma_f32_16x16x32_f16 v[100:103], v[174:177], v[190:193], v[100:103]
	v_mfma_f32_16x16x32_f16 v[88:91], v[166:169], v[220:223], v[88:91]
	v_mfma_f32_16x16x32_f16 v[84:87], v[174:177], v[220:223], v[84:87]
	v_mfma_f32_16x16x32_f16 v[72:75], v[166:169], v[228:231], v[72:75]
	v_mfma_f32_16x16x32_f16 v[68:71], v[174:177], v[228:231], v[68:71]
	s_barrier
; #define PG8_STAGE(bufoff, gbase, voff) do { _Pragma("unroll") for (int _i = 0; _i < 2; ++_i) \
;         __builtin_amdgcn_global_load_lds((const unsigned*)((const char*)(gbase) + (voff)[_i]), (LAS unsigned*)(lds + (bufoff) + ldsw + _i * 8192), 16, 0, 0); } while (0)
; #define PG8_LDA(dst, b, h) do { _Pragma("unroll") for (int m = 0; m < 4; ++m) _Pragma("unroll") for (int k = 0; k < 2; ++k) dst[m][k] = *(const LAS half8*)(lds + PG8_SA(b, h) + aoff + m * 2048 + k * 1024); } while (0)
; #define PG8_LDB(dst, b, h) do { _Pragma("unroll") for (int n = 0; n < 2; ++n) _Pragma("unroll") for (int k = 0; k < 2; ++k) dst[n][k] = *(const LAS half8*)(lds + PG8_SB(b, h) + boff + n * 2048 + k * 1024); } while (0)
; #define PG8_MMA(ai, bj, At, Bt) do { __builtin_amdgcn_s_setprio(1); _Pragma("unroll") for (int m = 0; m < 4; ++m) _Pragma("unroll") for (int n = 0; n < 2; ++n) _Pragma("unroll") for (int k = 0; k < 2; ++k) \
;         acc[ai][bj][m][n] = __builtin_amdgcn_mfma_f32_16x16x32_f16(Bt[n][k], At[m][k], acc[ai][bj][m][n], 0, 0, 0); __builtin_amdgcn_s_setprio(0); } while (0)
; #define PG8_WAIT_V(n) asm volatile("s_waitcnt vmcnt(" #n ")" ::: "memory")
; #define PG8_WAIT_L(n) asm volatile("s_waitcnt lgkmcnt(" #n ")" ::: "memory")
; #define PG8_BAR __builtin_amdgcn_s_barrier()
; #define PG8_SCHED __builtin_amdgcn_sched_barrier(0)
; template <class Epi, class Sched, bool ALIGN_EPI = false, bool SP2 = false>
; __device__ __forceinline__ void gemm_phase(LAS unsigned char* lds, const Gemm g, const Sched& S, const Epi& E) {
;     ...
;             PG8_LDB(B0, 0, 0); PG8_LDB(B1, 0, 1); PG8_SCHED; PG8_LDA(At, 0, 0); PG8_STAGE(PG8_SA(1, 1), a1 + hstepA, voffA);
;             PG8_WAIT_V(8); PG8_WAIT_L(0); PG8_BAR; PG8_MMA(0, 0, At, B0); PG8_MMA(0, 1, At, B1); PG8_BAR; PG8_SCHED;
;             PG8_LDA(At, 0, 1); PG8_STAGE(PG8_SB(0, 0), b2, voffB); PG8_STAGE(PG8_SB(0, 1), b2 + hstepB, voffB); PG8_STAGE(PG8_SA(0, 0), a2, voffA);
;             PG8_WAIT_V(8); PG8_WAIT_L(0); PG8_BAR; PG8_MMA(1, 0, At, B0); PG8_MMA(1, 1, At, B1); PG8_BAR; PG8_SCHED;
;             PG8_LDB(B0, 1, 0); PG8_LDB(B1, 1, 1); PG8_SCHED; PG8_LDA(At, 1, 0); PG8_STAGE(PG8_SA(0, 1), a2 + hstepA, voffA);
;             PG8_WAIT_V(8); PG8_WAIT_L(0); PG8_BAR; PG8_MMA(0, 0, At, B0); PG8_MMA(0, 1, At, B1); PG8_BAR; PG8_SCHED;
	s_setprio 0
	s_add_i32 s64, s65, s17
	v_lshl_add_u64 v[194:195], s[10:11], 0, v[2:3]
	s_mov_b32 m0, s64
	ds_read_b128 v[178:181], v144 offset:16384
	ds_read_b128 v[182:185], v144 offset:17408
	ds_read_b128 v[186:189], v144 offset:18432
	ds_read_b128 v[190:193], v144 offset:19456
	ds_read_b128 v[204:207], v144 offset:20480
	ds_read_b128 v[220:223], v144 offset:21504
	ds_read_b128 v[224:227], v144 offset:22528
	ds_read_b128 v[228:231], v144 offset:23552
	global_load_lds_dwordx4 v[194:195], off
	s_add_i32 m0, s64, 0x2000
	s_add_u32 s64, s10, 0x20000
	v_lshl_add_u64 v[196:197], s[10:11], 0, v[132:133]
	s_addc_u32 s65, s11, 0
	s_add_i32 s63, s63, s17
	global_load_lds_dwordx4 v[196:197], off
	v_lshl_add_u64 v[208:209], s[64:65], 0, v[2:3]
	s_mov_b32 m0, s63
	v_lshl_add_u64 v[232:233], s[12:13], 0, v[134:135]
	global_load_lds_dwordx4 v[208:209], off
	v_lshl_add_u64 v[208:209], s[64:65], 0, v[132:133]
	s_add_i32 m0, s63, 0x2000
	s_nop 0
	global_load_lds_dwordx4 v[208:209], off
	v_lshl_add_u64 v[208:209], s[12:13], 0, v[136:137]
	s_mov_b32 m0, s24
	s_nop 0
	global_load_lds_dwordx4 v[208:209], off
	s_mov_b32 m0, s25
	s_nop 0
	global_load_lds_dwordx4 v[232:233], off
	s_waitcnt vmcnt(8)
	s_waitcnt lgkmcnt(0)
	s_setprio 1
	s_barrier
	v_mfma_f32_16x16x32_f16 v[64:67], v[146:149], v[178:181], 0
	v_mfma_f32_16x16x32_f16 v[60:63], v[154:157], v[178:181], 0
	v_mfma_f32_16x16x32_f16 v[48:51], v[146:149], v[186:189], 0
	v_mfma_f32_16x16x32_f16 v[44:47], v[154:157], v[186:189], 0
	v_mfma_f32_16x16x32_f16 v[32:35], v[146:149], v[204:207], 0
	v_mfma_f32_16x16x32_f16 v[28:31], v[154:157], v[204:207], 0
	v_mfma_f32_16x16x32_f16 v[16:19], v[146:149], v[224:227], 0
	v_mfma_f32_16x16x32_f16 v[12:15], v[154:157], v[224:227], 0
	v_mfma_f32_16x16x32_f16 v[64:67], v[150:153], v[182:185], v[64:67]
	v_mfma_f32_16x16x32_f16 v[60:63], v[158:161], v[182:185], v[60:63]
	v_mfma_f32_16x16x32_f16 v[48:51], v[150:153], v[190:193], v[48:51]
	v_mfma_f32_16x16x32_f16 v[44:47], v[158:161], v[190:193], v[44:47]
	v_mfma_f32_16x16x32_f16 v[32:35], v[150:153], v[220:223], v[32:35]
	v_mfma_f32_16x16x32_f16 v[28:31], v[158:161], v[220:223], v[28:31]
	v_mfma_f32_16x16x32_f16 v[16:19], v[150:153], v[228:231], v[16:19]
	v_mfma_f32_16x16x32_f16 v[12:15], v[158:161], v[228:231], v[12:15]
	v_mfma_f32_16x16x32_f16 v[56:59], v[162:165], v[178:181], 0
	v_mfma_f32_16x16x32_f16 v[52:55], v[170:173], v[178:181], 0
	v_mfma_f32_16x16x32_f16 v[40:43], v[162:165], v[186:189], 0
	v_mfma_f32_16x16x32_f16 v[36:39], v[170:173], v[186:189], 0
	v_mfma_f32_16x16x32_f16 v[24:27], v[162:165], v[204:207], 0
	v_mfma_f32_16x16x32_f16 v[20:23], v[170:173], v[204:207], 0
	v_mfma_f32_16x16x32_f16 v[8:11], v[162:165], v[224:227], 0
	v_mfma_f32_16x16x32_f16 v[4:7], v[170:173], v[224:227], 0
	v_mfma_f32_16x16x32_f16 v[56:59], v[166:169], v[182:185], v[56:59]
	v_mfma_f32_16x16x32_f16 v[52:55], v[174:177], v[182:185], v[52:55]
	v_mfma_f32_16x16x32_f16 v[40:43], v[166:169], v[190:193], v[40:43]
	v_mfma_f32_16x16x32_f16 v[36:39], v[174:177], v[190:193], v[36:39]
	v_mfma_f32_16x16x32_f16 v[24:27], v[166:169], v[220:223], v[24:27]
	v_mfma_f32_16x16x32_f16 v[20:23], v[174:177], v[220:223], v[20:23]
	v_mfma_f32_16x16x32_f16 v[8:11], v[166:169], v[228:231], v[8:11]
	v_mfma_f32_16x16x32_f16 v[4:7], v[174:177], v[228:231], v[4:7]
	s_barrier
	s_setprio 0
	s_add_i32 s63, 0, 0x18000
	v_add_u32_e32 v145, s63, v143
	s_add_i32 s64, 0, 0x1c000
	ds_read_b128 v[146:149], v145
	ds_read_b128 v[150:153], v145 offset:1024
	ds_read_b128 v[154:157], v145 offset:2048
	ds_read_b128 v[158:161], v145 offset:3072
	v_add_u32_e32 v145, s64, v143
	ds_read_b128 v[162:165], v145
	ds_read_b128 v[166:169], v145 offset:1024
	ds_read_b128 v[170:173], v145 offset:2048
	ds_read_b128 v[174:177], v145 offset:3072
	s_add_u32 s12, s12, 0x20000
	s_addc_u32 s13, s13, 0
	s_mov_b32 m0, s37
	v_lshl_add_u64 v[234:235], s[12:13], 0, v[136:137]
	ds_read_b128 v[178:181], v144 offset:32768
	ds_read_b128 v[182:185], v144 offset:33792
	ds_read_b128 v[186:189], v144 offset:34816
	ds_read_b128 v[190:193], v144 offset:35840
	ds_read_b128 v[204:207], v144 offset:36864
	ds_read_b128 v[220:223], v144 offset:37888
	ds_read_b128 v[224:227], v144 offset:38912
	ds_read_b128 v[228:231], v144 offset:39936
	global_load_lds_dwordx4 v[234:235], off
	v_lshl_add_u64 v[234:235], s[12:13], 0, v[134:135]
	s_mov_b32 m0, s38
	s_nop 0
	global_load_lds_dwordx4 v[234:235], off
	s_waitcnt vmcnt(8)
	s_waitcnt lgkmcnt(0)
	s_setprio 1
	s_barrier
; #define PG8_STAGE(bufoff, gbase, voff) do { _Pragma("unroll") for (int _i = 0; _i < 2; ++_i) \
;         __builtin_amdgcn_global_load_lds((const unsigned*)((const char*)(gbase) + (voff)[_i]), (LAS unsigned*)(lds + (bufoff) + ldsw + _i * 8192), 16, 0, 0); } while (0)
; #define PG8_LDA(dst, b, h) do { _Pragma("unroll") for (int m = 0; m < 4; ++m) _Pragma("unroll") for (int k = 0; k < 2; ++k) dst[m][k] = *(const LAS half8*)(lds + PG8_SA(b, h) + aoff + m * 2048 + k * 1024); } while (0)
; #define PG8_LDB(dst, b, h) do { _Pragma("unroll") for (int n = 0; n < 2; ++n) _Pragma("unroll") for (int k = 0; k < 2; ++k) dst[n][k] = *(const LAS half8*)(lds + PG8_SB(b, h) + boff + n * 2048 + k * 1024); } while (0)
; #define PG8_MMA(ai, bj, At, Bt) do { __builtin_amdgcn_s_setprio(1); _Pragma("unroll") for (int m = 0; m < 4; ++m) _Pragma("unroll") for (int n = 0; n < 2; ++n) _Pragma("unroll") for (int k = 0; k < 2; ++k) \
;         acc[ai][bj][m][n] = __builtin_amdgcn_mfma_f32_16x16x32_f16(Bt[n][k], At[m][k], acc[ai][bj][m][n], 0, 0, 0); __builtin_amdgcn_s_setprio(0); } while (0)
; #define PG8_WAIT_V(n) asm volatile("s_waitcnt vmcnt(" #n ")" ::: "memory")
; #define PG8_WAIT_L(n) asm volatile("s_waitcnt lgkmcnt(" #n ")" ::: "memory")
; #define PG8_BAR __builtin_amdgcn_s_barrier()
; #define PG8_SCHED __builtin_amdgcn_sched_barrier(0)
; template <class Epi, class Sched, bool ALIGN_EPI = false, bool SP2 = false>
; __device__ __forceinline__ void gemm_phase(LAS unsigned char* lds, const Gemm g, const Sched& S, const Epi& E) {
;     ...
;             PG8_LDB(B0, 1, 0); PG8_LDB(B1, 1, 1); PG8_SCHED; PG8_LDA(At, 1, 0); PG8_STAGE(PG8_SA(0, 1), a2 + hstepA, voffA);
;             PG8_WAIT_V(8); PG8_WAIT_L(0); PG8_BAR; PG8_MMA(0, 0, At, B0); PG8_MMA(0, 1, At, B1); PG8_BAR; PG8_SCHED;
;             PG8_LDA(At, 1, 1); PG8_STAGE(PG8_SB(1, 0), b3, voffB); PG8_STAGE(PG8_SB(1, 1), b3 + hstepB, voffB); PG8_STAGE(PG8_SA(1, 0), a3, voffA);
;             PG8_WAIT_V(8); PG8_WAIT_L(0); PG8_BAR; PG8_MMA(1, 0, At, B0); PG8_MMA(1, 1, At, B1); PG8_BAR; PG8_SCHED;
	v_mfma_f32_16x16x32_f16 v[128:131], v[146:149], v[178:181], v[128:131]
	v_mfma_f32_16x16x32_f16 v[124:127], v[154:157], v[178:181], v[124:127]
	v_mfma_f32_16x16x32_f16 v[112:115], v[146:149], v[186:189], v[112:115]
	v_mfma_f32_16x16x32_f16 v[108:111], v[154:157], v[186:189], v[108:111]
	v_mfma_f32_16x16x32_f16 v[96:99], v[146:149], v[204:207], v[96:99]
	v_mfma_f32_16x16x32_f16 v[92:95], v[154:157], v[204:207], v[92:95]
	v_mfma_f32_16x16x32_f16 v[80:83], v[146:149], v[224:227], v[80:83]
	v_mfma_f32_16x16x32_f16 v[76:79], v[154:157], v[224:227], v[76:79]
	v_mfma_f32_16x16x32_f16 v[128:131], v[150:153], v[182:185], v[128:131]
	v_mfma_f32_16x16x32_f16 v[124:127], v[158:161], v[182:185], v[124:127]
	v_mfma_f32_16x16x32_f16 v[112:115], v[150:153], v[190:193], v[112:115]
	v_mfma_f32_16x16x32_f16 v[108:111], v[158:161], v[190:193], v[108:111]
	v_mfma_f32_16x16x32_f16 v[96:99], v[150:153], v[220:223], v[96:99]
	v_mfma_f32_16x16x32_f16 v[92:95], v[158:161], v[220:223], v[92:95]
	v_mfma_f32_16x16x32_f16 v[80:83], v[150:153], v[228:231], v[80:83]
	v_mfma_f32_16x16x32_f16 v[76:79], v[158:161], v[228:231], v[76:79]
	v_mfma_f32_16x16x32_f16 v[120:123], v[162:165], v[178:181], v[120:123]
	v_mfma_f32_16x16x32_f16 v[116:119], v[170:173], v[178:181], v[116:119]
	v_mfma_f32_16x16x32_f16 v[104:107], v[162:165], v[186:189], v[104:107]
	v_mfma_f32_16x16x32_f16 v[100:103], v[170:173], v[186:189], v[100:103]
	v_mfma_f32_16x16x32_f16 v[88:91], v[162:165], v[204:207], v[88:91]
	v_mfma_f32_16x16x32_f16 v[84:87], v[170:173], v[204:207], v[84:87]
	v_mfma_f32_16x16x32_f16 v[72:75], v[162:165], v[224:227], v[72:75]
	v_mfma_f32_16x16x32_f16 v[68:71], v[170:173], v[224:227], v[68:71]
	v_mfma_f32_16x16x32_f16 v[120:123], v[166:169], v[182:185], v[120:123]
	v_mfma_f32_16x16x32_f16 v[116:119], v[174:177], v[182:185], v[116:119]
	v_mfma_f32_16x16x32_f16 v[104:107], v[166:169], v[190:193], v[104:107]
	v_mfma_f32_16x16x32_f16 v[100:103], v[174:177], v[190:193], v[100:103]
	v_mfma_f32_16x16x32_f16 v[88:91], v[166:169], v[220:223], v[88:91]
	v_mfma_f32_16x16x32_f16 v[84:87], v[174:177], v[220:223], v[84:87]
	v_mfma_f32_16x16x32_f16 v[72:75], v[166:169], v[228:231], v[72:75]
	v_mfma_f32_16x16x32_f16 v[68:71], v[174:177], v[228:231], v[68:71]
	s_barrier
	s_setprio 0
	s_add_i32 s12, s63, s17
	v_lshl_add_u64 v[194:195], v[194:195], 0, s[96:97]
	s_mov_b32 m0, s12
	ds_read_b128 v[178:181], v144 offset:49152
	ds_read_b128 v[182:185], v144 offset:50176
	ds_read_b128 v[186:189], v144 offset:51200
	ds_read_b128 v[190:193], v144 offset:52224
	ds_read_b128 v[204:207], v144 offset:53248
	ds_read_b128 v[220:223], v144 offset:54272
	ds_read_b128 v[224:227], v144 offset:55296
	ds_read_b128 v[228:231], v144 offset:56320
	global_load_lds_dwordx4 v[194:195], off
	s_add_i32 m0, s12, 0x2000
	s_add_u32 s10, s10, 0x20080
	v_lshl_add_u64 v[194:195], v[196:197], 0, s[96:97]
	s_addc_u32 s11, s11, 0
	s_add_i32 s12, s64, s17
	global_load_lds_dwordx4 v[194:195], off
	v_lshl_add_u64 v[194:195], s[10:11], 0, v[2:3]
	s_mov_b32 m0, s12
	s_nop 0
	global_load_lds_dwordx4 v[194:195], off
	v_lshl_add_u64 v[194:195], s[10:11], 0, v[132:133]
	s_add_i32 m0, s12, 0x2000
	s_nop 0
	global_load_lds_dwordx4 v[194:195], off
	v_lshl_add_u64 v[194:195], v[208:209], 0, s[96:97]
	s_mov_b32 m0, s60
	s_nop 0
	global_load_lds_dwordx4 v[194:195], off
	v_lshl_add_u64 v[194:195], v[232:233], 0, s[96:97]
	s_mov_b32 m0, s61
	s_nop 0
	global_load_lds_dwordx4 v[194:195], off
	s_waitcnt vmcnt(8)
	s_waitcnt lgkmcnt(0)
	s_setprio 1
	s_barrier
	v_mfma_f32_16x16x32_f16 v[64:67], v[146:149], v[178:181], v[64:67]
	v_mfma_f32_16x16x32_f16 v[60:63], v[154:157], v[178:181], v[60:63]
	v_mfma_f32_16x16x32_f16 v[48:51], v[146:149], v[186:189], v[48:51]
	v_mfma_f32_16x16x32_f16 v[44:47], v[154:157], v[186:189], v[44:47]
	v_mfma_f32_16x16x32_f16 v[32:35], v[146:149], v[204:207], v[32:35]
	v_mfma_f32_16x16x32_f16 v[28:31], v[154:157], v[204:207], v[28:31]
	v_mfma_f32_16x16x32_f16 v[16:19], v[146:149], v[224:227], v[16:19]
	v_mfma_f32_16x16x32_f16 v[12:15], v[154:157], v[224:227], v[12:15]
	v_mfma_f32_16x16x32_f16 v[64:67], v[150:153], v[182:185], v[64:67]
	v_mfma_f32_16x16x32_f16 v[60:63], v[158:161], v[182:185], v[60:63]
	v_mfma_f32_16x16x32_f16 v[48:51], v[150:153], v[190:193], v[48:51]
	v_mfma_f32_16x16x32_f16 v[44:47], v[158:161], v[190:193], v[44:47]
	v_mfma_f32_16x16x32_f16 v[32:35], v[150:153], v[220:223], v[32:35]
	v_mfma_f32_16x16x32_f16 v[28:31], v[158:161], v[220:223], v[28:31]
	v_mfma_f32_16x16x32_f16 v[16:19], v[150:153], v[228:231], v[16:19]
	v_mfma_f32_16x16x32_f16 v[12:15], v[158:161], v[228:231], v[12:15]
	v_mfma_f32_16x16x32_f16 v[56:59], v[162:165], v[178:181], v[56:59]
	v_mfma_f32_16x16x32_f16 v[52:55], v[170:173], v[178:181], v[52:55]
	v_mfma_f32_16x16x32_f16 v[40:43], v[162:165], v[186:189], v[40:43]
	v_mfma_f32_16x16x32_f16 v[36:39], v[170:173], v[186:189], v[36:39]
	v_mfma_f32_16x16x32_f16 v[24:27], v[162:165], v[204:207], v[24:27]
	v_mfma_f32_16x16x32_f16 v[20:23], v[170:173], v[204:207], v[20:23]
	v_mfma_f32_16x16x32_f16 v[8:11], v[162:165], v[224:227], v[8:11]
	v_mfma_f32_16x16x32_f16 v[4:7], v[170:173], v[224:227], v[4:7]
	v_mfma_f32_16x16x32_f16 v[56:59], v[166:169], v[182:185], v[56:59]
	v_mfma_f32_16x16x32_f16 v[52:55], v[174:177], v[182:185], v[52:55]
	v_mfma_f32_16x16x32_f16 v[40:43], v[166:169], v[190:193], v[40:43]
	v_mfma_f32_16x16x32_f16 v[36:39], v[174:177], v[190:193], v[36:39]
	v_mfma_f32_16x16x32_f16 v[24:27], v[166:169], v[220:223], v[24:27]
	v_mfma_f32_16x16x32_f16 v[20:23], v[174:177], v[220:223], v[20:23]
	v_mfma_f32_16x16x32_f16 v[8:11], v[166:169], v[228:231], v[8:11]
	v_mfma_f32_16x16x32_f16 v[4:7], v[174:177], v[228:231], v[4:7]
	s_barrier
	s_setprio 0
	s_add_i32 s62, s62, 2
	s_add_u32 s8, s8, 0x100
	s_addc_u32 s9, s9, 0
	s_cmp_gt_u32 s62, 5
	s_cbranch_scc0 .LBB0_2230

;     __device__ __forceinline__ bool next(int i, Unit& u) const { if (i != 0 || !valid) return false; u.pm = pm; u.pn = pn; return true; }
; #define PG8_LDA(dst, b, h) do { _Pragma("unroll") for (int m = 0; m < 4; ++m) _Pragma("unroll") for (int k = 0; k < 2; ++k) dst[m][k] = *(const LAS half8*)(lds + PG8_SA(b, h) + aoff + m * 2048 + k * 1024); } while (0)
; template <class Epi, class Sched, bool ALIGN_EPI = false, bool SP2 = false>
; __device__ __forceinline__ void gemm_phase(LAS unsigned char* lds, const Gemm g, const Sched& S, const Epi& E) {
;     ...
;     if constexpr (SP2) {
;         PG8_STAGE(PG8_SB(0, 0), cB, voffB); PG8_STAGE(PG8_SB(0, 1), cB + hstepB, voffB); PG8_STAGE(PG8_SA(0, 0), cA, voffA); PG8_STAGE(PG8_SA(0, 1), cA + hstepA, voffA);
;         if (wr == 1) PG8_BAR;
;         PG8_WAIT_V(2); PG8_BAR;
;         PG8_STAGE(PG8_SB(1, 0), cB + kstep, voffB); PG8_STAGE(PG8_SA(1, 0), cA + kstep, voffA); PG8_STAGE(PG8_SB(1, 1), cB + hstepB + kstep, voffB);
;         PG8_WAIT_V(6); PG8_BAR;
;     } else {
;         PG8_STAGE(PG8_SB(0, 0), cB, voffB); PG8_STAGE(PG8_SA(0, 0), cA, voffA); PG8_STAGE(PG8_SB(0, 1), cB + hstepB, voffB); PG8_STAGE(PG8_SA(0, 1), cA + hstepA, voffA);
;         if (wr == 1) PG8_BAR;
;         PG8_WAIT_V(4); PG8_BAR;
;         PG8_STAGE(PG8_SB(1, 0), cB + kstep, voffB); PG8_STAGE(PG8_SA(1, 0), cA + kstep, voffA); PG8_STAGE(PG8_SB(1, 1), cB + hstepB + kstep, voffB);
;         PG8_WAIT_V(6); PG8_BAR;
;     }
;     for (;;) {
;         const bool has_next = S.next(ui + 1, nxt);
;         const char* nA = has_next ? (const char*)g.A + (size_t)nxt.pm * tstepA : cA; const char* nB = has_next ? (const char*)g.Bt + (size_t)nxt.pn * tstepB : cB;
;         for (int t = 0; t < nt; t += 2) {
;             const bool last = (t == nt - 2);
;             const char* a1 = cA + (size_t)(t + 1) * kstep;
;             const char* a2 = last ? nA : cA + (size_t)(t + 2) * kstep; const char* b2 = last ? nB : cB + (size_t)(t + 2) * kstep;
;             const char* a3 = a2 + kstep; const char* b3 = b2 + kstep;
;             if (last && has_next) S.a_ready(nxt);
;             if constexpr (SP2) {
;             PG8_LDB(B0, 0, 0); PG8_LDB(B1, 0, 1); PG8_SCHED; PG8_LDA(At, 0, 0); PG8_STAGE(PG8_SA(1, 1), a1 + hstepA, voffA);
;             PG8_WAIT_V(8); PG8_WAIT_L(0); PG8_BAR; PG8_MMA(0, 0, At, B0); PG8_MMA(0, 1, At, B1); PG8_BAR; PG8_SCHED;
.LBB0_2238:
	v_lshrrev_b32_e32 v1, 1, v15
	v_and_b32_e32 v1, 24, v1
	v_and_b32_e32 v19, 15, v15
	v_lshlrev_b32_e32 v20, 1, v1
	v_lshlrev_b32_e32 v15, 2, v15
	s_and_b32 s25, s17, 3
	v_lshl_or_b32 v142, s16, 6, v19
	v_lshl_or_b32 v19, v19, 6, v20
	s_lshl_b32 s16, s16, 13
	v_and_b32_e32 v15, 32, v15
	s_add_i32 m0, s1, 0x18000
	v_lshl_add_u64 v[10:11], v[10:11], 0, s[96:97]
	v_bitop3_b32 v20, v19, s16, v15 bitop3:0xde
	s_lshl_b32 s16, s25, 12
	s_waitcnt vmcnt(2)
	s_barrier
	global_load_lds_dwordx4 v[10:11], off
	v_lshl_add_u64 v[8:9], v[8:9], 0, s[96:97]
	s_add_i32 m0, s1, 0x1a000
	s_add_i32 s39, s1, 0x8000
	s_add_i32 s57, s1, 0xa000
	v_bitop3_b32 v143, v19, s16, v15 bitop3:0xde
	global_load_lds_dwordx4 v[8:9], off
	v_lshl_add_u64 v[6:7], v[6:7], 0, s[96:97]
	s_mov_b32 m0, s39
	s_add_u32 s16, s8, 0x20080
	global_load_lds_dwordx4 v[6:7], off
	v_lshl_add_u64 v[4:5], v[4:5], 0, s[96:97]
	s_mov_b32 m0, s57
	s_addc_u32 s17, s9, 0
	global_load_lds_dwordx4 v[4:5], off
	s_add_i32 m0, s1, 0x1c000
	v_lshl_add_u64 v[4:5], s[16:17], 0, v[2:3]
	global_load_lds_dwordx4 v[4:5], off
	v_lshl_add_u64 v[4:5], s[16:17], 0, v[132:133]
	s_add_i32 m0, s1, 0x1e000
	s_add_u32 s58, s74, s14
	global_load_lds_dwordx4 v[4:5], off
	v_lshlrev_b32_e32 v4, 13, v17
	v_and_b32_e32 v4, 0xffffc000, v4
	s_addc_u32 s59, s75, s15
	v_lshl_add_u32 v4, v16, 10, v4
	v_and_b32_e32 v5, 1, v17
	v_readlane_b32 s16, v254, 53
	v_lshl_or_b32 v4, v5, 6, v4
	s_add_u32 s14, s16, s14
	v_readlane_b32 s16, v254, 54
	v_lshl_add_u32 v4, v18, 1, v4
	v_mov_b32_e32 v5, v3
	s_addc_u32 s15, s16, s15
	v_lshl_add_u64 v[138:139], s[14:15], 0, v[4:5]
	v_lshlrev_b32_e32 v4, 13, v12
	v_and_b32_e32 v4, 0xffffc000, v4
	v_lshl_add_u32 v4, v13, 10, v4
	v_and_b32_e32 v5, 1, v12
	v_lshl_or_b32 v4, v5, 6, v4
	s_waitcnt vmcnt(6)
	v_lshl_add_u32 v4, v14, 1, v4
	v_mov_b32_e32 v5, v3
	v_lshl_add_u64 v[140:141], s[14:15], 0, v[4:5]
	s_add_u32 s60, s50, s12
	v_mov_b32_e32 v4, 0
	s_addc_u32 s61, s51, s13
	s_mov_b32 s62, -2
	s_mov_b64 s[12:13], 0
	v_add_u32_e32 v144, 0, v20
	s_waitcnt vmcnt(0)
	s_barrier
	s_add_u32 s14, s58, s12
	s_addc_u32 s15, s59, s13
	s_add_u32 s14, s14, 0x3e100100
	s_addc_u32 s15, s15, 0
	s_add_u32 s63, s60, s12
	s_addc_u32 s64, s61, s13
	s_add_i32 s65, 0, 0x10000
	s_cmpk_eq_i32 s12, 0x300
	s_cselect_b32 s17, s11, s15
	s_cselect_b32 s16, s10, s14
	v_add_u32_e32 v145, s65, v143
	s_cselect_b32 s15, s9, s64
	s_cselect_b32 s14, s8, s63
	s_add_i32 s63, 0, 0x14000
	ds_read_b128 v[146:149], v145
	ds_read_b128 v[150:153], v145 offset:1024
	ds_read_b128 v[154:157], v145 offset:2048
	ds_read_b128 v[158:161], v145 offset:3072
	v_add_u32_e32 v145, s63, v143
	ds_read_b128 v[162:165], v145
	ds_read_b128 v[166:169], v145 offset:1024
	ds_read_b128 v[170:173], v145 offset:2048
	ds_read_b128 v[174:177], v145 offset:3072
	v_lshl_add_u64 v[194:195], v[138:139], 0, s[12:13]
	s_add_i32 m0, s1, 0xc000
	ds_read_b128 v[178:181], v144
	ds_read_b128 v[182:185], v144 offset:1024
	ds_read_b128 v[186:189], v144 offset:2048
	ds_read_b128 v[190:193], v144 offset:3072
	ds_read_b128 v[204:207], v144 offset:4096
	ds_read_b128 v[220:223], v144 offset:5120
	ds_read_b128 v[224:227], v144 offset:6144
	ds_read_b128 v[228:231], v144 offset:7168
	global_load_lds_dwordx4 v[194:195], off
	v_lshl_add_u64 v[194:195], v[140:141], 0, s[12:13]
	s_add_i32 m0, s1, 0xe000
	s_nop 0
	global_load_lds_dwordx4 v[194:195], off
	s_waitcnt vmcnt(8)
	s_waitcnt lgkmcnt(0)
	s_setprio 1
	s_barrier
	v_mfma_f32_16x16x32_f16 v[128:131], v[146:149], v[178:181], 0
	v_mfma_f32_16x16x32_f16 v[124:127], v[154:157], v[178:181], 0
	v_mfma_f32_16x16x32_f16 v[112:115], v[146:149], v[186:189], 0
	v_mfma_f32_16x16x32_f16 v[108:111], v[154:157], v[186:189], 0
	v_mfma_f32_16x16x32_f16 v[96:99], v[146:149], v[204:207], 0
	v_mfma_f32_16x16x32_f16 v[92:95], v[154:157], v[204:207], 0
	v_mfma_f32_16x16x32_f16 v[80:83], v[146:149], v[224:227], 0
	v_mfma_f32_16x16x32_f16 v[76:79], v[154:157], v[224:227], 0
	v_mfma_f32_16x16x32_f16 v[128:131], v[150:153], v[182:185], v[128:131]
	v_mfma_f32_16x16x32_f16 v[124:127], v[158:161], v[182:185], v[124:127]
	v_mfma_f32_16x16x32_f16 v[112:115], v[150:153], v[190:193], v[112:115]
	v_mfma_f32_16x16x32_f16 v[108:111], v[158:161], v[190:193], v[108:111]
	v_mfma_f32_16x16x32_f16 v[96:99], v[150:153], v[220:223], v[96:99]
	v_mfma_f32_16x16x32_f16 v[92:95], v[158:161], v[220:223], v[92:95]
	v_mfma_f32_16x16x32_f16 v[80:83], v[150:153], v[228:231], v[80:83]
	v_mfma_f32_16x16x32_f16 v[76:79], v[158:161], v[228:231], v[76:79]
	v_mfma_f32_16x16x32_f16 v[120:123], v[162:165], v[178:181], 0
	v_mfma_f32_16x16x32_f16 v[116:119], v[170:173], v[178:181], 0
	v_mfma_f32_16x16x32_f16 v[104:107], v[162:165], v[186:189], 0
	v_mfma_f32_16x16x32_f16 v[100:103], v[170:173], v[186:189], 0
	v_mfma_f32_16x16x32_f16 v[88:91], v[162:165], v[204:207], 0
	v_mfma_f32_16x16x32_f16 v[84:87], v[170:173], v[204:207], 0
	v_mfma_f32_16x16x32_f16 v[72:75], v[162:165], v[224:227], 0
	v_mfma_f32_16x16x32_f16 v[68:71], v[170:173], v[224:227], 0
	v_mfma_f32_16x16x32_f16 v[120:123], v[166:169], v[182:185], v[120:123]
	v_mfma_f32_16x16x32_f16 v[116:119], v[174:177], v[182:185], v[116:119]
	v_mfma_f32_16x16x32_f16 v[104:107], v[166:169], v[190:193], v[104:107]
	v_mfma_f32_16x16x32_f16 v[100:103], v[174:177], v[190:193], v[100:103]
	v_mfma_f32_16x16x32_f16 v[88:91], v[166:169], v[220:223], v[88:91]
	v_mfma_f32_16x16x32_f16 v[84:87], v[174:177], v[220:223], v[84:87]
	v_mfma_f32_16x16x32_f16 v[72:75], v[166:169], v[228:231], v[72:75]
	v_mfma_f32_16x16x32_f16 v[68:71], v[174:177], v[228:231], v[68:71]
	s_barrier
; #define PG8_STAGE(bufoff, gbase, voff) do { _Pragma("unroll") for (int _i = 0; _i < 2; ++_i) \
;         __builtin_amdgcn_global_load_lds((const unsigned*)((const char*)(gbase) + (voff)[_i]), (LAS unsigned*)(lds + (bufoff) + ldsw + _i * 8192), 16, 0, 0); } while (0)
; #define PG8_LDA(dst, b, h) do { _Pragma("unroll") for (int m = 0; m < 4; ++m) _Pragma("unroll") for (int k = 0; k < 2; ++k) dst[m][k] = *(const LAS half8*)(lds + PG8_SA(b, h) + aoff + m * 2048 + k * 1024); } while (0)
; #define PG8_LDB(dst, b, h) do { _Pragma("unroll") for (int n = 0; n < 2; ++n) _Pragma("unroll") for (int k = 0; k < 2; ++k) dst[n][k] = *(const LAS half8*)(lds + PG8_SB(b, h) + boff + n * 2048 + k * 1024); } while (0)
; #define PG8_MMA(ai, bj, At, Bt) do { __builtin_amdgcn_s_setprio(1); _Pragma("unroll") for (int m = 0; m < 4; ++m) _Pragma("unroll") for (int n = 0; n < 2; ++n) _Pragma("unroll") for (int k = 0; k < 2; ++k) \
;         acc[ai][bj][m][n] = __builtin_amdgcn_mfma_f32_16x16x32_f16(Bt[n][k], At[m][k], acc[ai][bj][m][n], 0, 0, 0); __builtin_amdgcn_s_setprio(0); } while (0)
; #define PG8_WAIT_V(n) asm volatile("s_waitcnt vmcnt(" #n ")" ::: "memory")
; #define PG8_WAIT_L(n) asm volatile("s_waitcnt lgkmcnt(" #n ")" ::: "memory")
; #define PG8_BAR __builtin_amdgcn_s_barrier()
; #define PG8_SCHED __builtin_amdgcn_sched_barrier(0)
; template <class Epi, class Sched, bool ALIGN_EPI = false, bool SP2 = false>
; __device__ __forceinline__ void gemm_phase(LAS unsigned char* lds, const Gemm g, const Sched& S, const Epi& E) {
;     ...
;             PG8_LDB(B0, 0, 0); PG8_LDB(B1, 0, 1); PG8_SCHED; PG8_LDA(At, 0, 0); PG8_STAGE(PG8_SA(1, 1), a1 + hstepA, voffA);
;             PG8_WAIT_V(8); PG8_WAIT_L(0); PG8_BAR; PG8_MMA(0, 0, At, B0); PG8_MMA(0, 1, At, B1); PG8_BAR; PG8_SCHED;
;             PG8_LDA(At, 0, 1); PG8_STAGE(PG8_SB(0, 0), b2, voffB); PG8_STAGE(PG8_SB(0, 1), b2 + hstepB, voffB); PG8_STAGE(PG8_SA(0, 0), a2, voffA);
;             PG8_WAIT_V(8); PG8_WAIT_L(0); PG8_BAR; PG8_MMA(1, 0, At, B0); PG8_MMA(1, 1, At, B1); PG8_BAR; PG8_SCHED;
;             PG8_LDB(B0, 1, 0); PG8_LDB(B1, 1, 1); PG8_SCHED; PG8_LDA(At, 1, 0); PG8_STAGE(PG8_SA(0, 1), a2 + hstepA, voffA);
;             PG8_WAIT_V(8); PG8_WAIT_L(0); PG8_BAR; PG8_MMA(0, 0, At, B0); PG8_MMA(0, 1, At, B1); PG8_BAR; PG8_SCHED;
	s_setprio 0
	s_add_i32 s64, s65, s24
	v_lshl_add_u64 v[194:195], s[14:15], 0, v[2:3]
	s_mov_b32 m0, s64
	ds_read_b128 v[178:181], v144 offset:16384
	ds_read_b128 v[182:185], v144 offset:17408
	ds_read_b128 v[186:189], v144 offset:18432
	ds_read_b128 v[190:193], v144 offset:19456
	ds_read_b128 v[204:207], v144 offset:20480
	ds_read_b128 v[220:223], v144 offset:21504
	ds_read_b128 v[224:227], v144 offset:22528
	ds_read_b128 v[228:231], v144 offset:23552
	global_load_lds_dwordx4 v[194:195], off
	s_add_i32 m0, s64, 0x2000
	s_add_u32 s64, s14, 0x20000
	v_lshl_add_u64 v[196:197], s[14:15], 0, v[132:133]
	s_addc_u32 s65, s15, 0
	s_add_i32 s63, s63, s24
	global_load_lds_dwordx4 v[196:197], off
	v_lshl_add_u64 v[208:209], s[64:65], 0, v[2:3]
	s_mov_b32 m0, s63
	v_lshl_add_u64 v[232:233], s[16:17], 0, v[134:135]
	global_load_lds_dwordx4 v[208:209], off
	v_lshl_add_u64 v[208:209], s[64:65], 0, v[132:133]
	s_add_i32 m0, s63, 0x2000
	s_nop 0
	global_load_lds_dwordx4 v[208:209], off
	v_lshl_add_u64 v[208:209], s[16:17], 0, v[136:137]
	s_mov_b32 m0, s1
	s_nop 0
	global_load_lds_dwordx4 v[208:209], off
	s_mov_b32 m0, s7
	s_nop 0
	global_load_lds_dwordx4 v[232:233], off
	s_waitcnt vmcnt(8)
	s_waitcnt lgkmcnt(0)
	s_setprio 1
	s_barrier
	v_mfma_f32_16x16x32_f16 v[64:67], v[146:149], v[178:181], 0
	v_mfma_f32_16x16x32_f16 v[60:63], v[154:157], v[178:181], 0
	v_mfma_f32_16x16x32_f16 v[48:51], v[146:149], v[186:189], 0
	v_mfma_f32_16x16x32_f16 v[44:47], v[154:157], v[186:189], 0
	v_mfma_f32_16x16x32_f16 v[32:35], v[146:149], v[204:207], 0
	v_mfma_f32_16x16x32_f16 v[28:31], v[154:157], v[204:207], 0
	v_mfma_f32_16x16x32_f16 v[16:19], v[146:149], v[224:227], 0
	v_mfma_f32_16x16x32_f16 v[12:15], v[154:157], v[224:227], 0
	v_mfma_f32_16x16x32_f16 v[64:67], v[150:153], v[182:185], v[64:67]
	v_mfma_f32_16x16x32_f16 v[60:63], v[158:161], v[182:185], v[60:63]
	v_mfma_f32_16x16x32_f16 v[48:51], v[150:153], v[190:193], v[48:51]
	v_mfma_f32_16x16x32_f16 v[44:47], v[158:161], v[190:193], v[44:47]
	v_mfma_f32_16x16x32_f16 v[32:35], v[150:153], v[220:223], v[32:35]
	v_mfma_f32_16x16x32_f16 v[28:31], v[158:161], v[220:223], v[28:31]
	v_mfma_f32_16x16x32_f16 v[16:19], v[150:153], v[228:231], v[16:19]
	v_mfma_f32_16x16x32_f16 v[12:15], v[158:161], v[228:231], v[12:15]
	v_mfma_f32_16x16x32_f16 v[56:59], v[162:165], v[178:181], 0
	v_mfma_f32_16x16x32_f16 v[52:55], v[170:173], v[178:181], 0
	v_mfma_f32_16x16x32_f16 v[40:43], v[162:165], v[186:189], 0
	v_mfma_f32_16x16x32_f16 v[36:39], v[170:173], v[186:189], 0
	v_mfma_f32_16x16x32_f16 v[24:27], v[162:165], v[204:207], 0
	v_mfma_f32_16x16x32_f16 v[20:23], v[170:173], v[204:207], 0
	v_mfma_f32_16x16x32_f16 v[8:11], v[162:165], v[224:227], 0
	v_mfma_f32_16x16x32_f16 v[4:7], v[170:173], v[224:227], 0
	v_mfma_f32_16x16x32_f16 v[56:59], v[166:169], v[182:185], v[56:59]
	v_mfma_f32_16x16x32_f16 v[52:55], v[174:177], v[182:185], v[52:55]
	v_mfma_f32_16x16x32_f16 v[40:43], v[166:169], v[190:193], v[40:43]
	v_mfma_f32_16x16x32_f16 v[36:39], v[174:177], v[190:193], v[36:39]
	v_mfma_f32_16x16x32_f16 v[24:27], v[166:169], v[220:223], v[24:27]
	v_mfma_f32_16x16x32_f16 v[20:23], v[174:177], v[220:223], v[20:23]
	v_mfma_f32_16x16x32_f16 v[8:11], v[166:169], v[228:231], v[8:11]
	v_mfma_f32_16x16x32_f16 v[4:7], v[174:177], v[228:231], v[4:7]
	s_barrier
	s_setprio 0
	s_add_i32 s63, 0, 0x18000
	v_add_u32_e32 v145, s63, v143
	s_add_i32 s64, 0, 0x1c000
	ds_read_b128 v[146:149], v145
	ds_read_b128 v[150:153], v145 offset:1024
	ds_read_b128 v[154:157], v145 offset:2048
	ds_read_b128 v[158:161], v145 offset:3072
	v_add_u32_e32 v145, s64, v143
	ds_read_b128 v[162:165], v145
	ds_read_b128 v[166:169], v145 offset:1024
	ds_read_b128 v[170:173], v145 offset:2048
	ds_read_b128 v[174:177], v145 offset:3072
	s_add_u32 s16, s16, 0x20000
	s_addc_u32 s17, s17, 0
	s_mov_b32 m0, s37
	v_lshl_add_u64 v[234:235], s[16:17], 0, v[136:137]
	ds_read_b128 v[178:181], v144 offset:32768
	ds_read_b128 v[182:185], v144 offset:33792
	ds_read_b128 v[186:189], v144 offset:34816
	ds_read_b128 v[190:193], v144 offset:35840
	ds_read_b128 v[204:207], v144 offset:36864
	ds_read_b128 v[220:223], v144 offset:37888
	ds_read_b128 v[224:227], v144 offset:38912
	ds_read_b128 v[228:231], v144 offset:39936
	global_load_lds_dwordx4 v[234:235], off
	v_lshl_add_u64 v[234:235], s[16:17], 0, v[134:135]
	s_mov_b32 m0, s38
	s_nop 0
	global_load_lds_dwordx4 v[234:235], off
	s_waitcnt vmcnt(8)
	s_waitcnt lgkmcnt(0)
	s_setprio 1
	s_barrier
; #define PG8_STAGE(bufoff, gbase, voff) do { _Pragma("unroll") for (int _i = 0; _i < 2; ++_i) \
;         __builtin_amdgcn_global_load_lds((const unsigned*)((const char*)(gbase) + (voff)[_i]), (LAS unsigned*)(lds + (bufoff) + ldsw + _i * 8192), 16, 0, 0); } while (0)
; #define PG8_LDA(dst, b, h) do { _Pragma("unroll") for (int m = 0; m < 4; ++m) _Pragma("unroll") for (int k = 0; k < 2; ++k) dst[m][k] = *(const LAS half8*)(lds + PG8_SA(b, h) + aoff + m * 2048 + k * 1024); } while (0)
; #define PG8_LDB(dst, b, h) do { _Pragma("unroll") for (int n = 0; n < 2; ++n) _Pragma("unroll") for (int k = 0; k < 2; ++k) dst[n][k] = *(const LAS half8*)(lds + PG8_SB(b, h) + boff + n * 2048 + k * 1024); } while (0)
; #define PG8_MMA(ai, bj, At, Bt) do { __builtin_amdgcn_s_setprio(1); _Pragma("unroll") for (int m = 0; m < 4; ++m) _Pragma("unroll") for (int n = 0; n < 2; ++n) _Pragma("unroll") for (int k = 0; k < 2; ++k) \
;         acc[ai][bj][m][n] = __builtin_amdgcn_mfma_f32_16x16x32_f16(Bt[n][k], At[m][k], acc[ai][bj][m][n], 0, 0, 0); __builtin_amdgcn_s_setprio(0); } while (0)
; #define PG8_WAIT_V(n) asm volatile("s_waitcnt vmcnt(" #n ")" ::: "memory")
; #define PG8_WAIT_L(n) asm volatile("s_waitcnt lgkmcnt(" #n ")" ::: "memory")
; #define PG8_BAR __builtin_amdgcn_s_barrier()
; #define PG8_SCHED __builtin_amdgcn_sched_barrier(0)
; template <class Epi, class Sched, bool ALIGN_EPI = false, bool SP2 = false>
; __device__ __forceinline__ void gemm_phase(LAS unsigned char* lds, const Gemm g, const Sched& S, const Epi& E) {
;     ...
;             PG8_LDB(B0, 1, 0); PG8_LDB(B1, 1, 1); PG8_SCHED; PG8_LDA(At, 1, 0); PG8_STAGE(PG8_SA(0, 1), a2 + hstepA, voffA);
;             PG8_WAIT_V(8); PG8_WAIT_L(0); PG8_BAR; PG8_MMA(0, 0, At, B0); PG8_MMA(0, 1, At, B1); PG8_BAR; PG8_SCHED;
;             PG8_LDA(At, 1, 1); PG8_STAGE(PG8_SB(1, 0), b3, voffB); PG8_STAGE(PG8_SB(1, 1), b3 + hstepB, voffB); PG8_STAGE(PG8_SA(1, 0), a3, voffA);
;             PG8_WAIT_V(8); PG8_WAIT_L(0); PG8_BAR; PG8_MMA(1, 0, At, B0); PG8_MMA(1, 1, At, B1); PG8_BAR; PG8_SCHED;
	v_mfma_f32_16x16x32_f16 v[128:131], v[146:149], v[178:181], v[128:131]
	v_mfma_f32_16x16x32_f16 v[124:127], v[154:157], v[178:181], v[124:127]
	v_mfma_f32_16x16x32_f16 v[112:115], v[146:149], v[186:189], v[112:115]
	v_mfma_f32_16x16x32_f16 v[108:111], v[154:157], v[186:189], v[108:111]
	v_mfma_f32_16x16x32_f16 v[96:99], v[146:149], v[204:207], v[96:99]
	v_mfma_f32_16x16x32_f16 v[92:95], v[154:157], v[204:207], v[92:95]
	v_mfma_f32_16x16x32_f16 v[80:83], v[146:149], v[224:227], v[80:83]
	v_mfma_f32_16x16x32_f16 v[76:79], v[154:157], v[224:227], v[76:79]
	v_mfma_f32_16x16x32_f16 v[128:131], v[150:153], v[182:185], v[128:131]
	v_mfma_f32_16x16x32_f16 v[124:127], v[158:161], v[182:185], v[124:127]
	v_mfma_f32_16x16x32_f16 v[112:115], v[150:153], v[190:193], v[112:115]
	v_mfma_f32_16x16x32_f16 v[108:111], v[158:161], v[190:193], v[108:111]
	v_mfma_f32_16x16x32_f16 v[96:99], v[150:153], v[220:223], v[96:99]
	v_mfma_f32_16x16x32_f16 v[92:95], v[158:161], v[220:223], v[92:95]
	v_mfma_f32_16x16x32_f16 v[80:83], v[150:153], v[228:231], v[80:83]
	v_mfma_f32_16x16x32_f16 v[76:79], v[158:161], v[228:231], v[76:79]
	v_mfma_f32_16x16x32_f16 v[120:123], v[162:165], v[178:181], v[120:123]
	v_mfma_f32_16x16x32_f16 v[116:119], v[170:173], v[178:181], v[116:119]
	v_mfma_f32_16x16x32_f16 v[104:107], v[162:165], v[186:189], v[104:107]
	v_mfma_f32_16x16x32_f16 v[100:103], v[170:173], v[186:189], v[100:103]
	v_mfma_f32_16x16x32_f16 v[88:91], v[162:165], v[204:207], v[88:91]
	v_mfma_f32_16x16x32_f16 v[84:87], v[170:173], v[204:207], v[84:87]
	v_mfma_f32_16x16x32_f16 v[72:75], v[162:165], v[224:227], v[72:75]
	v_mfma_f32_16x16x32_f16 v[68:71], v[170:173], v[224:227], v[68:71]
	v_mfma_f32_16x16x32_f16 v[120:123], v[166:169], v[182:185], v[120:123]
	v_mfma_f32_16x16x32_f16 v[116:119], v[174:177], v[182:185], v[116:119]
	v_mfma_f32_16x16x32_f16 v[104:107], v[166:169], v[190:193], v[104:107]
	v_mfma_f32_16x16x32_f16 v[100:103], v[174:177], v[190:193], v[100:103]
	v_mfma_f32_16x16x32_f16 v[88:91], v[166:169], v[220:223], v[88:91]
	v_mfma_f32_16x16x32_f16 v[84:87], v[174:177], v[220:223], v[84:87]
	v_mfma_f32_16x16x32_f16 v[72:75], v[166:169], v[228:231], v[72:75]
	v_mfma_f32_16x16x32_f16 v[68:71], v[174:177], v[228:231], v[68:71]
	s_barrier
	s_setprio 0
	s_add_i32 s16, s63, s24
	v_lshl_add_u64 v[194:195], v[194:195], 0, s[96:97]
	s_mov_b32 m0, s16
	ds_read_b128 v[178:181], v144 offset:49152
	ds_read_b128 v[182:185], v144 offset:50176
	ds_read_b128 v[186:189], v144 offset:51200
	ds_read_b128 v[190:193], v144 offset:52224
	ds_read_b128 v[204:207], v144 offset:53248
	ds_read_b128 v[220:223], v144 offset:54272
	ds_read_b128 v[224:227], v144 offset:55296
	ds_read_b128 v[228:231], v144 offset:56320
	global_load_lds_dwordx4 v[194:195], off
	s_add_i32 m0, s16, 0x2000
	s_add_u32 s14, s14, 0x20080
	v_lshl_add_u64 v[194:195], v[196:197], 0, s[96:97]
	s_addc_u32 s15, s15, 0
	s_add_i32 s16, s64, s24
	global_load_lds_dwordx4 v[194:195], off
	v_lshl_add_u64 v[194:195], s[14:15], 0, v[2:3]
	s_mov_b32 m0, s16
	s_nop 0
	global_load_lds_dwordx4 v[194:195], off
	v_lshl_add_u64 v[194:195], s[14:15], 0, v[132:133]
	s_add_i32 m0, s16, 0x2000
	s_nop 0
	global_load_lds_dwordx4 v[194:195], off
	v_lshl_add_u64 v[194:195], v[208:209], 0, s[96:97]
	s_mov_b32 m0, s39
	s_nop 0
	global_load_lds_dwordx4 v[194:195], off
	v_lshl_add_u64 v[194:195], v[232:233], 0, s[96:97]
	s_mov_b32 m0, s57
	s_nop 0
	global_load_lds_dwordx4 v[194:195], off
	s_waitcnt vmcnt(8)
	s_waitcnt lgkmcnt(0)
	s_setprio 1
	s_barrier
	v_mfma_f32_16x16x32_f16 v[64:67], v[146:149], v[178:181], v[64:67]
	v_mfma_f32_16x16x32_f16 v[60:63], v[154:157], v[178:181], v[60:63]
	v_mfma_f32_16x16x32_f16 v[48:51], v[146:149], v[186:189], v[48:51]
	v_mfma_f32_16x16x32_f16 v[44:47], v[154:157], v[186:189], v[44:47]
	v_mfma_f32_16x16x32_f16 v[32:35], v[146:149], v[204:207], v[32:35]
	v_mfma_f32_16x16x32_f16 v[28:31], v[154:157], v[204:207], v[28:31]
	v_mfma_f32_16x16x32_f16 v[16:19], v[146:149], v[224:227], v[16:19]
	v_mfma_f32_16x16x32_f16 v[12:15], v[154:157], v[224:227], v[12:15]
	v_mfma_f32_16x16x32_f16 v[64:67], v[150:153], v[182:185], v[64:67]
	v_mfma_f32_16x16x32_f16 v[60:63], v[158:161], v[182:185], v[60:63]
	v_mfma_f32_16x16x32_f16 v[48:51], v[150:153], v[190:193], v[48:51]
	v_mfma_f32_16x16x32_f16 v[44:47], v[158:161], v[190:193], v[44:47]
	v_mfma_f32_16x16x32_f16 v[32:35], v[150:153], v[220:223], v[32:35]
	v_mfma_f32_16x16x32_f16 v[28:31], v[158:161], v[220:223], v[28:31]
	v_mfma_f32_16x16x32_f16 v[16:19], v[150:153], v[228:231], v[16:19]
	v_mfma_f32_16x16x32_f16 v[12:15], v[158:161], v[228:231], v[12:15]
	v_mfma_f32_16x16x32_f16 v[56:59], v[162:165], v[178:181], v[56:59]
	v_mfma_f32_16x16x32_f16 v[52:55], v[170:173], v[178:181], v[52:55]
	v_mfma_f32_16x16x32_f16 v[40:43], v[162:165], v[186:189], v[40:43]
	v_mfma_f32_16x16x32_f16 v[36:39], v[170:173], v[186:189], v[36:39]
	v_mfma_f32_16x16x32_f16 v[24:27], v[162:165], v[204:207], v[24:27]
	v_mfma_f32_16x16x32_f16 v[20:23], v[170:173], v[204:207], v[20:23]
	v_mfma_f32_16x16x32_f16 v[8:11], v[162:165], v[224:227], v[8:11]
	v_mfma_f32_16x16x32_f16 v[4:7], v[170:173], v[224:227], v[4:7]
	v_mfma_f32_16x16x32_f16 v[56:59], v[166:169], v[182:185], v[56:59]
	v_mfma_f32_16x16x32_f16 v[52:55], v[174:177], v[182:185], v[52:55]
	v_mfma_f32_16x16x32_f16 v[40:43], v[166:169], v[190:193], v[40:43]
	v_mfma_f32_16x16x32_f16 v[36:39], v[174:177], v[190:193], v[36:39]
	v_mfma_f32_16x16x32_f16 v[24:27], v[166:169], v[220:223], v[24:27]
	v_mfma_f32_16x16x32_f16 v[20:23], v[174:177], v[220:223], v[20:23]
	v_mfma_f32_16x16x32_f16 v[8:11], v[166:169], v[228:231], v[8:11]
	v_mfma_f32_16x16x32_f16 v[4:7], v[174:177], v[228:231], v[4:7]
	s_barrier
	s_setprio 0
	s_add_i32 s62, s62, 2
	s_add_u32 s12, s12, 0x100
	s_addc_u32 s13, s13, 0
	s_cmp_gt_u32 s62, 5
	s_cbranch_scc0 .LBB0_2239
